# K-loops: the per-slab barrier moved behind the first two MFMAs (their operands are already in registers)
# speedup vs baseline: 1.0319x; 1.0009x over previous
.LBB0_147:
	s_and_b32 s13, s12, 0x18000
	v_add_u32_e32 v222, s13, v180
	s_add_i32 s13, s12, 0xfffe8000
	s_and_b32 s13, s13, 0x18000
	v_or_b32_e32 v223, s13, v179
	v_add_u32_e32 v233, s13, v176
	s_waitcnt lgkmcnt(0)
	v_mfma_f32_32x32x16_bf16 v[112:127], v[150:153], v[142:145], v[112:127]
	v_mfma_f32_32x32x16_bf16 v[96:111], v[150:153], v[130:133], v[96:111]
	s_waitcnt vmcnt(8)
	s_barrier
	v_add_u32_e32 v206, v223, v177
	v_add_u32_e32 v234, v233, v177
	ds_read_b128 v[202:205], v206 offset:16384
	ds_read_b128 v[206:209], v206 offset:18432
	ds_read_b128 v[210:213], v234
	v_mfma_f32_32x32x16_bf16 v[80:95], v[146:149], v[142:145], v[80:95]
	v_mfma_f32_32x32x16_bf16 v[64:79], v[146:149], v[130:133], v[64:79]
	ds_read_b128 v[214:217], v234 offset:2048
	v_readfirstlane_b32 s13, v222
	s_mov_b32 m0, s13
	s_nop 0
	global_load_lds_dwordx4 v[170:171], off
	v_mfma_f32_32x32x16_bf16 v[48:63], v[138:141], v[142:145], v[48:63]
	v_mfma_f32_32x32x16_bf16 v[32:47], v[138:141], v[130:133], v[32:47]
	ds_read_b128 v[224:227], v234 offset:4096
	s_add_i32 s14, s13, 0x2000
	v_lshl_add_u64 v[150:151], v[170:171], 0, s[34:35]
	s_mov_b32 m0, s14
	s_nop 0
	global_load_lds_dwordx4 v[150:151], off
	v_mfma_f32_32x32x16_bf16 v[16:31], v[134:137], v[142:145], v[16:31]
	v_mfma_f32_32x32x16_bf16 v[0:15], v[134:137], v[130:133], v[0:15]
	ds_read_b128 v[234:237], v234 offset:6144
	s_waitcnt lgkmcnt(3)
	v_mfma_f32_32x32x16_bf16 v[112:127], v[210:213], v[202:205], v[112:127]
	v_add_u32_e32 v130, v223, v178
	v_add_u32_e32 v134, v233, v178
	ds_read_b128 v[142:145], v130 offset:16384
	v_mfma_f32_32x32x16_bf16 v[96:111], v[210:213], v[206:209], v[96:111]
	ds_read_b128 v[130:133], v130 offset:18432
	s_add_i32 s14, s13, 0x6000
	s_addk_i32 s13, 0x4000
	s_mov_b32 m0, s13
	s_nop 0
	global_load_lds_dwordx4 v[172:173], off
	s_waitcnt lgkmcnt(4)
	v_mfma_f32_32x32x16_bf16 v[80:95], v[214:217], v[202:205], v[80:95]
	ds_read_b128 v[150:153], v134
	v_mfma_f32_32x32x16_bf16 v[64:79], v[214:217], v[206:209], v[64:79]
	ds_read_b128 v[146:149], v134 offset:2048
	s_waitcnt lgkmcnt(5)
	v_mfma_f32_32x32x16_bf16 v[48:63], v[224:227], v[202:205], v[48:63]
	ds_read_b128 v[138:141], v134 offset:4096
	v_mfma_f32_32x32x16_bf16 v[32:47], v[224:227], v[206:209], v[32:47]
	ds_read_b128 v[134:137], v134 offset:6144
	v_lshl_add_u64 v[222:223], v[172:173], 0, s[34:35]
	s_mov_b32 m0, s14
	s_nop 0
	global_load_lds_dwordx4 v[222:223], off
	s_waitcnt lgkmcnt(6)
	v_mfma_f32_32x32x16_bf16 v[16:31], v[234:237], v[202:205], v[16:31]
	s_add_i32 s12, s12, 0x8000
	v_lshl_add_u64 v[170:171], v[170:171], 0, 64
	v_lshl_add_u64 v[172:173], v[172:173], 0, 64
	s_cmp_eq_u32 s12, 0x100000
	v_mfma_f32_32x32x16_bf16 v[0:15], v[234:237], v[206:209], v[0:15]
	s_cbranch_scc0 .LBB0_147
	s_waitcnt vmcnt(8) lgkmcnt(0)
	s_barrier
	v_add_u32_e32 v202, v179, v177
	v_add_u32_e32 v222, v176, v177
	ds_read_b128 v[170:173], v202 offset:49152
	ds_read_b128 v[202:205], v202 offset:51200
	ds_read_b128 v[206:209], v222 offset:32768
	ds_read_b128 v[210:213], v222 offset:34816
	ds_read_b128 v[214:217], v222 offset:36864
	ds_read_b128 v[224:227], v222 offset:38912
	s_waitcnt lgkmcnt(9)
	v_mfma_f32_32x32x16_bf16 v[112:127], v[150:153], v[142:145], v[112:127]
	v_mfma_f32_32x32x16_bf16 v[96:111], v[150:153], v[130:133], v[96:111]
	s_waitcnt lgkmcnt(8)
	v_mfma_f32_32x32x16_bf16 v[80:95], v[146:149], v[142:145], v[80:95]
	v_mfma_f32_32x32x16_bf16 v[64:79], v[146:149], v[130:133], v[64:79]
	s_waitcnt lgkmcnt(7)
	v_mfma_f32_32x32x16_bf16 v[48:63], v[138:141], v[142:145], v[48:63]
	v_mfma_f32_32x32x16_bf16 v[32:47], v[138:141], v[130:133], v[32:47]
	s_waitcnt lgkmcnt(6)
	v_mfma_f32_32x32x16_bf16 v[16:31], v[134:137], v[142:145], v[16:31]
	v_mfma_f32_32x32x16_bf16 v[0:15], v[134:137], v[130:133], v[0:15]
	v_add_u32_e32 v134, v179, v178
	v_add_u32_e32 v150, v176, v178
	ds_read_b128 v[130:133], v134 offset:49152
	ds_read_b128 v[134:137], v134 offset:51200
	ds_read_b128 v[138:141], v150 offset:32768
	ds_read_b128 v[142:145], v150 offset:34816
	ds_read_b128 v[146:149], v150 offset:36864
	ds_read_b128 v[150:153], v150 offset:38912
	s_waitcnt lgkmcnt(9)
	v_mfma_f32_32x32x16_bf16 v[112:127], v[206:209], v[170:173], v[112:127]
	v_mfma_f32_32x32x16_bf16 v[96:111], v[206:209], v[202:205], v[96:111]
	s_waitcnt lgkmcnt(8)
	v_mfma_f32_32x32x16_bf16 v[80:95], v[210:213], v[170:173], v[80:95]
	v_mfma_f32_32x32x16_bf16 v[64:79], v[210:213], v[202:205], v[64:79]
	s_waitcnt lgkmcnt(7)
	v_mfma_f32_32x32x16_bf16 v[48:63], v[214:217], v[170:173], v[48:63]
	v_mfma_f32_32x32x16_bf16 v[32:47], v[214:217], v[202:205], v[32:47]
	s_waitcnt lgkmcnt(6)
	v_mfma_f32_32x32x16_bf16 v[0:15], v[224:227], v[202:205], v[0:15]
	s_waitcnt vmcnt(4) lgkmcnt(0)
	s_barrier
	v_add_u32_e32 v202, v199, v177
	v_add_u32_e32 v222, v200, v177
	v_mfma_f32_32x32x16_bf16 v[16:31], v[224:227], v[170:173], v[16:31]
	ds_read_b128 v[170:173], v202 offset:16384
	ds_read_b128 v[202:205], v202 offset:18432
	ds_read_b128 v[206:209], v222
	ds_read_b128 v[210:213], v222 offset:2048
	ds_read_b128 v[214:217], v222 offset:4096
	ds_read_b128 v[224:227], v222 offset:6144
	s_waitcnt lgkmcnt(9)
	v_mfma_f32_32x32x16_bf16 v[112:127], v[138:141], v[130:133], v[112:127]
	v_mfma_f32_32x32x16_bf16 v[96:111], v[138:141], v[134:137], v[96:111]
	s_waitcnt lgkmcnt(8)
	v_mfma_f32_32x32x16_bf16 v[80:95], v[142:145], v[130:133], v[80:95]
	v_mfma_f32_32x32x16_bf16 v[64:79], v[142:145], v[134:137], v[64:79]
	s_waitcnt lgkmcnt(7)
	v_mfma_f32_32x32x16_bf16 v[48:63], v[146:149], v[130:133], v[48:63]
	v_mfma_f32_32x32x16_bf16 v[32:47], v[146:149], v[134:137], v[32:47]
	s_waitcnt lgkmcnt(6)
	v_mfma_f32_32x32x16_bf16 v[16:31], v[150:153], v[130:133], v[16:31]
	v_mfma_f32_32x32x16_bf16 v[0:15], v[150:153], v[134:137], v[0:15]
	v_add_u32_e32 v134, v199, v178
	v_add_u32_e32 v150, v200, v178
	ds_read_b128 v[130:133], v134 offset:16384
	ds_read_b128 v[134:137], v134 offset:18432
	ds_read_b128 v[138:141], v150
	ds_read_b128 v[142:145], v150 offset:2048
	ds_read_b128 v[146:149], v150 offset:4096
	ds_read_b128 v[150:153], v150 offset:6144
	s_waitcnt lgkmcnt(9)
	v_mfma_f32_32x32x16_bf16 v[112:127], v[206:209], v[170:173], v[112:127]
	v_mfma_f32_32x32x16_bf16 v[96:111], v[206:209], v[202:205], v[96:111]
	s_waitcnt lgkmcnt(8)
	v_mfma_f32_32x32x16_bf16 v[80:95], v[210:213], v[170:173], v[80:95]
	v_mfma_f32_32x32x16_bf16 v[64:79], v[210:213], v[202:205], v[64:79]
	s_waitcnt lgkmcnt(7)
	v_mfma_f32_32x32x16_bf16 v[48:63], v[214:217], v[170:173], v[48:63]
	v_mfma_f32_32x32x16_bf16 v[32:47], v[214:217], v[202:205], v[32:47]
	s_waitcnt lgkmcnt(6)
	v_mfma_f32_32x32x16_bf16 v[0:15], v[224:227], v[202:205], v[0:15]
	s_waitcnt vmcnt(0) lgkmcnt(0)
	s_barrier
	v_add_u32_e32 v202, v197, v177
	v_add_u32_e32 v222, v198, v177
	v_mfma_f32_32x32x16_bf16 v[16:31], v[224:227], v[170:173], v[16:31]
	ds_read_b128 v[170:173], v202 offset:16384
	ds_read_b128 v[202:205], v202 offset:18432
	ds_read_b128 v[206:209], v222
	ds_read_b128 v[210:213], v222 offset:2048
	ds_read_b128 v[214:217], v222 offset:4096
	ds_read_b128 v[224:227], v222 offset:6144
	s_waitcnt lgkmcnt(9)
	v_mfma_f32_32x32x16_bf16 v[112:127], v[138:141], v[130:133], v[112:127]
	v_mfma_f32_32x32x16_bf16 v[96:111], v[138:141], v[134:137], v[96:111]
	s_waitcnt lgkmcnt(8)
	v_mfma_f32_32x32x16_bf16 v[80:95], v[142:145], v[130:133], v[80:95]
	v_mfma_f32_32x32x16_bf16 v[64:79], v[142:145], v[134:137], v[64:79]
	s_waitcnt lgkmcnt(7)
	v_mfma_f32_32x32x16_bf16 v[48:63], v[146:149], v[130:133], v[48:63]
	v_mfma_f32_32x32x16_bf16 v[32:47], v[146:149], v[134:137], v[32:47]
	s_waitcnt lgkmcnt(6)
	v_mfma_f32_32x32x16_bf16 v[16:31], v[150:153], v[130:133], v[16:31]
	v_mfma_f32_32x32x16_bf16 v[0:15], v[150:153], v[134:137], v[0:15]
	v_add_u32_e32 v134, v197, v178
	v_add_u32_e32 v150, v198, v178
	ds_read_b128 v[130:133], v134 offset:16384
	ds_read_b128 v[134:137], v134 offset:18432
	ds_read_b128 v[138:141], v150
	ds_read_b128 v[142:145], v150 offset:2048
	ds_read_b128 v[146:149], v150 offset:4096
	ds_read_b128 v[150:153], v150 offset:6144
	s_waitcnt lgkmcnt(9)
	v_mfma_f32_32x32x16_bf16 v[112:127], v[206:209], v[170:173], v[112:127]
	v_mfma_f32_32x32x16_bf16 v[96:111], v[206:209], v[202:205], v[96:111]
	s_waitcnt lgkmcnt(8)
	v_mfma_f32_32x32x16_bf16 v[80:95], v[210:213], v[170:173], v[80:95]
	v_mfma_f32_32x32x16_bf16 v[64:79], v[210:213], v[202:205], v[64:79]
	s_waitcnt lgkmcnt(7)
	v_mfma_f32_32x32x16_bf16 v[48:63], v[214:217], v[170:173], v[48:63]
	v_mfma_f32_32x32x16_bf16 v[32:47], v[214:217], v[202:205], v[32:47]
	s_waitcnt lgkmcnt(6)
	v_mfma_f32_32x32x16_bf16 v[16:31], v[224:227], v[170:173], v[16:31]
	v_mfma_f32_32x32x16_bf16 v[0:15], v[224:227], v[202:205], v[0:15]
	s_waitcnt lgkmcnt(3)
	v_mfma_f32_32x32x16_bf16 v[96:111], v[138:141], v[134:137], v[96:111]
	v_mfma_f32_32x32x16_bf16 v[112:127], v[138:141], v[130:133], v[112:127]
	s_nop 10
	v_cvt_pk_bf16_f32 v96, v96, s0
	v_cvt_pk_bf16_f32 v98, v98, s0
	s_waitcnt lgkmcnt(2)
	v_mfma_f32_32x32x16_bf16 v[80:95], v[142:145], v[130:133], v[80:95]
	v_cvt_pk_bf16_f32 v112, v112, s0
	s_waitcnt lgkmcnt(1)
	v_mfma_f32_32x32x16_bf16 v[48:63], v[146:149], v[130:133], v[48:63]
	s_nop 8
	v_cvt_pk_bf16_f32 v80, v80, s0
	s_waitcnt lgkmcnt(0)
	v_mfma_f32_32x32x16_bf16 v[16:31], v[150:153], v[130:133], v[16:31]
	v_or_b32_e32 v130, s11, v174
	v_ashrrev_i32_e32 v131, 31, v130
	v_lshl_add_u64 v[130:131], v[130:131], 1, v[158:159]
	v_cvt_pk_bf16_f32 v48, v48, s0
	v_mfma_f32_32x32x16_bf16 v[64:79], v[142:145], v[134:137], v[64:79]
	s_nop 6
	v_cvt_pk_bf16_f32 v16, v16, s0
	v_mfma_f32_32x32x16_bf16 v[32:47], v[146:149], v[134:137], v[32:47]
	s_nop 2
	v_cvt_pk_bf16_f32 v64, v64, s0
	v_cvt_pk_bf16_f32 v66, v66, s0
	v_mfma_f32_32x32x16_bf16 v[0:15], v[150:153], v[134:137], v[0:15]
	v_add_u32_e32 v134, s7, v128
	v_or_b32_e32 v132, v134, v181
	s_movk_i32 s7, 0x1800
	v_mad_i64_i32 v[132:133], s[12:13], v132, s7, v[130:131]
	global_store_short v[132:133], v96, off offset:64
	v_or_b32_e32 v96, v134, v182
	global_store_short v[132:133], v112, off
	v_mad_i64_i32 v[132:133], s[12:13], v96, s7, v[130:131]
	v_cvt_pk_bf16_f32 v96, v113, s0
	global_store_short v[132:133], v96, off
	v_cvt_pk_bf16_f32 v96, v97, s0
	global_store_short v[132:133], v96, off offset:64
	v_or_b32_e32 v96, v134, v183
	v_mad_i64_i32 v[96:97], s[12:13], v96, s7, v[130:131]
	v_cvt_pk_bf16_f32 v112, v114, s0
	global_store_short v[96:97], v112, off
	global_store_short v[96:97], v98, off offset:64
	v_or_b32_e32 v96, v134, v184
	v_mad_i64_i32 v[96:97], s[12:13], v96, s7, v[130:131]
	v_cvt_pk_bf16_f32 v98, v115, s0
	global_store_short v[96:97], v98, off
	v_cvt_pk_bf16_f32 v98, v99, s0
	global_store_short v[96:97], v98, off offset:64
	v_or_b32_e32 v96, v134, v185
	v_mad_i64_i32 v[96:97], s[12:13], v96, s7, v[130:131]
	v_cvt_pk_bf16_f32 v98, v116, s0
	global_store_short v[96:97], v98, off
	v_cvt_pk_bf16_f32 v98, v100, s0
	global_store_short v[96:97], v98, off offset:64
	v_or_b32_e32 v96, v134, v186
	v_mad_i64_i32 v[96:97], s[12:13], v96, s7, v[130:131]
	v_cvt_pk_bf16_f32 v98, v117, s0
	global_store_short v[96:97], v98, off
	v_cvt_pk_bf16_f32 v98, v101, s0
	global_store_short v[96:97], v98, off offset:64
	v_or_b32_e32 v96, v134, v187
	v_mad_i64_i32 v[96:97], s[12:13], v96, s7, v[130:131]
	v_cvt_pk_bf16_f32 v98, v118, s0
	global_store_short v[96:97], v98, off
	v_cvt_pk_bf16_f32 v98, v102, s0
	global_store_short v[96:97], v98, off offset:64
	v_or_b32_e32 v96, v134, v188
	v_mad_i64_i32 v[96:97], s[12:13], v96, s7, v[130:131]
	v_cvt_pk_bf16_f32 v98, v119, s0
	global_store_short v[96:97], v98, off
	v_cvt_pk_bf16_f32 v98, v103, s0
	global_store_short v[96:97], v98, off offset:64
	v_or_b32_e32 v96, v134, v189
	v_mad_i64_i32 v[96:97], s[12:13], v96, s7, v[130:131]
	v_cvt_pk_bf16_f32 v98, v120, s0
	global_store_short v[96:97], v98, off
	v_cvt_pk_bf16_f32 v98, v104, s0
	global_store_short v[96:97], v98, off offset:64
	v_or_b32_e32 v96, v134, v190
	v_mad_i64_i32 v[96:97], s[12:13], v96, s7, v[130:131]
	v_cvt_pk_bf16_f32 v98, v121, s0
	global_store_short v[96:97], v98, off
	v_cvt_pk_bf16_f32 v98, v105, s0
	global_store_short v[96:97], v98, off offset:64
	v_or_b32_e32 v96, v134, v191
	v_mad_i64_i32 v[96:97], s[12:13], v96, s7, v[130:131]
	v_cvt_pk_bf16_f32 v98, v122, s0
	global_store_short v[96:97], v98, off
	v_cvt_pk_bf16_f32 v98, v106, s0
	global_store_short v[96:97], v98, off offset:64
	v_or_b32_e32 v96, v134, v192
	v_mad_i64_i32 v[96:97], s[12:13], v96, s7, v[130:131]
	v_cvt_pk_bf16_f32 v98, v123, s0
	global_store_short v[96:97], v98, off
	v_cvt_pk_bf16_f32 v98, v107, s0
	global_store_short v[96:97], v98, off offset:64
	v_or_b32_e32 v96, v134, v193
	v_mad_i64_i32 v[96:97], s[12:13], v96, s7, v[130:131]
	v_cvt_pk_bf16_f32 v98, v124, s0
	global_store_short v[96:97], v98, off
	v_cvt_pk_bf16_f32 v98, v108, s0
	global_store_short v[96:97], v98, off offset:64
	v_or_b32_e32 v96, v134, v194
	v_mad_i64_i32 v[96:97], s[12:13], v96, s7, v[130:131]
	v_cvt_pk_bf16_f32 v98, v125, s0
	global_store_short v[96:97], v98, off
	v_cvt_pk_bf16_f32 v98, v109, s0
	global_store_short v[96:97], v98, off offset:64
	v_or_b32_e32 v96, v134, v195
	v_mad_i64_i32 v[96:97], s[12:13], v96, s7, v[130:131]
	v_cvt_pk_bf16_f32 v98, v126, s0
	global_store_short v[96:97], v98, off
	v_cvt_pk_bf16_f32 v98, v110, s0
	global_store_short v[96:97], v98, off offset:64
	v_or_b32_e32 v96, v134, v196
	v_mad_i64_i32 v[96:97], s[12:13], v96, s7, v[130:131]
	v_cvt_pk_bf16_f32 v98, v127, s0
	global_store_short v[96:97], v98, off
	v_cvt_pk_bf16_f32 v98, v111, s0
	global_store_short v[96:97], v98, off offset:64
	v_or_b32_e32 v98, 32, v134
	v_or_b32_e32 v96, v98, v181
	v_mad_i64_i32 v[96:97], s[12:13], v96, s7, v[130:131]
	global_store_short v[96:97], v64, off offset:64
	v_or_b32_e32 v64, v98, v182
	global_store_short v[96:97], v80, off
	v_mad_i64_i32 v[96:97], s[12:13], v64, s7, v[130:131]
	v_cvt_pk_bf16_f32 v64, v81, s0
	global_store_short v[96:97], v64, off
	v_cvt_pk_bf16_f32 v64, v65, s0
	global_store_short v[96:97], v64, off offset:64
	v_or_b32_e32 v64, v98, v183
	v_mad_i64_i32 v[64:65], s[12:13], v64, s7, v[130:131]
	v_cvt_pk_bf16_f32 v80, v82, s0
	global_store_short v[64:65], v80, off
	global_store_short v[64:65], v66, off offset:64
	v_or_b32_e32 v64, v98, v184
	v_mad_i64_i32 v[64:65], s[12:13], v64, s7, v[130:131]
	v_cvt_pk_bf16_f32 v66, v83, s0
	global_store_short v[64:65], v66, off
	v_cvt_pk_bf16_f32 v66, v67, s0
	global_store_short v[64:65], v66, off offset:64
	v_or_b32_e32 v64, v98, v185
	v_mad_i64_i32 v[64:65], s[12:13], v64, s7, v[130:131]
	v_cvt_pk_bf16_f32 v66, v84, s0
	global_store_short v[64:65], v66, off
	v_cvt_pk_bf16_f32 v66, v68, s0
	global_store_short v[64:65], v66, off offset:64
	v_or_b32_e32 v64, v98, v186
	v_mad_i64_i32 v[64:65], s[12:13], v64, s7, v[130:131]
	v_cvt_pk_bf16_f32 v66, v85, s0
	global_store_short v[64:65], v66, off
	v_cvt_pk_bf16_f32 v66, v69, s0
	global_store_short v[64:65], v66, off offset:64
	v_or_b32_e32 v64, v98, v187
	v_mad_i64_i32 v[64:65], s[12:13], v64, s7, v[130:131]
	v_cvt_pk_bf16_f32 v66, v86, s0
	global_store_short v[64:65], v66, off
	v_cvt_pk_bf16_f32 v66, v70, s0
	global_store_short v[64:65], v66, off offset:64
	v_or_b32_e32 v64, v98, v188
	v_mad_i64_i32 v[64:65], s[12:13], v64, s7, v[130:131]
	v_cvt_pk_bf16_f32 v66, v87, s0
	global_store_short v[64:65], v66, off
	v_cvt_pk_bf16_f32 v66, v71, s0
	global_store_short v[64:65], v66, off offset:64
	v_or_b32_e32 v64, v98, v189
	v_mad_i64_i32 v[64:65], s[12:13], v64, s7, v[130:131]
	v_cvt_pk_bf16_f32 v66, v88, s0
	global_store_short v[64:65], v66, off
	v_cvt_pk_bf16_f32 v66, v72, s0
	global_store_short v[64:65], v66, off offset:64
	v_or_b32_e32 v64, v98, v190
	v_mad_i64_i32 v[64:65], s[12:13], v64, s7, v[130:131]
	v_cvt_pk_bf16_f32 v66, v89, s0
	global_store_short v[64:65], v66, off
	v_cvt_pk_bf16_f32 v66, v73, s0
	global_store_short v[64:65], v66, off offset:64
	v_or_b32_e32 v64, v98, v191
	v_mad_i64_i32 v[64:65], s[12:13], v64, s7, v[130:131]
	v_cvt_pk_bf16_f32 v66, v90, s0
	global_store_short v[64:65], v66, off
	v_cvt_pk_bf16_f32 v66, v74, s0
	global_store_short v[64:65], v66, off offset:64
	v_or_b32_e32 v64, v98, v192
	v_mad_i64_i32 v[64:65], s[12:13], v64, s7, v[130:131]
	v_cvt_pk_bf16_f32 v66, v91, s0
	global_store_short v[64:65], v66, off
	v_cvt_pk_bf16_f32 v66, v75, s0
	global_store_short v[64:65], v66, off offset:64
	v_or_b32_e32 v64, v98, v193
	v_mad_i64_i32 v[64:65], s[12:13], v64, s7, v[130:131]
	v_cvt_pk_bf16_f32 v66, v92, s0
	global_store_short v[64:65], v66, off
	v_cvt_pk_bf16_f32 v66, v76, s0
	global_store_short v[64:65], v66, off offset:64
	v_or_b32_e32 v64, v98, v194
	v_mad_i64_i32 v[64:65], s[12:13], v64, s7, v[130:131]
	v_cvt_pk_bf16_f32 v66, v93, s0
	global_store_short v[64:65], v66, off
	v_cvt_pk_bf16_f32 v66, v77, s0
	global_store_short v[64:65], v66, off offset:64
	v_or_b32_e32 v64, v98, v195
	v_mad_i64_i32 v[64:65], s[12:13], v64, s7, v[130:131]
	v_cvt_pk_bf16_f32 v66, v94, s0
	global_store_short v[64:65], v66, off
	v_cvt_pk_bf16_f32 v66, v78, s0
	global_store_short v[64:65], v66, off offset:64
	v_or_b32_e32 v64, v98, v196
	v_mad_i64_i32 v[64:65], s[12:13], v64, s7, v[130:131]
	v_cvt_pk_bf16_f32 v66, v95, s0
	global_store_short v[64:65], v66, off
	v_cvt_pk_bf16_f32 v66, v79, s0
	global_store_short v[64:65], v66, off offset:64
	v_or_b32_e32 v66, 64, v134
	v_or_b32_e32 v64, v66, v181
	v_mad_i64_i32 v[64:65], s[12:13], v64, s7, v[130:131]
	v_cvt_pk_bf16_f32 v32, v32, s0
	global_store_short v[64:65], v32, off offset:64
	v_or_b32_e32 v32, v66, v182
	global_store_short v[64:65], v48, off
	v_mad_i64_i32 v[64:65], s[12:13], v32, s7, v[130:131]
	v_cvt_pk_bf16_f32 v32, v49, s0
	global_store_short v[64:65], v32, off
	v_cvt_pk_bf16_f32 v32, v33, s0
	global_store_short v[64:65], v32, off offset:64
	v_or_b32_e32 v32, v66, v183
	v_mad_i64_i32 v[32:33], s[12:13], v32, s7, v[130:131]
	v_cvt_pk_bf16_f32 v48, v50, s0
	v_cvt_pk_bf16_f32 v34, v34, s0
	global_store_short v[32:33], v48, off
	global_store_short v[32:33], v34, off offset:64
	v_or_b32_e32 v32, v66, v184
	v_mad_i64_i32 v[32:33], s[12:13], v32, s7, v[130:131]
	v_cvt_pk_bf16_f32 v34, v51, s0
	global_store_short v[32:33], v34, off
	v_cvt_pk_bf16_f32 v34, v35, s0
	global_store_short v[32:33], v34, off offset:64
	v_or_b32_e32 v32, v66, v185
	v_mad_i64_i32 v[32:33], s[12:13], v32, s7, v[130:131]
	v_cvt_pk_bf16_f32 v34, v52, s0
	global_store_short v[32:33], v34, off
	v_cvt_pk_bf16_f32 v34, v36, s0
	global_store_short v[32:33], v34, off offset:64
	v_or_b32_e32 v32, v66, v186
	v_mad_i64_i32 v[32:33], s[12:13], v32, s7, v[130:131]
	v_cvt_pk_bf16_f32 v34, v53, s0
	global_store_short v[32:33], v34, off
	v_cvt_pk_bf16_f32 v34, v37, s0
	global_store_short v[32:33], v34, off offset:64
	v_or_b32_e32 v32, v66, v187
	v_mad_i64_i32 v[32:33], s[12:13], v32, s7, v[130:131]
	v_cvt_pk_bf16_f32 v34, v54, s0
	global_store_short v[32:33], v34, off
	v_cvt_pk_bf16_f32 v34, v38, s0
	global_store_short v[32:33], v34, off offset:64
	v_or_b32_e32 v32, v66, v188
	v_mad_i64_i32 v[32:33], s[12:13], v32, s7, v[130:131]
	v_cvt_pk_bf16_f32 v34, v55, s0
	global_store_short v[32:33], v34, off
	v_cvt_pk_bf16_f32 v34, v39, s0
	global_store_short v[32:33], v34, off offset:64
	v_or_b32_e32 v32, v66, v189
	v_mad_i64_i32 v[32:33], s[12:13], v32, s7, v[130:131]
	v_cvt_pk_bf16_f32 v34, v56, s0
	global_store_short v[32:33], v34, off
	v_cvt_pk_bf16_f32 v34, v40, s0
	global_store_short v[32:33], v34, off offset:64
	v_or_b32_e32 v32, v66, v190
	v_mad_i64_i32 v[32:33], s[12:13], v32, s7, v[130:131]
	v_cvt_pk_bf16_f32 v34, v57, s0
	global_store_short v[32:33], v34, off
	v_cvt_pk_bf16_f32 v34, v41, s0
	global_store_short v[32:33], v34, off offset:64
	v_or_b32_e32 v32, v66, v191
	v_mad_i64_i32 v[32:33], s[12:13], v32, s7, v[130:131]
	v_cvt_pk_bf16_f32 v34, v58, s0
	global_store_short v[32:33], v34, off
	v_cvt_pk_bf16_f32 v34, v42, s0
	global_store_short v[32:33], v34, off offset:64
	v_or_b32_e32 v32, v66, v192
	v_mad_i64_i32 v[32:33], s[12:13], v32, s7, v[130:131]
	v_cvt_pk_bf16_f32 v34, v59, s0
	global_store_short v[32:33], v34, off
	v_cvt_pk_bf16_f32 v34, v43, s0
	global_store_short v[32:33], v34, off offset:64
	v_or_b32_e32 v32, v66, v193
	v_mad_i64_i32 v[32:33], s[12:13], v32, s7, v[130:131]
	v_cvt_pk_bf16_f32 v34, v60, s0
	global_store_short v[32:33], v34, off
	v_cvt_pk_bf16_f32 v34, v44, s0
	global_store_short v[32:33], v34, off offset:64
	v_or_b32_e32 v32, v66, v194
	v_mad_i64_i32 v[32:33], s[12:13], v32, s7, v[130:131]
	v_cvt_pk_bf16_f32 v34, v61, s0
	global_store_short v[32:33], v34, off
	v_cvt_pk_bf16_f32 v34, v45, s0
	global_store_short v[32:33], v34, off offset:64
	v_or_b32_e32 v32, v66, v195
	v_mad_i64_i32 v[32:33], s[12:13], v32, s7, v[130:131]
	v_cvt_pk_bf16_f32 v34, v62, s0
	global_store_short v[32:33], v34, off
	v_cvt_pk_bf16_f32 v34, v46, s0
	global_store_short v[32:33], v34, off offset:64
	v_or_b32_e32 v32, v66, v196
	v_mad_i64_i32 v[32:33], s[12:13], v32, s7, v[130:131]
	v_cvt_pk_bf16_f32 v34, v63, s0
	global_store_short v[32:33], v34, off
	v_cvt_pk_bf16_f32 v34, v47, s0
	global_store_short v[32:33], v34, off offset:64
	v_or_b32_e32 v34, 0x60, v134
	v_or_b32_e32 v32, v34, v181
	v_mad_i64_i32 v[32:33], s[12:13], v32, s7, v[130:131]
	v_cvt_pk_bf16_f32 v0, v0, s0
	global_store_short v[32:33], v0, off offset:64
	v_or_b32_e32 v0, v34, v182
	global_store_short v[32:33], v16, off
	v_mad_i64_i32 v[32:33], s[12:13], v0, s7, v[130:131]
	v_cvt_pk_bf16_f32 v0, v17, s0
	global_store_short v[32:33], v0, off
	v_cvt_pk_bf16_f32 v0, v1, s0
	global_store_short v[32:33], v0, off offset:64
	v_or_b32_e32 v0, v34, v183
	v_mad_i64_i32 v[0:1], s[12:13], v0, s7, v[130:131]
	v_cvt_pk_bf16_f32 v16, v18, s0
	v_cvt_pk_bf16_f32 v2, v2, s0
	global_store_short v[0:1], v16, off
	global_store_short v[0:1], v2, off offset:64
	v_or_b32_e32 v0, v34, v184
	v_mad_i64_i32 v[0:1], s[12:13], v0, s7, v[130:131]
	v_cvt_pk_bf16_f32 v2, v19, s0
	global_store_short v[0:1], v2, off
	v_cvt_pk_bf16_f32 v2, v3, s0
	global_store_short v[0:1], v2, off offset:64
	v_or_b32_e32 v0, v34, v185
	v_mad_i64_i32 v[0:1], s[12:13], v0, s7, v[130:131]
	v_cvt_pk_bf16_f32 v2, v20, s0
	global_store_short v[0:1], v2, off
	v_cvt_pk_bf16_f32 v2, v4, s0
	global_store_short v[0:1], v2, off offset:64
	v_or_b32_e32 v0, v34, v186
	v_mad_i64_i32 v[0:1], s[12:13], v0, s7, v[130:131]
	v_cvt_pk_bf16_f32 v2, v21, s0
	global_store_short v[0:1], v2, off
	v_cvt_pk_bf16_f32 v2, v5, s0
	global_store_short v[0:1], v2, off offset:64
	v_or_b32_e32 v0, v34, v187
	v_mad_i64_i32 v[0:1], s[12:13], v0, s7, v[130:131]
	v_cvt_pk_bf16_f32 v2, v22, s0
	global_store_short v[0:1], v2, off
	v_cvt_pk_bf16_f32 v2, v6, s0
	global_store_short v[0:1], v2, off offset:64
	v_or_b32_e32 v0, v34, v188
	v_mad_i64_i32 v[0:1], s[12:13], v0, s7, v[130:131]
	v_cvt_pk_bf16_f32 v2, v23, s0
	global_store_short v[0:1], v2, off
	v_cvt_pk_bf16_f32 v2, v7, s0
	global_store_short v[0:1], v2, off offset:64
	v_or_b32_e32 v0, v34, v189
	v_mad_i64_i32 v[0:1], s[12:13], v0, s7, v[130:131]
	v_cvt_pk_bf16_f32 v2, v24, s0
	global_store_short v[0:1], v2, off
	v_cvt_pk_bf16_f32 v2, v8, s0
	global_store_short v[0:1], v2, off offset:64
	v_or_b32_e32 v0, v34, v190
	v_mad_i64_i32 v[0:1], s[12:13], v0, s7, v[130:131]
	v_cvt_pk_bf16_f32 v2, v25, s0
	global_store_short v[0:1], v2, off
	v_cvt_pk_bf16_f32 v2, v9, s0
	global_store_short v[0:1], v2, off offset:64
	v_or_b32_e32 v0, v34, v191
	v_mad_i64_i32 v[0:1], s[12:13], v0, s7, v[130:131]
	v_cvt_pk_bf16_f32 v2, v26, s0
	global_store_short v[0:1], v2, off
	v_cvt_pk_bf16_f32 v2, v10, s0
	global_store_short v[0:1], v2, off offset:64
	v_or_b32_e32 v0, v34, v192
	v_mad_i64_i32 v[0:1], s[12:13], v0, s7, v[130:131]
	v_cvt_pk_bf16_f32 v2, v27, s0
	global_store_short v[0:1], v2, off
	v_cvt_pk_bf16_f32 v2, v11, s0
	global_store_short v[0:1], v2, off offset:64
	v_or_b32_e32 v0, v34, v193
	v_mad_i64_i32 v[0:1], s[12:13], v0, s7, v[130:131]
	v_cvt_pk_bf16_f32 v2, v28, s0
	global_store_short v[0:1], v2, off
	v_cvt_pk_bf16_f32 v2, v12, s0
	global_store_short v[0:1], v2, off offset:64
	v_or_b32_e32 v0, v34, v194
	v_mad_i64_i32 v[0:1], s[12:13], v0, s7, v[130:131]
	v_cvt_pk_bf16_f32 v2, v29, s0
	global_store_short v[0:1], v2, off
	v_cvt_pk_bf16_f32 v2, v13, s0
	global_store_short v[0:1], v2, off offset:64
	v_or_b32_e32 v0, v34, v195
	v_mad_i64_i32 v[0:1], s[12:13], v0, s7, v[130:131]
	v_cvt_pk_bf16_f32 v2, v30, s0
	global_store_short v[0:1], v2, off
	v_cvt_pk_bf16_f32 v2, v14, s0
	global_store_short v[0:1], v2, off offset:64
	v_or_b32_e32 v0, v34, v196
	v_mad_i64_i32 v[0:1], s[12:13], v0, s7, v[130:131]
	v_readlane_b32 s7, v252, 7
	s_add_i32 s10, s10, s7
	s_add_i32 s4, s4, s7
	v_readlane_b32 s7, v252, 8
	v_cvt_pk_bf16_f32 v2, v31, s0
	s_add_i32 s6, s6, s7
	global_store_short v[0:1], v2, off
	v_cvt_pk_bf16_f32 v2, v15, s0
	s_cmpk_gt_i32 s10, 0x5f
	global_store_short v[0:1], v2, off offset:64
	s_cbranch_scc0 .LBB0_146

.LBB0_263:
	s_and_b32 s11, s10, 0x18000
	v_add_u32_e32 v222, s11, v180
	s_add_i32 s11, s10, 0xfffe8000
	s_and_b32 s11, s11, 0x18000
	v_or_b32_e32 v223, s11, v179
	v_add_u32_e32 v233, s11, v176
	s_waitcnt lgkmcnt(0)
	v_mfma_f32_32x32x16_bf16 v[112:127], v[150:153], v[142:145], v[112:127]
	v_mfma_f32_32x32x16_bf16 v[96:111], v[150:153], v[130:133], v[96:111]
	s_waitcnt vmcnt(8)
	s_barrier
	v_add_u32_e32 v206, v223, v177
	v_add_u32_e32 v234, v233, v177
	ds_read_b128 v[202:205], v206 offset:16384
	ds_read_b128 v[206:209], v206 offset:18432
	ds_read_b128 v[210:213], v234
	v_mfma_f32_32x32x16_bf16 v[80:95], v[146:149], v[142:145], v[80:95]
	v_mfma_f32_32x32x16_bf16 v[64:79], v[146:149], v[130:133], v[64:79]
	ds_read_b128 v[214:217], v234 offset:2048
	v_readfirstlane_b32 s11, v222
	s_mov_b32 m0, s11
	s_nop 0
	global_load_lds_dwordx4 v[170:171], off
	v_mfma_f32_32x32x16_bf16 v[48:63], v[138:141], v[142:145], v[48:63]
	v_mfma_f32_32x32x16_bf16 v[32:47], v[138:141], v[130:133], v[32:47]
	ds_read_b128 v[224:227], v234 offset:4096
	s_add_i32 s12, s11, 0x2000
	v_lshl_add_u64 v[150:151], v[170:171], 0, s[34:35]
	s_mov_b32 m0, s12
	s_nop 0
	global_load_lds_dwordx4 v[150:151], off
	v_mfma_f32_32x32x16_bf16 v[16:31], v[134:137], v[142:145], v[16:31]
	v_mfma_f32_32x32x16_bf16 v[0:15], v[134:137], v[130:133], v[0:15]
	ds_read_b128 v[234:237], v234 offset:6144
	s_waitcnt lgkmcnt(3)
	v_mfma_f32_32x32x16_bf16 v[112:127], v[210:213], v[202:205], v[112:127]
	v_add_u32_e32 v130, v223, v178
	v_add_u32_e32 v134, v233, v178
	ds_read_b128 v[142:145], v130 offset:16384
	v_mfma_f32_32x32x16_bf16 v[96:111], v[210:213], v[206:209], v[96:111]
	ds_read_b128 v[130:133], v130 offset:18432
	s_add_i32 s12, s11, 0x6000
	s_addk_i32 s11, 0x4000
	s_mov_b32 m0, s11
	s_nop 0
	global_load_lds_dwordx4 v[172:173], off
	s_waitcnt lgkmcnt(4)
	v_mfma_f32_32x32x16_bf16 v[80:95], v[214:217], v[202:205], v[80:95]
	ds_read_b128 v[150:153], v134
	v_mfma_f32_32x32x16_bf16 v[64:79], v[214:217], v[206:209], v[64:79]
	ds_read_b128 v[146:149], v134 offset:2048
	s_waitcnt lgkmcnt(5)
	v_mfma_f32_32x32x16_bf16 v[48:63], v[224:227], v[202:205], v[48:63]
	ds_read_b128 v[138:141], v134 offset:4096
	v_mfma_f32_32x32x16_bf16 v[32:47], v[224:227], v[206:209], v[32:47]
	ds_read_b128 v[134:137], v134 offset:6144
	v_lshl_add_u64 v[222:223], v[172:173], 0, s[34:35]
	s_mov_b32 m0, s12
	s_nop 0
	global_load_lds_dwordx4 v[222:223], off
	s_waitcnt lgkmcnt(6)
	v_mfma_f32_32x32x16_bf16 v[16:31], v[234:237], v[202:205], v[16:31]
	s_add_i32 s10, s10, 0x8000
	v_lshl_add_u64 v[170:171], v[170:171], 0, 64
	v_lshl_add_u64 v[172:173], v[172:173], 0, 64
	s_cmp_eq_u32 s10, 0x100000
	v_mfma_f32_32x32x16_bf16 v[0:15], v[234:237], v[206:209], v[0:15]
	s_cbranch_scc0 .LBB0_263
	s_waitcnt vmcnt(8) lgkmcnt(0)
	s_barrier
	v_add_u32_e32 v202, v179, v177
	v_add_u32_e32 v222, v176, v177
	ds_read_b128 v[170:173], v202 offset:49152
	ds_read_b128 v[202:205], v202 offset:51200
	ds_read_b128 v[206:209], v222 offset:32768
	ds_read_b128 v[210:213], v222 offset:34816
	ds_read_b128 v[214:217], v222 offset:36864
	ds_read_b128 v[224:227], v222 offset:38912
	s_waitcnt lgkmcnt(9)
	v_mfma_f32_32x32x16_bf16 v[112:127], v[150:153], v[142:145], v[112:127]
	v_mfma_f32_32x32x16_bf16 v[96:111], v[150:153], v[130:133], v[96:111]
	s_waitcnt lgkmcnt(8)
	v_mfma_f32_32x32x16_bf16 v[80:95], v[146:149], v[142:145], v[80:95]
	v_mfma_f32_32x32x16_bf16 v[64:79], v[146:149], v[130:133], v[64:79]
	s_waitcnt lgkmcnt(7)
	v_mfma_f32_32x32x16_bf16 v[48:63], v[138:141], v[142:145], v[48:63]
	v_mfma_f32_32x32x16_bf16 v[32:47], v[138:141], v[130:133], v[32:47]
	s_waitcnt lgkmcnt(6)
	v_mfma_f32_32x32x16_bf16 v[16:31], v[134:137], v[142:145], v[16:31]
	v_mfma_f32_32x32x16_bf16 v[0:15], v[134:137], v[130:133], v[0:15]
	v_add_u32_e32 v134, v179, v178
	v_add_u32_e32 v150, v176, v178
	ds_read_b128 v[130:133], v134 offset:49152
	ds_read_b128 v[134:137], v134 offset:51200
	ds_read_b128 v[138:141], v150 offset:32768
	ds_read_b128 v[142:145], v150 offset:34816
	ds_read_b128 v[146:149], v150 offset:36864
	ds_read_b128 v[150:153], v150 offset:38912
	s_waitcnt lgkmcnt(9)
	v_mfma_f32_32x32x16_bf16 v[112:127], v[206:209], v[170:173], v[112:127]
	v_mfma_f32_32x32x16_bf16 v[96:111], v[206:209], v[202:205], v[96:111]
	s_waitcnt lgkmcnt(8)
	v_mfma_f32_32x32x16_bf16 v[80:95], v[210:213], v[170:173], v[80:95]
	v_mfma_f32_32x32x16_bf16 v[64:79], v[210:213], v[202:205], v[64:79]
	s_waitcnt lgkmcnt(7)
	v_mfma_f32_32x32x16_bf16 v[48:63], v[214:217], v[170:173], v[48:63]
	v_mfma_f32_32x32x16_bf16 v[32:47], v[214:217], v[202:205], v[32:47]
	s_waitcnt lgkmcnt(6)
	v_mfma_f32_32x32x16_bf16 v[0:15], v[224:227], v[202:205], v[0:15]
	s_waitcnt vmcnt(4) lgkmcnt(0)
	s_barrier
	v_add_u32_e32 v202, v199, v177
	v_add_u32_e32 v222, v200, v177
	v_mfma_f32_32x32x16_bf16 v[16:31], v[224:227], v[170:173], v[16:31]
	ds_read_b128 v[170:173], v202 offset:16384
	ds_read_b128 v[202:205], v202 offset:18432
	ds_read_b128 v[206:209], v222
	ds_read_b128 v[210:213], v222 offset:2048
	ds_read_b128 v[214:217], v222 offset:4096
	ds_read_b128 v[224:227], v222 offset:6144
	s_waitcnt lgkmcnt(9)
	v_mfma_f32_32x32x16_bf16 v[112:127], v[138:141], v[130:133], v[112:127]
	v_mfma_f32_32x32x16_bf16 v[96:111], v[138:141], v[134:137], v[96:111]
	s_waitcnt lgkmcnt(8)
	v_mfma_f32_32x32x16_bf16 v[80:95], v[142:145], v[130:133], v[80:95]
	v_mfma_f32_32x32x16_bf16 v[64:79], v[142:145], v[134:137], v[64:79]
	s_waitcnt lgkmcnt(7)
	v_mfma_f32_32x32x16_bf16 v[48:63], v[146:149], v[130:133], v[48:63]
	v_mfma_f32_32x32x16_bf16 v[32:47], v[146:149], v[134:137], v[32:47]
	s_waitcnt lgkmcnt(6)
	v_mfma_f32_32x32x16_bf16 v[16:31], v[150:153], v[130:133], v[16:31]
	v_mfma_f32_32x32x16_bf16 v[0:15], v[150:153], v[134:137], v[0:15]
	v_add_u32_e32 v134, v199, v178
	v_add_u32_e32 v150, v200, v178
	ds_read_b128 v[130:133], v134 offset:16384
	ds_read_b128 v[134:137], v134 offset:18432
	ds_read_b128 v[138:141], v150
	ds_read_b128 v[142:145], v150 offset:2048
	ds_read_b128 v[146:149], v150 offset:4096
	ds_read_b128 v[150:153], v150 offset:6144
	s_waitcnt lgkmcnt(9)
	v_mfma_f32_32x32x16_bf16 v[112:127], v[206:209], v[170:173], v[112:127]
	v_mfma_f32_32x32x16_bf16 v[96:111], v[206:209], v[202:205], v[96:111]
	s_waitcnt lgkmcnt(8)
	v_mfma_f32_32x32x16_bf16 v[80:95], v[210:213], v[170:173], v[80:95]
	v_mfma_f32_32x32x16_bf16 v[64:79], v[210:213], v[202:205], v[64:79]
	s_waitcnt lgkmcnt(7)
	v_mfma_f32_32x32x16_bf16 v[48:63], v[214:217], v[170:173], v[48:63]
	v_mfma_f32_32x32x16_bf16 v[32:47], v[214:217], v[202:205], v[32:47]
	s_waitcnt lgkmcnt(6)
	v_mfma_f32_32x32x16_bf16 v[0:15], v[224:227], v[202:205], v[0:15]
	s_waitcnt vmcnt(0) lgkmcnt(0)
	s_barrier
	v_add_u32_e32 v202, v197, v177
	v_add_u32_e32 v222, v198, v177
	v_mfma_f32_32x32x16_bf16 v[16:31], v[224:227], v[170:173], v[16:31]
	ds_read_b128 v[170:173], v202 offset:16384
	ds_read_b128 v[202:205], v202 offset:18432
	ds_read_b128 v[206:209], v222
	ds_read_b128 v[210:213], v222 offset:2048
	ds_read_b128 v[214:217], v222 offset:4096
	ds_read_b128 v[224:227], v222 offset:6144
	s_waitcnt lgkmcnt(9)
	v_mfma_f32_32x32x16_bf16 v[112:127], v[138:141], v[130:133], v[112:127]
	v_mfma_f32_32x32x16_bf16 v[96:111], v[138:141], v[134:137], v[96:111]
	s_waitcnt lgkmcnt(8)
	v_mfma_f32_32x32x16_bf16 v[80:95], v[142:145], v[130:133], v[80:95]
	v_mfma_f32_32x32x16_bf16 v[64:79], v[142:145], v[134:137], v[64:79]
	s_waitcnt lgkmcnt(7)
	v_mfma_f32_32x32x16_bf16 v[48:63], v[146:149], v[130:133], v[48:63]
	v_mfma_f32_32x32x16_bf16 v[32:47], v[146:149], v[134:137], v[32:47]
	s_waitcnt lgkmcnt(6)
	v_mfma_f32_32x32x16_bf16 v[16:31], v[150:153], v[130:133], v[16:31]
	v_mfma_f32_32x32x16_bf16 v[0:15], v[150:153], v[134:137], v[0:15]
	v_add_u32_e32 v134, v197, v178
	v_add_u32_e32 v150, v198, v178
	ds_read_b128 v[130:133], v134 offset:16384
	ds_read_b128 v[134:137], v134 offset:18432
	ds_read_b128 v[138:141], v150
	ds_read_b128 v[142:145], v150 offset:2048
	ds_read_b128 v[146:149], v150 offset:4096
	ds_read_b128 v[150:153], v150 offset:6144
	s_waitcnt lgkmcnt(9)
	v_mfma_f32_32x32x16_bf16 v[112:127], v[206:209], v[170:173], v[112:127]
	v_mfma_f32_32x32x16_bf16 v[96:111], v[206:209], v[202:205], v[96:111]
	s_waitcnt lgkmcnt(8)
	v_mfma_f32_32x32x16_bf16 v[80:95], v[210:213], v[170:173], v[80:95]
	v_mfma_f32_32x32x16_bf16 v[64:79], v[210:213], v[202:205], v[64:79]
	s_waitcnt lgkmcnt(7)
	v_mfma_f32_32x32x16_bf16 v[48:63], v[214:217], v[170:173], v[48:63]
	v_mfma_f32_32x32x16_bf16 v[32:47], v[214:217], v[202:205], v[32:47]
	s_waitcnt lgkmcnt(6)
	v_mfma_f32_32x32x16_bf16 v[16:31], v[224:227], v[170:173], v[16:31]
	v_mfma_f32_32x32x16_bf16 v[0:15], v[224:227], v[202:205], v[0:15]
	s_waitcnt lgkmcnt(3)
	v_mfma_f32_32x32x16_bf16 v[112:127], v[138:141], v[130:133], v[112:127]
	v_mfma_f32_32x32x16_bf16 v[96:111], v[138:141], v[134:137], v[96:111]
	s_nop 10
	v_cvt_pk_bf16_f32 v112, v112, s0
	s_waitcnt lgkmcnt(2)
	v_mfma_f32_32x32x16_bf16 v[80:95], v[142:145], v[130:133], v[80:95]
	v_cvt_pk_bf16_f32 v96, v96, s0
	v_cvt_pk_bf16_f32 v98, v98, s0
	s_waitcnt lgkmcnt(1)
	v_mfma_f32_32x32x16_bf16 v[48:63], v[146:149], v[130:133], v[48:63]
	s_nop 7
	v_cvt_pk_bf16_f32 v80, v80, s0
	s_waitcnt lgkmcnt(0)
	v_mfma_f32_32x32x16_bf16 v[16:31], v[150:153], v[130:133], v[16:31]
	v_add_u32_e32 v132, s5, v128
	v_or_b32_e32 v130, s7, v174
	v_ashrrev_i32_e32 v131, 31, v130
	v_lshl_add_u64 v[130:131], v[130:131], 1, v[158:159]
	v_cvt_pk_bf16_f32 v48, v48, s0
	v_readlane_b32 s5, v252, 7
	s_add_i32 s6, s6, s5
	v_mfma_f32_32x32x16_bf16 v[64:79], v[142:145], v[134:137], v[64:79]
	s_nop 3
	v_cvt_pk_bf16_f32 v16, v16, s0
	s_add_i32 s2, s2, s5
	v_readlane_b32 s5, v252, 8
	s_add_i32 s4, s4, s5
	s_cmp_gt_i32 s6, 31
	s_nop 2
	v_cvt_pk_bf16_f32 v64, v64, s0
	v_mfma_f32_32x32x16_bf16 v[32:47], v[146:149], v[134:137], v[32:47]
	v_cvt_pk_bf16_f32 v66, v66, s0
	v_mfma_f32_32x32x16_bf16 v[0:15], v[150:153], v[134:137], v[0:15]
	v_or_b32_e32 v134, v132, v181
	v_ashrrev_i32_e32 v135, 31, v134
	v_lshlrev_b64 v[134:135], 11, v[134:135]
	v_lshl_add_u64 v[134:135], v[130:131], 0, v[134:135]
	global_store_short v[134:135], v112, off
	global_store_short v[134:135], v96, off offset:64
	v_or_b32_e32 v134, v132, v182
	v_ashrrev_i32_e32 v135, 31, v134
	v_lshlrev_b64 v[134:135], 11, v[134:135]
	v_lshl_add_u64 v[134:135], v[130:131], 0, v[134:135]
	v_cvt_pk_bf16_f32 v96, v113, s0
	global_store_short v[134:135], v96, off
	v_cvt_pk_bf16_f32 v96, v97, s0
	global_store_short v[134:135], v96, off offset:64
	v_or_b32_e32 v96, v132, v183
	v_ashrrev_i32_e32 v97, 31, v96
	v_lshlrev_b64 v[96:97], 11, v[96:97]
	v_lshl_add_u64 v[96:97], v[130:131], 0, v[96:97]
	v_cvt_pk_bf16_f32 v112, v114, s0
	global_store_short v[96:97], v112, off
	global_store_short v[96:97], v98, off offset:64
	v_or_b32_e32 v96, v132, v184
	v_ashrrev_i32_e32 v97, 31, v96
	v_lshlrev_b64 v[96:97], 11, v[96:97]
	v_lshl_add_u64 v[96:97], v[130:131], 0, v[96:97]
	v_cvt_pk_bf16_f32 v98, v115, s0
	global_store_short v[96:97], v98, off
	v_cvt_pk_bf16_f32 v98, v99, s0
	global_store_short v[96:97], v98, off offset:64
	v_or_b32_e32 v96, v132, v185
	v_ashrrev_i32_e32 v97, 31, v96
	v_lshlrev_b64 v[96:97], 11, v[96:97]
	v_lshl_add_u64 v[96:97], v[130:131], 0, v[96:97]
	v_cvt_pk_bf16_f32 v98, v116, s0
	global_store_short v[96:97], v98, off
	v_cvt_pk_bf16_f32 v98, v100, s0
	global_store_short v[96:97], v98, off offset:64
	v_or_b32_e32 v96, v132, v186
	v_ashrrev_i32_e32 v97, 31, v96
	v_lshlrev_b64 v[96:97], 11, v[96:97]
	v_lshl_add_u64 v[96:97], v[130:131], 0, v[96:97]
	v_cvt_pk_bf16_f32 v98, v117, s0
	global_store_short v[96:97], v98, off
	v_cvt_pk_bf16_f32 v98, v101, s0
	global_store_short v[96:97], v98, off offset:64
	v_or_b32_e32 v96, v132, v187
	v_ashrrev_i32_e32 v97, 31, v96
	v_lshlrev_b64 v[96:97], 11, v[96:97]
	v_lshl_add_u64 v[96:97], v[130:131], 0, v[96:97]
	v_cvt_pk_bf16_f32 v98, v118, s0
	global_store_short v[96:97], v98, off
	v_cvt_pk_bf16_f32 v98, v102, s0
	global_store_short v[96:97], v98, off offset:64
	v_or_b32_e32 v96, v132, v188
	v_ashrrev_i32_e32 v97, 31, v96
	v_lshlrev_b64 v[96:97], 11, v[96:97]
	v_lshl_add_u64 v[96:97], v[130:131], 0, v[96:97]
	v_cvt_pk_bf16_f32 v98, v119, s0
	global_store_short v[96:97], v98, off
	v_cvt_pk_bf16_f32 v98, v103, s0
	global_store_short v[96:97], v98, off offset:64
	v_or_b32_e32 v96, v132, v189
	v_ashrrev_i32_e32 v97, 31, v96
	v_lshlrev_b64 v[96:97], 11, v[96:97]
	v_lshl_add_u64 v[96:97], v[130:131], 0, v[96:97]
	v_cvt_pk_bf16_f32 v98, v120, s0
	global_store_short v[96:97], v98, off
	v_cvt_pk_bf16_f32 v98, v104, s0
	global_store_short v[96:97], v98, off offset:64
	v_or_b32_e32 v96, v132, v190
	v_ashrrev_i32_e32 v97, 31, v96
	v_lshlrev_b64 v[96:97], 11, v[96:97]
	v_lshl_add_u64 v[96:97], v[130:131], 0, v[96:97]
	v_cvt_pk_bf16_f32 v98, v121, s0
	global_store_short v[96:97], v98, off
	v_cvt_pk_bf16_f32 v98, v105, s0
	global_store_short v[96:97], v98, off offset:64
	v_or_b32_e32 v96, v132, v191
	v_ashrrev_i32_e32 v97, 31, v96
	v_lshlrev_b64 v[96:97], 11, v[96:97]
	v_lshl_add_u64 v[96:97], v[130:131], 0, v[96:97]
	v_cvt_pk_bf16_f32 v98, v122, s0
	global_store_short v[96:97], v98, off
	v_cvt_pk_bf16_f32 v98, v106, s0
	global_store_short v[96:97], v98, off offset:64
	v_or_b32_e32 v96, v132, v192
	v_ashrrev_i32_e32 v97, 31, v96
	v_lshlrev_b64 v[96:97], 11, v[96:97]
	v_lshl_add_u64 v[96:97], v[130:131], 0, v[96:97]
	v_cvt_pk_bf16_f32 v98, v123, s0
	global_store_short v[96:97], v98, off
	v_cvt_pk_bf16_f32 v98, v107, s0
	global_store_short v[96:97], v98, off offset:64
	v_or_b32_e32 v96, v132, v193
	v_ashrrev_i32_e32 v97, 31, v96
	v_lshlrev_b64 v[96:97], 11, v[96:97]
	v_lshl_add_u64 v[96:97], v[130:131], 0, v[96:97]
	v_cvt_pk_bf16_f32 v98, v124, s0
	global_store_short v[96:97], v98, off
	v_cvt_pk_bf16_f32 v98, v108, s0
	global_store_short v[96:97], v98, off offset:64
	v_or_b32_e32 v96, v132, v194
	v_ashrrev_i32_e32 v97, 31, v96
	v_lshlrev_b64 v[96:97], 11, v[96:97]
	v_lshl_add_u64 v[96:97], v[130:131], 0, v[96:97]
	v_cvt_pk_bf16_f32 v98, v125, s0
	global_store_short v[96:97], v98, off
	v_cvt_pk_bf16_f32 v98, v109, s0
	global_store_short v[96:97], v98, off offset:64
	v_or_b32_e32 v96, v132, v195
	v_ashrrev_i32_e32 v97, 31, v96
	v_lshlrev_b64 v[96:97], 11, v[96:97]
	v_lshl_add_u64 v[96:97], v[130:131], 0, v[96:97]
	v_cvt_pk_bf16_f32 v98, v126, s0
	global_store_short v[96:97], v98, off
	v_cvt_pk_bf16_f32 v98, v110, s0
	global_store_short v[96:97], v98, off offset:64
	v_or_b32_e32 v96, v132, v196
	v_ashrrev_i32_e32 v97, 31, v96
	v_lshlrev_b64 v[96:97], 11, v[96:97]
	v_lshl_add_u64 v[96:97], v[130:131], 0, v[96:97]
	v_cvt_pk_bf16_f32 v98, v127, s0
	global_store_short v[96:97], v98, off
	v_cvt_pk_bf16_f32 v98, v111, s0
	global_store_short v[96:97], v98, off offset:64
	v_or_b32_e32 v98, 32, v132
	v_or_b32_e32 v96, v98, v181
	v_ashrrev_i32_e32 v97, 31, v96
	v_lshlrev_b64 v[96:97], 11, v[96:97]
	v_lshl_add_u64 v[96:97], v[130:131], 0, v[96:97]
	global_store_short v[96:97], v80, off
	global_store_short v[96:97], v64, off offset:64
	v_or_b32_e32 v96, v98, v182
	v_ashrrev_i32_e32 v97, 31, v96
	v_lshlrev_b64 v[96:97], 11, v[96:97]
	v_lshl_add_u64 v[96:97], v[130:131], 0, v[96:97]
	v_cvt_pk_bf16_f32 v64, v81, s0
	global_store_short v[96:97], v64, off
	v_cvt_pk_bf16_f32 v64, v65, s0
	global_store_short v[96:97], v64, off offset:64
	v_or_b32_e32 v64, v98, v183
	v_ashrrev_i32_e32 v65, 31, v64
	v_lshlrev_b64 v[64:65], 11, v[64:65]
	v_lshl_add_u64 v[64:65], v[130:131], 0, v[64:65]
	v_cvt_pk_bf16_f32 v80, v82, s0
	global_store_short v[64:65], v80, off
	global_store_short v[64:65], v66, off offset:64
	v_or_b32_e32 v64, v98, v184
	v_ashrrev_i32_e32 v65, 31, v64
	v_lshlrev_b64 v[64:65], 11, v[64:65]
	v_lshl_add_u64 v[64:65], v[130:131], 0, v[64:65]
	v_cvt_pk_bf16_f32 v66, v83, s0
	global_store_short v[64:65], v66, off
	v_cvt_pk_bf16_f32 v66, v67, s0
	global_store_short v[64:65], v66, off offset:64
	v_or_b32_e32 v64, v98, v185
	v_ashrrev_i32_e32 v65, 31, v64
	v_lshlrev_b64 v[64:65], 11, v[64:65]
	v_lshl_add_u64 v[64:65], v[130:131], 0, v[64:65]
	v_cvt_pk_bf16_f32 v66, v84, s0
	global_store_short v[64:65], v66, off
	v_cvt_pk_bf16_f32 v66, v68, s0
	global_store_short v[64:65], v66, off offset:64
	v_or_b32_e32 v64, v98, v186
	v_ashrrev_i32_e32 v65, 31, v64
	v_lshlrev_b64 v[64:65], 11, v[64:65]
	v_lshl_add_u64 v[64:65], v[130:131], 0, v[64:65]
	v_cvt_pk_bf16_f32 v66, v85, s0
	global_store_short v[64:65], v66, off
	v_cvt_pk_bf16_f32 v66, v69, s0
	global_store_short v[64:65], v66, off offset:64
	v_or_b32_e32 v64, v98, v187
	v_ashrrev_i32_e32 v65, 31, v64
	v_lshlrev_b64 v[64:65], 11, v[64:65]
	v_lshl_add_u64 v[64:65], v[130:131], 0, v[64:65]
	v_cvt_pk_bf16_f32 v66, v86, s0
	global_store_short v[64:65], v66, off
	v_cvt_pk_bf16_f32 v66, v70, s0
	global_store_short v[64:65], v66, off offset:64
	v_or_b32_e32 v64, v98, v188
	v_ashrrev_i32_e32 v65, 31, v64
	v_lshlrev_b64 v[64:65], 11, v[64:65]
	v_lshl_add_u64 v[64:65], v[130:131], 0, v[64:65]
	v_cvt_pk_bf16_f32 v66, v87, s0
	global_store_short v[64:65], v66, off
	v_cvt_pk_bf16_f32 v66, v71, s0
	global_store_short v[64:65], v66, off offset:64
	v_or_b32_e32 v64, v98, v189
	v_ashrrev_i32_e32 v65, 31, v64
	v_lshlrev_b64 v[64:65], 11, v[64:65]
	v_lshl_add_u64 v[64:65], v[130:131], 0, v[64:65]
	v_cvt_pk_bf16_f32 v66, v88, s0
	global_store_short v[64:65], v66, off
	v_cvt_pk_bf16_f32 v66, v72, s0
	global_store_short v[64:65], v66, off offset:64
	v_or_b32_e32 v64, v98, v190
	v_ashrrev_i32_e32 v65, 31, v64
	v_lshlrev_b64 v[64:65], 11, v[64:65]
	v_lshl_add_u64 v[64:65], v[130:131], 0, v[64:65]
	v_cvt_pk_bf16_f32 v66, v89, s0
	global_store_short v[64:65], v66, off
	v_cvt_pk_bf16_f32 v66, v73, s0
	global_store_short v[64:65], v66, off offset:64
	v_or_b32_e32 v64, v98, v191
	v_ashrrev_i32_e32 v65, 31, v64
	v_lshlrev_b64 v[64:65], 11, v[64:65]
	v_lshl_add_u64 v[64:65], v[130:131], 0, v[64:65]
	v_cvt_pk_bf16_f32 v66, v90, s0
	global_store_short v[64:65], v66, off
	v_cvt_pk_bf16_f32 v66, v74, s0
	global_store_short v[64:65], v66, off offset:64
	v_or_b32_e32 v64, v98, v192
	v_ashrrev_i32_e32 v65, 31, v64
	v_lshlrev_b64 v[64:65], 11, v[64:65]
	v_lshl_add_u64 v[64:65], v[130:131], 0, v[64:65]
	v_cvt_pk_bf16_f32 v66, v91, s0
	global_store_short v[64:65], v66, off
	v_cvt_pk_bf16_f32 v66, v75, s0
	global_store_short v[64:65], v66, off offset:64
	v_or_b32_e32 v64, v98, v193
	v_ashrrev_i32_e32 v65, 31, v64
	v_lshlrev_b64 v[64:65], 11, v[64:65]
	v_lshl_add_u64 v[64:65], v[130:131], 0, v[64:65]
	v_cvt_pk_bf16_f32 v66, v92, s0
	global_store_short v[64:65], v66, off
	v_cvt_pk_bf16_f32 v66, v76, s0
	global_store_short v[64:65], v66, off offset:64
	v_or_b32_e32 v64, v98, v194
	v_ashrrev_i32_e32 v65, 31, v64
	v_lshlrev_b64 v[64:65], 11, v[64:65]
	v_lshl_add_u64 v[64:65], v[130:131], 0, v[64:65]
	v_cvt_pk_bf16_f32 v66, v93, s0
	global_store_short v[64:65], v66, off
	v_cvt_pk_bf16_f32 v66, v77, s0
	global_store_short v[64:65], v66, off offset:64
	v_or_b32_e32 v64, v98, v195
	v_ashrrev_i32_e32 v65, 31, v64
	v_lshlrev_b64 v[64:65], 11, v[64:65]
	v_lshl_add_u64 v[64:65], v[130:131], 0, v[64:65]
	v_cvt_pk_bf16_f32 v66, v94, s0
	global_store_short v[64:65], v66, off
	v_cvt_pk_bf16_f32 v66, v78, s0
	global_store_short v[64:65], v66, off offset:64
	v_or_b32_e32 v64, v98, v196
	v_ashrrev_i32_e32 v65, 31, v64
	v_lshlrev_b64 v[64:65], 11, v[64:65]
	v_lshl_add_u64 v[64:65], v[130:131], 0, v[64:65]
	v_cvt_pk_bf16_f32 v66, v95, s0
	global_store_short v[64:65], v66, off
	v_cvt_pk_bf16_f32 v66, v79, s0
	global_store_short v[64:65], v66, off offset:64
	v_or_b32_e32 v66, 64, v132
	v_or_b32_e32 v64, v66, v181
	v_ashrrev_i32_e32 v65, 31, v64
	v_lshlrev_b64 v[64:65], 11, v[64:65]
	v_lshl_add_u64 v[64:65], v[130:131], 0, v[64:65]
	v_cvt_pk_bf16_f32 v32, v32, s0
	global_store_short v[64:65], v48, off
	global_store_short v[64:65], v32, off offset:64
	v_or_b32_e32 v64, v66, v182
	v_ashrrev_i32_e32 v65, 31, v64
	v_lshlrev_b64 v[64:65], 11, v[64:65]
	v_lshl_add_u64 v[64:65], v[130:131], 0, v[64:65]
	v_cvt_pk_bf16_f32 v32, v49, s0
	global_store_short v[64:65], v32, off
	v_cvt_pk_bf16_f32 v32, v33, s0
	global_store_short v[64:65], v32, off offset:64
	v_or_b32_e32 v32, v66, v183
	v_ashrrev_i32_e32 v33, 31, v32
	v_lshlrev_b64 v[32:33], 11, v[32:33]
	v_lshl_add_u64 v[32:33], v[130:131], 0, v[32:33]
	v_cvt_pk_bf16_f32 v48, v50, s0
	v_cvt_pk_bf16_f32 v34, v34, s0
	global_store_short v[32:33], v48, off
	global_store_short v[32:33], v34, off offset:64
	v_or_b32_e32 v32, v66, v184
	v_ashrrev_i32_e32 v33, 31, v32
	v_lshlrev_b64 v[32:33], 11, v[32:33]
	v_lshl_add_u64 v[32:33], v[130:131], 0, v[32:33]
	v_cvt_pk_bf16_f32 v34, v51, s0
	global_store_short v[32:33], v34, off
	v_cvt_pk_bf16_f32 v34, v35, s0
	global_store_short v[32:33], v34, off offset:64
	v_or_b32_e32 v32, v66, v185
	v_ashrrev_i32_e32 v33, 31, v32
	v_lshlrev_b64 v[32:33], 11, v[32:33]
	v_lshl_add_u64 v[32:33], v[130:131], 0, v[32:33]
	v_cvt_pk_bf16_f32 v34, v52, s0
	global_store_short v[32:33], v34, off
	v_cvt_pk_bf16_f32 v34, v36, s0
	global_store_short v[32:33], v34, off offset:64
	v_or_b32_e32 v32, v66, v186
	v_ashrrev_i32_e32 v33, 31, v32
	v_lshlrev_b64 v[32:33], 11, v[32:33]
	v_lshl_add_u64 v[32:33], v[130:131], 0, v[32:33]
	v_cvt_pk_bf16_f32 v34, v53, s0
	global_store_short v[32:33], v34, off
	v_cvt_pk_bf16_f32 v34, v37, s0
	global_store_short v[32:33], v34, off offset:64
	v_or_b32_e32 v32, v66, v187
	v_ashrrev_i32_e32 v33, 31, v32
	v_lshlrev_b64 v[32:33], 11, v[32:33]
	v_lshl_add_u64 v[32:33], v[130:131], 0, v[32:33]
	v_cvt_pk_bf16_f32 v34, v54, s0
	global_store_short v[32:33], v34, off
	v_cvt_pk_bf16_f32 v34, v38, s0
	global_store_short v[32:33], v34, off offset:64
	v_or_b32_e32 v32, v66, v188
	v_ashrrev_i32_e32 v33, 31, v32
	v_lshlrev_b64 v[32:33], 11, v[32:33]
	v_lshl_add_u64 v[32:33], v[130:131], 0, v[32:33]
	v_cvt_pk_bf16_f32 v34, v55, s0
	global_store_short v[32:33], v34, off
	v_cvt_pk_bf16_f32 v34, v39, s0
	global_store_short v[32:33], v34, off offset:64
	v_or_b32_e32 v32, v66, v189
	v_ashrrev_i32_e32 v33, 31, v32
	v_lshlrev_b64 v[32:33], 11, v[32:33]
	v_lshl_add_u64 v[32:33], v[130:131], 0, v[32:33]
	v_cvt_pk_bf16_f32 v34, v56, s0
	global_store_short v[32:33], v34, off
	v_cvt_pk_bf16_f32 v34, v40, s0
	global_store_short v[32:33], v34, off offset:64
	v_or_b32_e32 v32, v66, v190
	v_ashrrev_i32_e32 v33, 31, v32
	v_lshlrev_b64 v[32:33], 11, v[32:33]
	v_lshl_add_u64 v[32:33], v[130:131], 0, v[32:33]
	v_cvt_pk_bf16_f32 v34, v57, s0
	global_store_short v[32:33], v34, off
	v_cvt_pk_bf16_f32 v34, v41, s0
	global_store_short v[32:33], v34, off offset:64
	v_or_b32_e32 v32, v66, v191
	v_ashrrev_i32_e32 v33, 31, v32
	v_lshlrev_b64 v[32:33], 11, v[32:33]
	v_lshl_add_u64 v[32:33], v[130:131], 0, v[32:33]
	v_cvt_pk_bf16_f32 v34, v58, s0
	global_store_short v[32:33], v34, off
	v_cvt_pk_bf16_f32 v34, v42, s0
	global_store_short v[32:33], v34, off offset:64
	v_or_b32_e32 v32, v66, v192
	v_ashrrev_i32_e32 v33, 31, v32
	v_lshlrev_b64 v[32:33], 11, v[32:33]
	v_lshl_add_u64 v[32:33], v[130:131], 0, v[32:33]
	v_cvt_pk_bf16_f32 v34, v59, s0
	global_store_short v[32:33], v34, off
	v_cvt_pk_bf16_f32 v34, v43, s0
	global_store_short v[32:33], v34, off offset:64
	v_or_b32_e32 v32, v66, v193
	v_ashrrev_i32_e32 v33, 31, v32
	v_lshlrev_b64 v[32:33], 11, v[32:33]
	v_lshl_add_u64 v[32:33], v[130:131], 0, v[32:33]
	v_cvt_pk_bf16_f32 v34, v60, s0
	global_store_short v[32:33], v34, off
	v_cvt_pk_bf16_f32 v34, v44, s0
	global_store_short v[32:33], v34, off offset:64
	v_or_b32_e32 v32, v66, v194
	v_ashrrev_i32_e32 v33, 31, v32
	v_lshlrev_b64 v[32:33], 11, v[32:33]
	v_lshl_add_u64 v[32:33], v[130:131], 0, v[32:33]
	v_cvt_pk_bf16_f32 v34, v61, s0
	global_store_short v[32:33], v34, off
	v_cvt_pk_bf16_f32 v34, v45, s0
	global_store_short v[32:33], v34, off offset:64
	v_or_b32_e32 v32, v66, v195
	v_ashrrev_i32_e32 v33, 31, v32
	v_lshlrev_b64 v[32:33], 11, v[32:33]
	v_lshl_add_u64 v[32:33], v[130:131], 0, v[32:33]
	v_cvt_pk_bf16_f32 v34, v62, s0
	global_store_short v[32:33], v34, off
	v_cvt_pk_bf16_f32 v34, v46, s0
	global_store_short v[32:33], v34, off offset:64
	v_or_b32_e32 v32, v66, v196
	v_ashrrev_i32_e32 v33, 31, v32
	v_lshlrev_b64 v[32:33], 11, v[32:33]
	v_lshl_add_u64 v[32:33], v[130:131], 0, v[32:33]
	v_cvt_pk_bf16_f32 v34, v63, s0
	global_store_short v[32:33], v34, off
	v_cvt_pk_bf16_f32 v34, v47, s0
	global_store_short v[32:33], v34, off offset:64
	v_or_b32_e32 v34, 0x60, v132
	v_or_b32_e32 v32, v34, v181
	v_ashrrev_i32_e32 v33, 31, v32
	v_lshlrev_b64 v[32:33], 11, v[32:33]
	v_lshl_add_u64 v[32:33], v[130:131], 0, v[32:33]
	v_cvt_pk_bf16_f32 v0, v0, s0
	global_store_short v[32:33], v16, off
	global_store_short v[32:33], v0, off offset:64
	v_or_b32_e32 v32, v34, v182
	v_ashrrev_i32_e32 v33, 31, v32
	v_lshlrev_b64 v[32:33], 11, v[32:33]
	v_lshl_add_u64 v[32:33], v[130:131], 0, v[32:33]
	v_cvt_pk_bf16_f32 v0, v17, s0
	global_store_short v[32:33], v0, off
	v_cvt_pk_bf16_f32 v0, v1, s0
	global_store_short v[32:33], v0, off offset:64
	v_or_b32_e32 v0, v34, v183
	v_ashrrev_i32_e32 v1, 31, v0
	v_lshlrev_b64 v[0:1], 11, v[0:1]
	v_lshl_add_u64 v[0:1], v[130:131], 0, v[0:1]
	v_cvt_pk_bf16_f32 v16, v18, s0
	v_cvt_pk_bf16_f32 v2, v2, s0
	global_store_short v[0:1], v16, off
	global_store_short v[0:1], v2, off offset:64
	v_or_b32_e32 v0, v34, v184
	v_ashrrev_i32_e32 v1, 31, v0
	v_lshlrev_b64 v[0:1], 11, v[0:1]
	v_lshl_add_u64 v[0:1], v[130:131], 0, v[0:1]
	v_cvt_pk_bf16_f32 v2, v19, s0
	global_store_short v[0:1], v2, off
	v_cvt_pk_bf16_f32 v2, v3, s0
	global_store_short v[0:1], v2, off offset:64
	v_or_b32_e32 v0, v34, v185
	v_ashrrev_i32_e32 v1, 31, v0
	v_lshlrev_b64 v[0:1], 11, v[0:1]
	v_lshl_add_u64 v[0:1], v[130:131], 0, v[0:1]
	v_cvt_pk_bf16_f32 v2, v20, s0
	global_store_short v[0:1], v2, off
	v_cvt_pk_bf16_f32 v2, v4, s0
	global_store_short v[0:1], v2, off offset:64
	v_or_b32_e32 v0, v34, v186
	v_ashrrev_i32_e32 v1, 31, v0
	v_lshlrev_b64 v[0:1], 11, v[0:1]
	v_lshl_add_u64 v[0:1], v[130:131], 0, v[0:1]
	v_cvt_pk_bf16_f32 v2, v21, s0
	global_store_short v[0:1], v2, off
	v_cvt_pk_bf16_f32 v2, v5, s0
	global_store_short v[0:1], v2, off offset:64
	v_or_b32_e32 v0, v34, v187
	v_ashrrev_i32_e32 v1, 31, v0
	v_lshlrev_b64 v[0:1], 11, v[0:1]
	v_lshl_add_u64 v[0:1], v[130:131], 0, v[0:1]
	v_cvt_pk_bf16_f32 v2, v22, s0
	global_store_short v[0:1], v2, off
	v_cvt_pk_bf16_f32 v2, v6, s0
	global_store_short v[0:1], v2, off offset:64
	v_or_b32_e32 v0, v34, v188
	v_ashrrev_i32_e32 v1, 31, v0
	v_lshlrev_b64 v[0:1], 11, v[0:1]
	v_lshl_add_u64 v[0:1], v[130:131], 0, v[0:1]
	v_cvt_pk_bf16_f32 v2, v23, s0
	global_store_short v[0:1], v2, off
	v_cvt_pk_bf16_f32 v2, v7, s0
	global_store_short v[0:1], v2, off offset:64
	v_or_b32_e32 v0, v34, v189
	v_ashrrev_i32_e32 v1, 31, v0
	v_lshlrev_b64 v[0:1], 11, v[0:1]
	v_lshl_add_u64 v[0:1], v[130:131], 0, v[0:1]
	v_cvt_pk_bf16_f32 v2, v24, s0
	global_store_short v[0:1], v2, off
	v_cvt_pk_bf16_f32 v2, v8, s0
	global_store_short v[0:1], v2, off offset:64
	v_or_b32_e32 v0, v34, v190
	v_ashrrev_i32_e32 v1, 31, v0
	v_lshlrev_b64 v[0:1], 11, v[0:1]
	v_lshl_add_u64 v[0:1], v[130:131], 0, v[0:1]
	v_cvt_pk_bf16_f32 v2, v25, s0
	global_store_short v[0:1], v2, off
	v_cvt_pk_bf16_f32 v2, v9, s0
	global_store_short v[0:1], v2, off offset:64
	v_or_b32_e32 v0, v34, v191
	v_ashrrev_i32_e32 v1, 31, v0
	v_lshlrev_b64 v[0:1], 11, v[0:1]
	v_lshl_add_u64 v[0:1], v[130:131], 0, v[0:1]
	v_cvt_pk_bf16_f32 v2, v26, s0
	global_store_short v[0:1], v2, off
	v_cvt_pk_bf16_f32 v2, v10, s0
	global_store_short v[0:1], v2, off offset:64
	v_or_b32_e32 v0, v34, v192
	v_ashrrev_i32_e32 v1, 31, v0
	v_lshlrev_b64 v[0:1], 11, v[0:1]
	v_lshl_add_u64 v[0:1], v[130:131], 0, v[0:1]
	v_cvt_pk_bf16_f32 v2, v27, s0
	global_store_short v[0:1], v2, off
	v_cvt_pk_bf16_f32 v2, v11, s0
	global_store_short v[0:1], v2, off offset:64
	v_or_b32_e32 v0, v34, v193
	v_ashrrev_i32_e32 v1, 31, v0
	v_lshlrev_b64 v[0:1], 11, v[0:1]
	v_lshl_add_u64 v[0:1], v[130:131], 0, v[0:1]
	v_cvt_pk_bf16_f32 v2, v28, s0
	global_store_short v[0:1], v2, off
	v_cvt_pk_bf16_f32 v2, v12, s0
	global_store_short v[0:1], v2, off offset:64
	v_or_b32_e32 v0, v34, v194
	v_ashrrev_i32_e32 v1, 31, v0
	v_lshlrev_b64 v[0:1], 11, v[0:1]
	v_lshl_add_u64 v[0:1], v[130:131], 0, v[0:1]
	v_cvt_pk_bf16_f32 v2, v29, s0
	global_store_short v[0:1], v2, off
	v_cvt_pk_bf16_f32 v2, v13, s0
	global_store_short v[0:1], v2, off offset:64
	v_or_b32_e32 v0, v34, v195
	v_ashrrev_i32_e32 v1, 31, v0
	v_lshlrev_b64 v[0:1], 11, v[0:1]
	v_lshl_add_u64 v[0:1], v[130:131], 0, v[0:1]
	v_cvt_pk_bf16_f32 v2, v30, s0
	global_store_short v[0:1], v2, off
	v_cvt_pk_bf16_f32 v2, v14, s0
	global_store_short v[0:1], v2, off offset:64
	v_or_b32_e32 v0, v34, v196
	v_ashrrev_i32_e32 v1, 31, v0
	v_lshlrev_b64 v[0:1], 11, v[0:1]
	v_lshl_add_u64 v[0:1], v[130:131], 0, v[0:1]
	v_cvt_pk_bf16_f32 v2, v31, s0
	global_store_short v[0:1], v2, off
	v_cvt_pk_bf16_f32 v2, v15, s0
	global_store_short v[0:1], v2, off offset:64
	s_cbranch_scc0 .LBB0_262

.LBB0_330:
	s_and_b32 s3, s2, 0x18000
	v_add_u32_e32 v128, s3, v182
	s_add_i32 s3, s2, 0xfffe8000
	s_and_b32 s3, s3, 0x18000
	v_or_b32_e32 v214, s3, v181
	v_add_u32_e32 v215, s3, v178
	s_waitcnt lgkmcnt(0)
	v_mfma_f32_32x32x16_bf16 v[112:127], v[150:153], v[142:145], v[112:127]
	v_mfma_f32_32x32x16_bf16 v[96:111], v[150:153], v[130:133], v[96:111]
	s_waitcnt vmcnt(8)
	s_barrier
	v_add_u32_e32 v194, v214, v179
	v_add_u32_e32 v210, v215, v179
	ds_read_b128 v[190:193], v194 offset:16384
	ds_read_b128 v[194:197], v194 offset:18432
	ds_read_b128 v[198:201], v210
	v_mfma_f32_32x32x16_bf16 v[80:95], v[146:149], v[142:145], v[80:95]
	v_mfma_f32_32x32x16_bf16 v[64:79], v[146:149], v[130:133], v[64:79]
	ds_read_b128 v[202:205], v210 offset:2048
	v_readfirstlane_b32 s3, v128
	s_mov_b32 m0, s3
	s_nop 0
	global_load_lds_dwordx4 v[172:173], off
	v_mfma_f32_32x32x16_bf16 v[48:63], v[138:141], v[142:145], v[48:63]
	v_mfma_f32_32x32x16_bf16 v[32:47], v[138:141], v[130:133], v[32:47]
	ds_read_b128 v[206:209], v210 offset:4096
	s_add_i32 s24, s3, 0x2000
	v_lshl_add_u64 v[150:151], v[172:173], 0, s[26:27]
	s_mov_b32 m0, s24
	s_nop 0
	global_load_lds_dwordx4 v[150:151], off
	v_mfma_f32_32x32x16_bf16 v[16:31], v[134:137], v[142:145], v[16:31]
	v_mfma_f32_32x32x16_bf16 v[0:15], v[134:137], v[130:133], v[0:15]
	ds_read_b128 v[210:213], v210 offset:6144
	s_waitcnt lgkmcnt(3)
	v_mfma_f32_32x32x16_bf16 v[112:127], v[198:201], v[190:193], v[112:127]
	v_add_u32_e32 v128, v214, v180
	ds_read_b128 v[142:145], v128 offset:16384
	v_mfma_f32_32x32x16_bf16 v[96:111], v[198:201], v[194:197], v[96:111]
	ds_read_b128 v[130:133], v128 offset:18432
	s_add_i32 s24, s3, 0x6000
	s_addk_i32 s3, 0x4000
	s_mov_b32 m0, s3
	s_nop 0
	global_load_lds_dwordx4 v[174:175], off
	s_waitcnt lgkmcnt(4)
	v_mfma_f32_32x32x16_bf16 v[80:95], v[202:205], v[190:193], v[80:95]
	v_add_u32_e32 v128, v215, v180
	ds_read_b128 v[150:153], v128
	v_mfma_f32_32x32x16_bf16 v[64:79], v[202:205], v[194:197], v[64:79]
	ds_read_b128 v[146:149], v128 offset:2048
	s_waitcnt lgkmcnt(5)
	v_mfma_f32_32x32x16_bf16 v[48:63], v[206:209], v[190:193], v[48:63]
	ds_read_b128 v[138:141], v128 offset:4096
	v_mfma_f32_32x32x16_bf16 v[32:47], v[206:209], v[194:197], v[32:47]
	ds_read_b128 v[134:137], v128 offset:6144
	v_lshl_add_u64 v[214:215], v[174:175], 0, s[26:27]
	s_mov_b32 m0, s24
	s_nop 0
	global_load_lds_dwordx4 v[214:215], off
	s_waitcnt lgkmcnt(6)
	v_mfma_f32_32x32x16_bf16 v[16:31], v[210:213], v[190:193], v[16:31]
	s_add_i32 s2, s2, 0x8000
	v_lshl_add_u64 v[172:173], v[172:173], 0, 64
	v_lshl_add_u64 v[174:175], v[174:175], 0, 64
	s_cmp_eq_u32 s2, 0x100000
	v_mfma_f32_32x32x16_bf16 v[0:15], v[210:213], v[194:197], v[0:15]
	s_cbranch_scc0 .LBB0_330
	s_waitcnt vmcnt(8) lgkmcnt(0)
	s_barrier
	v_add_u32_e32 v128, v181, v179
	ds_read_b128 v[172:175], v128 offset:49152
	ds_read_b128 v[190:193], v128 offset:51200
	v_add_u32_e32 v128, v178, v179
	ds_read_b128 v[194:197], v128 offset:32768
	ds_read_b128 v[198:201], v128 offset:34816
	ds_read_b128 v[202:205], v128 offset:36864
	ds_read_b128 v[206:209], v128 offset:38912
	s_waitcnt lgkmcnt(9)
	v_mfma_f32_32x32x16_bf16 v[112:127], v[150:153], v[142:145], v[112:127]
	v_mfma_f32_32x32x16_bf16 v[96:111], v[150:153], v[130:133], v[96:111]
	s_waitcnt lgkmcnt(8)
	v_mfma_f32_32x32x16_bf16 v[80:95], v[146:149], v[142:145], v[80:95]
	v_mfma_f32_32x32x16_bf16 v[64:79], v[146:149], v[130:133], v[64:79]
	s_waitcnt lgkmcnt(7)
	v_mfma_f32_32x32x16_bf16 v[48:63], v[138:141], v[142:145], v[48:63]
	v_mfma_f32_32x32x16_bf16 v[32:47], v[138:141], v[130:133], v[32:47]
	s_waitcnt lgkmcnt(6)
	v_mfma_f32_32x32x16_bf16 v[16:31], v[134:137], v[142:145], v[16:31]
	v_mfma_f32_32x32x16_bf16 v[0:15], v[134:137], v[130:133], v[0:15]
	v_add_u32_e32 v128, v181, v180
	ds_read_b128 v[130:133], v128 offset:49152
	ds_read_b128 v[134:137], v128 offset:51200
	v_add_u32_e32 v128, v178, v180
	ds_read_b128 v[138:141], v128 offset:32768
	ds_read_b128 v[142:145], v128 offset:34816
	ds_read_b128 v[146:149], v128 offset:36864
	ds_read_b128 v[150:153], v128 offset:38912
	s_waitcnt lgkmcnt(9)
	v_mfma_f32_32x32x16_bf16 v[112:127], v[194:197], v[172:175], v[112:127]
	v_mfma_f32_32x32x16_bf16 v[96:111], v[194:197], v[190:193], v[96:111]
	s_waitcnt lgkmcnt(8)
	v_mfma_f32_32x32x16_bf16 v[80:95], v[198:201], v[172:175], v[80:95]
	v_mfma_f32_32x32x16_bf16 v[64:79], v[198:201], v[190:193], v[64:79]
	s_waitcnt lgkmcnt(7)
	v_mfma_f32_32x32x16_bf16 v[48:63], v[202:205], v[172:175], v[48:63]
	v_mfma_f32_32x32x16_bf16 v[32:47], v[202:205], v[190:193], v[32:47]
	s_waitcnt vmcnt(4) lgkmcnt(0)
	s_barrier
	v_add_u32_e32 v128, v187, v179
	s_waitcnt lgkmcnt(6)
	v_mfma_f32_32x32x16_bf16 v[16:31], v[206:209], v[172:175], v[16:31]
	v_mfma_f32_32x32x16_bf16 v[0:15], v[206:209], v[190:193], v[0:15]
	ds_read_b128 v[172:175], v128 offset:16384
	ds_read_b128 v[190:193], v128 offset:18432
	v_add_u32_e32 v128, v188, v179
	ds_read_b128 v[194:197], v128
	ds_read_b128 v[198:201], v128 offset:2048
	ds_read_b128 v[202:205], v128 offset:4096
	ds_read_b128 v[206:209], v128 offset:6144
	s_waitcnt lgkmcnt(9)
	v_mfma_f32_32x32x16_bf16 v[112:127], v[138:141], v[130:133], v[112:127]
	v_mfma_f32_32x32x16_bf16 v[96:111], v[138:141], v[134:137], v[96:111]
	s_waitcnt lgkmcnt(8)
	v_mfma_f32_32x32x16_bf16 v[80:95], v[142:145], v[130:133], v[80:95]
	v_mfma_f32_32x32x16_bf16 v[64:79], v[142:145], v[134:137], v[64:79]
	s_waitcnt lgkmcnt(7)
	v_mfma_f32_32x32x16_bf16 v[48:63], v[146:149], v[130:133], v[48:63]
	v_mfma_f32_32x32x16_bf16 v[32:47], v[146:149], v[134:137], v[32:47]
	s_waitcnt lgkmcnt(6)
	v_mfma_f32_32x32x16_bf16 v[16:31], v[150:153], v[130:133], v[16:31]
	v_mfma_f32_32x32x16_bf16 v[0:15], v[150:153], v[134:137], v[0:15]
	v_add_u32_e32 v128, v187, v180
	ds_read_b128 v[130:133], v128 offset:16384
	ds_read_b128 v[134:137], v128 offset:18432
	v_add_u32_e32 v128, v188, v180
	ds_read_b128 v[138:141], v128
	ds_read_b128 v[142:145], v128 offset:2048
	ds_read_b128 v[146:149], v128 offset:4096
	ds_read_b128 v[150:153], v128 offset:6144
	s_waitcnt lgkmcnt(9)
	v_mfma_f32_32x32x16_bf16 v[112:127], v[194:197], v[172:175], v[112:127]
	v_mfma_f32_32x32x16_bf16 v[96:111], v[194:197], v[190:193], v[96:111]
	s_waitcnt lgkmcnt(8)
	v_mfma_f32_32x32x16_bf16 v[80:95], v[198:201], v[172:175], v[80:95]
	v_mfma_f32_32x32x16_bf16 v[64:79], v[198:201], v[190:193], v[64:79]
	s_waitcnt lgkmcnt(7)
	v_mfma_f32_32x32x16_bf16 v[48:63], v[202:205], v[172:175], v[48:63]
	v_mfma_f32_32x32x16_bf16 v[32:47], v[202:205], v[190:193], v[32:47]
	s_waitcnt vmcnt(0) lgkmcnt(0)
	s_barrier
	v_add_u32_e32 v128, v185, v179
	s_waitcnt lgkmcnt(6)
	v_mfma_f32_32x32x16_bf16 v[16:31], v[206:209], v[172:175], v[16:31]
	v_mfma_f32_32x32x16_bf16 v[0:15], v[206:209], v[190:193], v[0:15]
	ds_read_b128 v[172:175], v128 offset:16384
	ds_read_b128 v[190:193], v128 offset:18432
	v_add_u32_e32 v128, v186, v179
	ds_read_b128 v[194:197], v128
	ds_read_b128 v[198:201], v128 offset:2048
	ds_read_b128 v[202:205], v128 offset:4096
	ds_read_b128 v[206:209], v128 offset:6144
	s_waitcnt lgkmcnt(9)
	v_mfma_f32_32x32x16_bf16 v[112:127], v[138:141], v[130:133], v[112:127]
	v_mfma_f32_32x32x16_bf16 v[96:111], v[138:141], v[134:137], v[96:111]
	s_waitcnt lgkmcnt(8)
	v_mfma_f32_32x32x16_bf16 v[80:95], v[142:145], v[130:133], v[80:95]
	v_mfma_f32_32x32x16_bf16 v[64:79], v[142:145], v[134:137], v[64:79]
	s_waitcnt lgkmcnt(7)
	v_mfma_f32_32x32x16_bf16 v[48:63], v[146:149], v[130:133], v[48:63]
	v_mfma_f32_32x32x16_bf16 v[32:47], v[146:149], v[134:137], v[32:47]
	s_waitcnt lgkmcnt(6)
	v_mfma_f32_32x32x16_bf16 v[16:31], v[150:153], v[130:133], v[16:31]
	v_mfma_f32_32x32x16_bf16 v[0:15], v[150:153], v[134:137], v[0:15]
	v_add_u32_e32 v128, v185, v180
	ds_read_b128 v[130:133], v128 offset:16384
	ds_read_b128 v[138:141], v128 offset:18432
	v_add_u32_e32 v128, v186, v180
	ds_read_b128 v[134:137], v128
	ds_read_b128 v[142:145], v128 offset:2048
	ds_read_b128 v[146:149], v128 offset:4096
	ds_read_b128 v[210:213], v128 offset:6144
	s_waitcnt lgkmcnt(9)
	v_mfma_f32_32x32x16_bf16 v[112:127], v[194:197], v[172:175], v[112:127]
	v_mfma_f32_32x32x16_bf16 v[96:111], v[194:197], v[190:193], v[96:111]
	s_waitcnt lgkmcnt(8)
	v_mfma_f32_32x32x16_bf16 v[80:95], v[198:201], v[172:175], v[80:95]
	v_mfma_f32_32x32x16_bf16 v[64:79], v[198:201], v[190:193], v[64:79]
	s_waitcnt lgkmcnt(7)
	v_mfma_f32_32x32x16_bf16 v[48:63], v[202:205], v[172:175], v[48:63]
	v_mfma_f32_32x32x16_bf16 v[32:47], v[202:205], v[190:193], v[32:47]
	s_waitcnt lgkmcnt(6)
	v_mfma_f32_32x32x16_bf16 v[16:31], v[206:209], v[172:175], v[16:31]
	v_add_u32_e32 v150, s0, v157
	s_movk_i32 s2, 0x2000
	s_movk_i32 s0, 0x1fff
	v_cmp_gt_i32_e32 vcc, s2, v150
	s_movk_i32 s2, 0x7ff
	v_mfma_f32_32x32x16_bf16 v[0:15], v[206:209], v[190:193], v[0:15]
	s_waitcnt lgkmcnt(3)
	v_mfma_f32_32x32x16_bf16 v[112:127], v[134:137], v[130:133], v[112:127]
	v_mfma_f32_32x32x16_bf16 v[96:111], v[134:137], v[138:141], v[96:111]
	v_or_b32_e32 v136, s1, v176
	v_cmp_lt_i32_e64 s[0:1], s0, v150
	v_cmp_lt_i32_e64 s[2:3], s2, v136
	s_waitcnt lgkmcnt(2)
	v_mfma_f32_32x32x16_bf16 v[80:95], v[142:145], v[130:133], v[80:95]
	v_mfma_f32_32x32x16_bf16 v[64:79], v[142:145], v[138:141], v[64:79]
	s_waitcnt lgkmcnt(1)
	v_mfma_f32_32x32x16_bf16 v[48:63], v[146:149], v[130:133], v[48:63]
	v_mfma_f32_32x32x16_bf16 v[32:47], v[146:149], v[138:141], v[32:47]
	s_waitcnt lgkmcnt(0)
	v_mfma_f32_32x32x16_bf16 v[16:31], v[210:213], v[130:133], v[16:31]
	v_or_b32_e32 v130, v150, v183
	v_mfma_f32_32x32x16_bf16 v[0:15], v[210:213], v[138:141], v[0:15]
	s_and_saveexec_b64 s[24:25], s[2:3]
	s_xor_b64 s[2:3], exec, s[24:25]
	s_cbranch_execz .LBB0_461
	v_ashrrev_i32_e32 v134, 8, v150
	v_ashrrev_i32_e32 v135, 31, v134
	s_and_saveexec_b64 s[24:25], vcc
	s_xor_b64 s[24:25], exec, s[24:25]
	v_lshlrev_b64 v[140:141], 18, v[134:135]
	v_and_b32_e32 v128, 0x84, v130
	s_or_saveexec_b64 s[24:25], s[24:25]
	v_mov_b64_e32 v[138:139], 0x100
	s_xor_b64 exec, exec, s[24:25]
	v_add_u32_e32 v128, 0xffffe000, v150
	v_lshrrev_b32_e32 v128, 11, v128
	s_mov_b32 s26, 0x240000
	v_mad_u64_u32 v[140:141], s[26:27], v128, s26, v[166:167]
	v_and_b32_e32 v128, 0x784, v130
	v_add_u32_e32 v128, 0x100, v128
	v_mov_b64_e32 v[138:139], 0x900
	s_or_b64 exec, exec, s[24:25]
	v_add_u32_e32 v132, v136, v184
	v_or_b32_e32 v142, 1, v130
	v_or_b32_e32 v144, 2, v130
	v_or_b32_e32 v146, 3, v130
	v_lshl_add_u64 v[140:141], v[140:141], 1, s[6:7]
	v_mad_u64_u32 v[152:153], s[24:25], v138, v132, 0
	v_ashrrev_i32_e32 v131, 31, v130
	v_ashrrev_i32_e32 v143, 31, v142
	v_ashrrev_i32_e32 v145, 31, v144
	v_ashrrev_i32_e32 v147, 31, v146
	v_lshl_add_u64 v[152:153], v[152:153], 1, v[140:141]
	v_lshlrev_b64 v[136:137], 12, v[130:131]
	v_lshlrev_b64 v[142:143], 12, v[142:143]
	v_lshlrev_b64 v[144:145], 12, v[144:145]
	v_lshlrev_b64 v[146:147], 12, v[146:147]
	v_cvt_pk_bf16_f32 v148, v112, v113
	v_cvt_pk_bf16_f32 v149, v114, v115
	v_mov_b32_e32 v133, v129
	v_lshl_add_u64 v[152:153], v[128:129], 1, v[152:153]
	global_store_dwordx2 v[152:153], v[148:149], off
	v_lshl_add_u64 v[148:149], s[18:19], 0, v[136:137]
	v_lshlrev_b64 v[136:137], 2, v[132:133]
	v_lshl_add_u64 v[152:153], s[18:19], 0, v[142:143]
	v_lshl_add_u64 v[172:173], s[18:19], 0, v[144:145]
	v_lshl_add_u64 v[174:175], s[18:19], 0, v[146:147]
	v_lshl_add_u64 v[142:143], v[148:149], 0, v[136:137]
	v_lshl_add_u64 v[144:145], v[152:153], 0, v[136:137]
	v_lshl_add_u64 v[146:147], v[172:173], 0, v[136:137]
	v_lshl_add_u64 v[148:149], v[174:175], 0, v[136:137]
	s_and_saveexec_b64 s[24:25], vcc
	s_cbranch_execz .LBB0_338
	global_store_dword v[142:143], v112, off nt
	global_store_dword v[144:145], v113, off nt
	global_store_dword v[146:147], v114, off nt
	global_store_dword v[148:149], v115, off nt

.LBB0_1102:
	s_and_b32 s7, s6, 0x18000
	v_add_u32_e32 v222, s7, v180
	s_add_i32 s7, s6, 0xfffe8000
	s_and_b32 s7, s7, 0x18000
	v_or_b32_e32 v223, s7, v179
	v_add_u32_e32 v233, s7, v176
	s_waitcnt lgkmcnt(0)
	v_mfma_f32_32x32x16_bf16 v[112:127], v[150:153], v[142:145], v[112:127]
	v_mfma_f32_32x32x16_bf16 v[96:111], v[150:153], v[130:133], v[96:111]
	s_waitcnt vmcnt(8)
	s_barrier
	v_add_u32_e32 v206, v223, v177
	v_add_u32_e32 v234, v233, v177
	ds_read_b128 v[202:205], v206 offset:16384
	ds_read_b128 v[206:209], v206 offset:18432
	ds_read_b128 v[210:213], v234
	v_mfma_f32_32x32x16_bf16 v[80:95], v[146:149], v[142:145], v[80:95]
	v_mfma_f32_32x32x16_bf16 v[64:79], v[146:149], v[130:133], v[64:79]
	ds_read_b128 v[214:217], v234 offset:2048
	v_readfirstlane_b32 s7, v222
	s_mov_b32 m0, s7
	s_nop 0
	global_load_lds_dwordx4 v[170:171], off
	v_mfma_f32_32x32x16_bf16 v[48:63], v[138:141], v[142:145], v[48:63]
	v_mfma_f32_32x32x16_bf16 v[32:47], v[138:141], v[130:133], v[32:47]
	ds_read_b128 v[224:227], v234 offset:4096
	s_add_i32 s10, s7, 0x2000
	v_lshl_add_u64 v[150:151], v[170:171], 0, s[34:35]
	s_mov_b32 m0, s10
	s_nop 0
	global_load_lds_dwordx4 v[150:151], off
	v_mfma_f32_32x32x16_bf16 v[16:31], v[134:137], v[142:145], v[16:31]
	v_mfma_f32_32x32x16_bf16 v[0:15], v[134:137], v[130:133], v[0:15]
	ds_read_b128 v[234:237], v234 offset:6144
	s_waitcnt lgkmcnt(3)
	v_mfma_f32_32x32x16_bf16 v[112:127], v[210:213], v[202:205], v[112:127]
	v_add_u32_e32 v130, v223, v178
	v_add_u32_e32 v134, v233, v178
	ds_read_b128 v[142:145], v130 offset:16384
	v_mfma_f32_32x32x16_bf16 v[96:111], v[210:213], v[206:209], v[96:111]
	ds_read_b128 v[130:133], v130 offset:18432
	s_add_i32 s10, s7, 0x6000
	s_addk_i32 s7, 0x4000
	s_mov_b32 m0, s7
	s_nop 0
	global_load_lds_dwordx4 v[172:173], off
	s_waitcnt lgkmcnt(4)
	v_mfma_f32_32x32x16_bf16 v[80:95], v[214:217], v[202:205], v[80:95]
	ds_read_b128 v[150:153], v134
	v_mfma_f32_32x32x16_bf16 v[64:79], v[214:217], v[206:209], v[64:79]
	ds_read_b128 v[146:149], v134 offset:2048
	s_waitcnt lgkmcnt(5)
	v_mfma_f32_32x32x16_bf16 v[48:63], v[224:227], v[202:205], v[48:63]
	ds_read_b128 v[138:141], v134 offset:4096
	v_mfma_f32_32x32x16_bf16 v[32:47], v[224:227], v[206:209], v[32:47]
	ds_read_b128 v[134:137], v134 offset:6144
	v_lshl_add_u64 v[222:223], v[172:173], 0, s[34:35]
	s_mov_b32 m0, s10
	s_nop 0
	global_load_lds_dwordx4 v[222:223], off
	s_waitcnt lgkmcnt(6)
	v_mfma_f32_32x32x16_bf16 v[16:31], v[234:237], v[202:205], v[16:31]
	s_add_i32 s6, s6, 0x8000
	v_lshl_add_u64 v[170:171], v[170:171], 0, 64
	v_lshl_add_u64 v[172:173], v[172:173], 0, 64
	s_cmp_eq_u32 s6, 0x100000
	v_mfma_f32_32x32x16_bf16 v[0:15], v[234:237], v[206:209], v[0:15]
	s_cbranch_scc0 .LBB0_1102
	s_waitcnt vmcnt(8) lgkmcnt(0)
	s_barrier
	v_add_u32_e32 v202, v179, v177
	v_add_u32_e32 v222, v176, v177
	ds_read_b128 v[170:173], v202 offset:49152
	ds_read_b128 v[202:205], v202 offset:51200
	ds_read_b128 v[206:209], v222 offset:32768
	ds_read_b128 v[210:213], v222 offset:34816
	ds_read_b128 v[214:217], v222 offset:36864
	ds_read_b128 v[224:227], v222 offset:38912
	s_waitcnt lgkmcnt(9)
	v_mfma_f32_32x32x16_bf16 v[112:127], v[150:153], v[142:145], v[112:127]
	v_mfma_f32_32x32x16_bf16 v[96:111], v[150:153], v[130:133], v[96:111]
	s_waitcnt lgkmcnt(8)
	v_mfma_f32_32x32x16_bf16 v[80:95], v[146:149], v[142:145], v[80:95]
	v_mfma_f32_32x32x16_bf16 v[64:79], v[146:149], v[130:133], v[64:79]
	s_waitcnt lgkmcnt(7)
	v_mfma_f32_32x32x16_bf16 v[48:63], v[138:141], v[142:145], v[48:63]
	v_mfma_f32_32x32x16_bf16 v[32:47], v[138:141], v[130:133], v[32:47]
	s_waitcnt lgkmcnt(6)
	v_mfma_f32_32x32x16_bf16 v[16:31], v[134:137], v[142:145], v[16:31]
	v_mfma_f32_32x32x16_bf16 v[0:15], v[134:137], v[130:133], v[0:15]
	v_add_u32_e32 v134, v179, v178
	v_add_u32_e32 v150, v176, v178
	ds_read_b128 v[130:133], v134 offset:49152
	ds_read_b128 v[134:137], v134 offset:51200
	ds_read_b128 v[138:141], v150 offset:32768
	ds_read_b128 v[142:145], v150 offset:34816
	ds_read_b128 v[146:149], v150 offset:36864
	ds_read_b128 v[150:153], v150 offset:38912
	s_waitcnt lgkmcnt(9)
	v_mfma_f32_32x32x16_bf16 v[112:127], v[206:209], v[170:173], v[112:127]
	v_mfma_f32_32x32x16_bf16 v[96:111], v[206:209], v[202:205], v[96:111]
	s_waitcnt lgkmcnt(8)
	v_mfma_f32_32x32x16_bf16 v[80:95], v[210:213], v[170:173], v[80:95]
	v_mfma_f32_32x32x16_bf16 v[64:79], v[210:213], v[202:205], v[64:79]
	s_waitcnt lgkmcnt(7)
	v_mfma_f32_32x32x16_bf16 v[48:63], v[214:217], v[170:173], v[48:63]
	v_mfma_f32_32x32x16_bf16 v[32:47], v[214:217], v[202:205], v[32:47]
	s_waitcnt lgkmcnt(6)
	v_mfma_f32_32x32x16_bf16 v[0:15], v[224:227], v[202:205], v[0:15]
	s_waitcnt vmcnt(4) lgkmcnt(0)
	s_barrier
	v_add_u32_e32 v202, v199, v177
	v_add_u32_e32 v222, v200, v177
	v_mfma_f32_32x32x16_bf16 v[16:31], v[224:227], v[170:173], v[16:31]
	ds_read_b128 v[170:173], v202 offset:16384
	ds_read_b128 v[202:205], v202 offset:18432
	ds_read_b128 v[206:209], v222
	ds_read_b128 v[210:213], v222 offset:2048
	ds_read_b128 v[214:217], v222 offset:4096
	ds_read_b128 v[224:227], v222 offset:6144
	s_waitcnt lgkmcnt(9)
	v_mfma_f32_32x32x16_bf16 v[112:127], v[138:141], v[130:133], v[112:127]
	v_mfma_f32_32x32x16_bf16 v[96:111], v[138:141], v[134:137], v[96:111]
	s_waitcnt lgkmcnt(8)
	v_mfma_f32_32x32x16_bf16 v[80:95], v[142:145], v[130:133], v[80:95]
	v_mfma_f32_32x32x16_bf16 v[64:79], v[142:145], v[134:137], v[64:79]
	s_waitcnt lgkmcnt(7)
	v_mfma_f32_32x32x16_bf16 v[48:63], v[146:149], v[130:133], v[48:63]
	v_mfma_f32_32x32x16_bf16 v[32:47], v[146:149], v[134:137], v[32:47]
	s_waitcnt lgkmcnt(6)
	v_mfma_f32_32x32x16_bf16 v[16:31], v[150:153], v[130:133], v[16:31]
	v_mfma_f32_32x32x16_bf16 v[0:15], v[150:153], v[134:137], v[0:15]
	v_add_u32_e32 v134, v199, v178
	v_add_u32_e32 v150, v200, v178
	ds_read_b128 v[130:133], v134 offset:16384
	ds_read_b128 v[134:137], v134 offset:18432
	ds_read_b128 v[138:141], v150
	ds_read_b128 v[142:145], v150 offset:2048
	ds_read_b128 v[146:149], v150 offset:4096
	ds_read_b128 v[150:153], v150 offset:6144
	s_waitcnt lgkmcnt(9)
	v_mfma_f32_32x32x16_bf16 v[112:127], v[206:209], v[170:173], v[112:127]
	v_mfma_f32_32x32x16_bf16 v[96:111], v[206:209], v[202:205], v[96:111]
	s_waitcnt lgkmcnt(8)
	v_mfma_f32_32x32x16_bf16 v[80:95], v[210:213], v[170:173], v[80:95]
	v_mfma_f32_32x32x16_bf16 v[64:79], v[210:213], v[202:205], v[64:79]
	s_waitcnt lgkmcnt(7)
	v_mfma_f32_32x32x16_bf16 v[48:63], v[214:217], v[170:173], v[48:63]
	v_mfma_f32_32x32x16_bf16 v[32:47], v[214:217], v[202:205], v[32:47]
	s_waitcnt lgkmcnt(6)
	v_mfma_f32_32x32x16_bf16 v[0:15], v[224:227], v[202:205], v[0:15]
	s_waitcnt vmcnt(0) lgkmcnt(0)
	s_barrier
	v_add_u32_e32 v202, v197, v177
	v_add_u32_e32 v222, v198, v177
	v_mfma_f32_32x32x16_bf16 v[16:31], v[224:227], v[170:173], v[16:31]
	ds_read_b128 v[170:173], v202 offset:16384
	ds_read_b128 v[202:205], v202 offset:18432
	ds_read_b128 v[206:209], v222
	ds_read_b128 v[210:213], v222 offset:2048
	ds_read_b128 v[214:217], v222 offset:4096
	ds_read_b128 v[224:227], v222 offset:6144
	s_waitcnt lgkmcnt(9)
	v_mfma_f32_32x32x16_bf16 v[112:127], v[138:141], v[130:133], v[112:127]
	v_mfma_f32_32x32x16_bf16 v[96:111], v[138:141], v[134:137], v[96:111]
	s_waitcnt lgkmcnt(8)
	v_mfma_f32_32x32x16_bf16 v[80:95], v[142:145], v[130:133], v[80:95]
	v_mfma_f32_32x32x16_bf16 v[64:79], v[142:145], v[134:137], v[64:79]
	s_waitcnt lgkmcnt(7)
	v_mfma_f32_32x32x16_bf16 v[48:63], v[146:149], v[130:133], v[48:63]
	v_mfma_f32_32x32x16_bf16 v[32:47], v[146:149], v[134:137], v[32:47]
	s_waitcnt lgkmcnt(6)
	v_mfma_f32_32x32x16_bf16 v[16:31], v[150:153], v[130:133], v[16:31]
	v_mfma_f32_32x32x16_bf16 v[0:15], v[150:153], v[134:137], v[0:15]
	v_add_u32_e32 v134, v197, v178
	v_add_u32_e32 v150, v198, v178
	ds_read_b128 v[130:133], v134 offset:16384
	ds_read_b128 v[134:137], v134 offset:18432
	ds_read_b128 v[138:141], v150
	ds_read_b128 v[142:145], v150 offset:2048
	ds_read_b128 v[146:149], v150 offset:4096
	ds_read_b128 v[150:153], v150 offset:6144
	s_waitcnt lgkmcnt(9)
	v_mfma_f32_32x32x16_bf16 v[112:127], v[206:209], v[170:173], v[112:127]
	v_mfma_f32_32x32x16_bf16 v[96:111], v[206:209], v[202:205], v[96:111]
	s_waitcnt lgkmcnt(8)
	v_mfma_f32_32x32x16_bf16 v[80:95], v[210:213], v[170:173], v[80:95]
	v_mfma_f32_32x32x16_bf16 v[64:79], v[210:213], v[202:205], v[64:79]
	s_waitcnt lgkmcnt(7)
	v_mfma_f32_32x32x16_bf16 v[48:63], v[214:217], v[170:173], v[48:63]
	v_mfma_f32_32x32x16_bf16 v[32:47], v[214:217], v[202:205], v[32:47]
	s_waitcnt lgkmcnt(6)
	v_mfma_f32_32x32x16_bf16 v[16:31], v[224:227], v[170:173], v[16:31]
	v_mfma_f32_32x32x16_bf16 v[0:15], v[224:227], v[202:205], v[0:15]
	s_waitcnt lgkmcnt(3)
	v_mfma_f32_32x32x16_bf16 v[112:127], v[138:141], v[130:133], v[112:127]
	v_mfma_f32_32x32x16_bf16 v[96:111], v[138:141], v[134:137], v[96:111]
	s_nop 10
	v_cvt_pk_bf16_f32 v112, v112, s0
	s_waitcnt lgkmcnt(2)
	v_mfma_f32_32x32x16_bf16 v[80:95], v[142:145], v[130:133], v[80:95]
	v_cvt_pk_bf16_f32 v96, v96, s0
	v_cvt_pk_bf16_f32 v98, v98, s0
	s_waitcnt lgkmcnt(1)
	v_mfma_f32_32x32x16_bf16 v[48:63], v[146:149], v[130:133], v[48:63]
	s_nop 7
	v_cvt_pk_bf16_f32 v80, v80, s0
	s_waitcnt lgkmcnt(0)
	v_mfma_f32_32x32x16_bf16 v[16:31], v[150:153], v[130:133], v[16:31]
	v_add_u32_e32 v132, s3, v128
	v_or_b32_e32 v130, s5, v174
	v_ashrrev_i32_e32 v131, 31, v130
	v_lshl_add_u64 v[130:131], v[130:131], 1, v[158:159]
	v_cvt_pk_bf16_f32 v48, v48, s0
	v_readlane_b32 s3, v252, 7
	s_add_i32 s4, s4, s3
	v_mfma_f32_32x32x16_bf16 v[64:79], v[142:145], v[134:137], v[64:79]
	s_nop 3
	v_cvt_pk_bf16_f32 v16, v16, s0
	v_mfma_f32_32x32x16_bf16 v[32:47], v[146:149], v[134:137], v[32:47]
	s_nop 5
	v_cvt_pk_bf16_f32 v64, v64, s0
	v_cvt_pk_bf16_f32 v66, v66, s0
	v_mfma_f32_32x32x16_bf16 v[0:15], v[150:153], v[134:137], v[0:15]
	v_or_b32_e32 v134, v132, v181
	v_ashrrev_i32_e32 v135, 31, v134
	v_lshlrev_b64 v[134:135], 11, v[134:135]
	v_lshl_add_u64 v[134:135], v[130:131], 0, v[134:135]
	global_store_short v[134:135], v112, off
	global_store_short v[134:135], v96, off offset:64
	v_or_b32_e32 v134, v132, v182
	v_ashrrev_i32_e32 v135, 31, v134
	v_lshlrev_b64 v[134:135], 11, v[134:135]
	v_lshl_add_u64 v[134:135], v[130:131], 0, v[134:135]
	v_cvt_pk_bf16_f32 v96, v113, s0
	global_store_short v[134:135], v96, off
	v_cvt_pk_bf16_f32 v96, v97, s0
	global_store_short v[134:135], v96, off offset:64
	v_or_b32_e32 v96, v132, v183
	v_ashrrev_i32_e32 v97, 31, v96
	v_lshlrev_b64 v[96:97], 11, v[96:97]
	v_lshl_add_u64 v[96:97], v[130:131], 0, v[96:97]
	v_cvt_pk_bf16_f32 v112, v114, s0
	global_store_short v[96:97], v112, off
	global_store_short v[96:97], v98, off offset:64
	v_or_b32_e32 v96, v132, v184
	v_ashrrev_i32_e32 v97, 31, v96
	v_lshlrev_b64 v[96:97], 11, v[96:97]
	v_lshl_add_u64 v[96:97], v[130:131], 0, v[96:97]
	v_cvt_pk_bf16_f32 v98, v115, s0
	global_store_short v[96:97], v98, off
	v_cvt_pk_bf16_f32 v98, v99, s0
	global_store_short v[96:97], v98, off offset:64
	v_or_b32_e32 v96, v132, v185
	v_ashrrev_i32_e32 v97, 31, v96
	v_lshlrev_b64 v[96:97], 11, v[96:97]
	v_lshl_add_u64 v[96:97], v[130:131], 0, v[96:97]
	v_cvt_pk_bf16_f32 v98, v116, s0
	global_store_short v[96:97], v98, off
	v_cvt_pk_bf16_f32 v98, v100, s0
	global_store_short v[96:97], v98, off offset:64
	v_or_b32_e32 v96, v132, v186
	v_ashrrev_i32_e32 v97, 31, v96
	v_lshlrev_b64 v[96:97], 11, v[96:97]
	v_lshl_add_u64 v[96:97], v[130:131], 0, v[96:97]
	v_cvt_pk_bf16_f32 v98, v117, s0
	global_store_short v[96:97], v98, off
	v_cvt_pk_bf16_f32 v98, v101, s0
	global_store_short v[96:97], v98, off offset:64
	v_or_b32_e32 v96, v132, v187
	v_ashrrev_i32_e32 v97, 31, v96
	v_lshlrev_b64 v[96:97], 11, v[96:97]
	v_lshl_add_u64 v[96:97], v[130:131], 0, v[96:97]
	v_cvt_pk_bf16_f32 v98, v118, s0
	global_store_short v[96:97], v98, off
	v_cvt_pk_bf16_f32 v98, v102, s0
	global_store_short v[96:97], v98, off offset:64
	v_or_b32_e32 v96, v132, v188
	v_ashrrev_i32_e32 v97, 31, v96
	v_lshlrev_b64 v[96:97], 11, v[96:97]
	v_lshl_add_u64 v[96:97], v[130:131], 0, v[96:97]
	v_cvt_pk_bf16_f32 v98, v119, s0
	global_store_short v[96:97], v98, off
	v_cvt_pk_bf16_f32 v98, v103, s0
	global_store_short v[96:97], v98, off offset:64
	v_or_b32_e32 v96, v132, v189
	v_ashrrev_i32_e32 v97, 31, v96
	v_lshlrev_b64 v[96:97], 11, v[96:97]
	v_lshl_add_u64 v[96:97], v[130:131], 0, v[96:97]
	v_cvt_pk_bf16_f32 v98, v120, s0
	global_store_short v[96:97], v98, off
	v_cvt_pk_bf16_f32 v98, v104, s0
	global_store_short v[96:97], v98, off offset:64
	v_or_b32_e32 v96, v132, v190
	v_ashrrev_i32_e32 v97, 31, v96
	v_lshlrev_b64 v[96:97], 11, v[96:97]
	v_lshl_add_u64 v[96:97], v[130:131], 0, v[96:97]
	v_cvt_pk_bf16_f32 v98, v121, s0
	global_store_short v[96:97], v98, off
	v_cvt_pk_bf16_f32 v98, v105, s0
	global_store_short v[96:97], v98, off offset:64
	v_or_b32_e32 v96, v132, v191
	v_ashrrev_i32_e32 v97, 31, v96
	v_lshlrev_b64 v[96:97], 11, v[96:97]
	v_lshl_add_u64 v[96:97], v[130:131], 0, v[96:97]
	v_cvt_pk_bf16_f32 v98, v122, s0
	global_store_short v[96:97], v98, off
	v_cvt_pk_bf16_f32 v98, v106, s0
	global_store_short v[96:97], v98, off offset:64
	v_or_b32_e32 v96, v132, v192
	v_ashrrev_i32_e32 v97, 31, v96
	v_lshlrev_b64 v[96:97], 11, v[96:97]
	v_lshl_add_u64 v[96:97], v[130:131], 0, v[96:97]
	v_cvt_pk_bf16_f32 v98, v123, s0
	global_store_short v[96:97], v98, off
	v_cvt_pk_bf16_f32 v98, v107, s0
	global_store_short v[96:97], v98, off offset:64
	v_or_b32_e32 v96, v132, v193
	v_ashrrev_i32_e32 v97, 31, v96
	v_lshlrev_b64 v[96:97], 11, v[96:97]
	v_lshl_add_u64 v[96:97], v[130:131], 0, v[96:97]
	v_cvt_pk_bf16_f32 v98, v124, s0
	global_store_short v[96:97], v98, off
	v_cvt_pk_bf16_f32 v98, v108, s0
	global_store_short v[96:97], v98, off offset:64
	v_or_b32_e32 v96, v132, v194
	v_ashrrev_i32_e32 v97, 31, v96
	v_lshlrev_b64 v[96:97], 11, v[96:97]
	v_lshl_add_u64 v[96:97], v[130:131], 0, v[96:97]
	v_cvt_pk_bf16_f32 v98, v125, s0
	global_store_short v[96:97], v98, off
	v_cvt_pk_bf16_f32 v98, v109, s0
	global_store_short v[96:97], v98, off offset:64
	v_or_b32_e32 v96, v132, v195
	v_ashrrev_i32_e32 v97, 31, v96
	v_lshlrev_b64 v[96:97], 11, v[96:97]
	v_lshl_add_u64 v[96:97], v[130:131], 0, v[96:97]
	v_cvt_pk_bf16_f32 v98, v126, s0
	global_store_short v[96:97], v98, off
	v_cvt_pk_bf16_f32 v98, v110, s0
	global_store_short v[96:97], v98, off offset:64
	v_or_b32_e32 v96, v132, v196
	v_ashrrev_i32_e32 v97, 31, v96
	v_lshlrev_b64 v[96:97], 11, v[96:97]
	v_lshl_add_u64 v[96:97], v[130:131], 0, v[96:97]
	v_cvt_pk_bf16_f32 v98, v127, s0
	global_store_short v[96:97], v98, off
	v_cvt_pk_bf16_f32 v98, v111, s0
	global_store_short v[96:97], v98, off offset:64
	v_or_b32_e32 v98, 32, v132
	v_or_b32_e32 v96, v98, v181
	v_ashrrev_i32_e32 v97, 31, v96
	v_lshlrev_b64 v[96:97], 11, v[96:97]
	v_lshl_add_u64 v[96:97], v[130:131], 0, v[96:97]
	global_store_short v[96:97], v80, off
	global_store_short v[96:97], v64, off offset:64
	v_or_b32_e32 v96, v98, v182
	v_ashrrev_i32_e32 v97, 31, v96
	v_lshlrev_b64 v[96:97], 11, v[96:97]
	v_lshl_add_u64 v[96:97], v[130:131], 0, v[96:97]
	v_cvt_pk_bf16_f32 v64, v81, s0
	global_store_short v[96:97], v64, off
	v_cvt_pk_bf16_f32 v64, v65, s0
	global_store_short v[96:97], v64, off offset:64
	v_or_b32_e32 v64, v98, v183
	v_ashrrev_i32_e32 v65, 31, v64
	v_lshlrev_b64 v[64:65], 11, v[64:65]
	v_lshl_add_u64 v[64:65], v[130:131], 0, v[64:65]
	v_cvt_pk_bf16_f32 v80, v82, s0
	global_store_short v[64:65], v80, off
	global_store_short v[64:65], v66, off offset:64
	v_or_b32_e32 v64, v98, v184
	v_ashrrev_i32_e32 v65, 31, v64
	v_lshlrev_b64 v[64:65], 11, v[64:65]
	v_lshl_add_u64 v[64:65], v[130:131], 0, v[64:65]
	v_cvt_pk_bf16_f32 v66, v83, s0
	global_store_short v[64:65], v66, off
	v_cvt_pk_bf16_f32 v66, v67, s0
	global_store_short v[64:65], v66, off offset:64
	v_or_b32_e32 v64, v98, v185
	v_ashrrev_i32_e32 v65, 31, v64
	v_lshlrev_b64 v[64:65], 11, v[64:65]
	v_lshl_add_u64 v[64:65], v[130:131], 0, v[64:65]
	v_cvt_pk_bf16_f32 v66, v84, s0
	global_store_short v[64:65], v66, off
	v_cvt_pk_bf16_f32 v66, v68, s0
	global_store_short v[64:65], v66, off offset:64
	v_or_b32_e32 v64, v98, v186
	v_ashrrev_i32_e32 v65, 31, v64
	v_lshlrev_b64 v[64:65], 11, v[64:65]
	v_lshl_add_u64 v[64:65], v[130:131], 0, v[64:65]
	v_cvt_pk_bf16_f32 v66, v85, s0
	global_store_short v[64:65], v66, off
	v_cvt_pk_bf16_f32 v66, v69, s0
	global_store_short v[64:65], v66, off offset:64
	v_or_b32_e32 v64, v98, v187
	v_ashrrev_i32_e32 v65, 31, v64
	v_lshlrev_b64 v[64:65], 11, v[64:65]
	v_lshl_add_u64 v[64:65], v[130:131], 0, v[64:65]
	v_cvt_pk_bf16_f32 v66, v86, s0
	global_store_short v[64:65], v66, off
	v_cvt_pk_bf16_f32 v66, v70, s0
	global_store_short v[64:65], v66, off offset:64
	v_or_b32_e32 v64, v98, v188
	v_ashrrev_i32_e32 v65, 31, v64
	v_lshlrev_b64 v[64:65], 11, v[64:65]
	v_lshl_add_u64 v[64:65], v[130:131], 0, v[64:65]
	v_cvt_pk_bf16_f32 v66, v87, s0
	global_store_short v[64:65], v66, off
	v_cvt_pk_bf16_f32 v66, v71, s0
	global_store_short v[64:65], v66, off offset:64
	v_or_b32_e32 v64, v98, v189
	v_ashrrev_i32_e32 v65, 31, v64
	v_lshlrev_b64 v[64:65], 11, v[64:65]
	v_lshl_add_u64 v[64:65], v[130:131], 0, v[64:65]
	v_cvt_pk_bf16_f32 v66, v88, s0
	global_store_short v[64:65], v66, off
	v_cvt_pk_bf16_f32 v66, v72, s0
	global_store_short v[64:65], v66, off offset:64
	v_or_b32_e32 v64, v98, v190
	v_ashrrev_i32_e32 v65, 31, v64
	v_lshlrev_b64 v[64:65], 11, v[64:65]
	v_lshl_add_u64 v[64:65], v[130:131], 0, v[64:65]
	v_cvt_pk_bf16_f32 v66, v89, s0
	global_store_short v[64:65], v66, off
	v_cvt_pk_bf16_f32 v66, v73, s0
	global_store_short v[64:65], v66, off offset:64
	v_or_b32_e32 v64, v98, v191
	v_ashrrev_i32_e32 v65, 31, v64
	v_lshlrev_b64 v[64:65], 11, v[64:65]
	v_lshl_add_u64 v[64:65], v[130:131], 0, v[64:65]
	v_cvt_pk_bf16_f32 v66, v90, s0
	global_store_short v[64:65], v66, off
	v_cvt_pk_bf16_f32 v66, v74, s0
	global_store_short v[64:65], v66, off offset:64
	v_or_b32_e32 v64, v98, v192
	v_ashrrev_i32_e32 v65, 31, v64
	v_lshlrev_b64 v[64:65], 11, v[64:65]
	v_lshl_add_u64 v[64:65], v[130:131], 0, v[64:65]
	v_cvt_pk_bf16_f32 v66, v91, s0
	global_store_short v[64:65], v66, off
	v_cvt_pk_bf16_f32 v66, v75, s0
	global_store_short v[64:65], v66, off offset:64
	v_or_b32_e32 v64, v98, v193
	v_ashrrev_i32_e32 v65, 31, v64
	v_lshlrev_b64 v[64:65], 11, v[64:65]
	v_lshl_add_u64 v[64:65], v[130:131], 0, v[64:65]
	v_cvt_pk_bf16_f32 v66, v92, s0
	global_store_short v[64:65], v66, off
	v_cvt_pk_bf16_f32 v66, v76, s0
	global_store_short v[64:65], v66, off offset:64
	v_or_b32_e32 v64, v98, v194
	v_ashrrev_i32_e32 v65, 31, v64
	v_lshlrev_b64 v[64:65], 11, v[64:65]
	v_lshl_add_u64 v[64:65], v[130:131], 0, v[64:65]
	v_cvt_pk_bf16_f32 v66, v93, s0
	global_store_short v[64:65], v66, off
	v_cvt_pk_bf16_f32 v66, v77, s0
	global_store_short v[64:65], v66, off offset:64
	v_or_b32_e32 v64, v98, v195
	v_ashrrev_i32_e32 v65, 31, v64
	v_lshlrev_b64 v[64:65], 11, v[64:65]
	v_lshl_add_u64 v[64:65], v[130:131], 0, v[64:65]
	v_cvt_pk_bf16_f32 v66, v94, s0
	global_store_short v[64:65], v66, off
	v_cvt_pk_bf16_f32 v66, v78, s0
	global_store_short v[64:65], v66, off offset:64
	v_or_b32_e32 v64, v98, v196
	v_ashrrev_i32_e32 v65, 31, v64
	v_lshlrev_b64 v[64:65], 11, v[64:65]
	v_lshl_add_u64 v[64:65], v[130:131], 0, v[64:65]
	v_cvt_pk_bf16_f32 v66, v95, s0
	global_store_short v[64:65], v66, off
	v_cvt_pk_bf16_f32 v66, v79, s0
	global_store_short v[64:65], v66, off offset:64
	v_or_b32_e32 v66, 64, v132
	v_or_b32_e32 v64, v66, v181
	v_ashrrev_i32_e32 v65, 31, v64
	v_lshlrev_b64 v[64:65], 11, v[64:65]
	v_lshl_add_u64 v[64:65], v[130:131], 0, v[64:65]
	v_cvt_pk_bf16_f32 v32, v32, s0
	global_store_short v[64:65], v48, off
	global_store_short v[64:65], v32, off offset:64
	v_or_b32_e32 v64, v66, v182
	v_ashrrev_i32_e32 v65, 31, v64
	v_lshlrev_b64 v[64:65], 11, v[64:65]
	v_lshl_add_u64 v[64:65], v[130:131], 0, v[64:65]
	v_cvt_pk_bf16_f32 v32, v49, s0
	global_store_short v[64:65], v32, off
	v_cvt_pk_bf16_f32 v32, v33, s0
	global_store_short v[64:65], v32, off offset:64
	v_or_b32_e32 v32, v66, v183
	v_ashrrev_i32_e32 v33, 31, v32
	v_lshlrev_b64 v[32:33], 11, v[32:33]
	v_lshl_add_u64 v[32:33], v[130:131], 0, v[32:33]
	v_cvt_pk_bf16_f32 v48, v50, s0
	v_cvt_pk_bf16_f32 v34, v34, s0
	global_store_short v[32:33], v48, off
	global_store_short v[32:33], v34, off offset:64
	v_or_b32_e32 v32, v66, v184
	v_ashrrev_i32_e32 v33, 31, v32
	v_lshlrev_b64 v[32:33], 11, v[32:33]
	v_lshl_add_u64 v[32:33], v[130:131], 0, v[32:33]
	v_cvt_pk_bf16_f32 v34, v51, s0
	global_store_short v[32:33], v34, off
	v_cvt_pk_bf16_f32 v34, v35, s0
	global_store_short v[32:33], v34, off offset:64
	v_or_b32_e32 v32, v66, v185
	v_ashrrev_i32_e32 v33, 31, v32
	v_lshlrev_b64 v[32:33], 11, v[32:33]
	v_lshl_add_u64 v[32:33], v[130:131], 0, v[32:33]
	v_cvt_pk_bf16_f32 v34, v52, s0
	global_store_short v[32:33], v34, off
	v_cvt_pk_bf16_f32 v34, v36, s0
	global_store_short v[32:33], v34, off offset:64
	v_or_b32_e32 v32, v66, v186
	v_ashrrev_i32_e32 v33, 31, v32
	v_lshlrev_b64 v[32:33], 11, v[32:33]
	v_lshl_add_u64 v[32:33], v[130:131], 0, v[32:33]
	v_cvt_pk_bf16_f32 v34, v53, s0
	global_store_short v[32:33], v34, off
	v_cvt_pk_bf16_f32 v34, v37, s0
	global_store_short v[32:33], v34, off offset:64
	v_or_b32_e32 v32, v66, v187
	v_ashrrev_i32_e32 v33, 31, v32
	v_lshlrev_b64 v[32:33], 11, v[32:33]
	v_lshl_add_u64 v[32:33], v[130:131], 0, v[32:33]
	v_cvt_pk_bf16_f32 v34, v54, s0
	global_store_short v[32:33], v34, off
	v_cvt_pk_bf16_f32 v34, v38, s0
	global_store_short v[32:33], v34, off offset:64
	v_or_b32_e32 v32, v66, v188
	v_ashrrev_i32_e32 v33, 31, v32
	v_lshlrev_b64 v[32:33], 11, v[32:33]
	v_lshl_add_u64 v[32:33], v[130:131], 0, v[32:33]
	v_cvt_pk_bf16_f32 v34, v55, s0
	global_store_short v[32:33], v34, off
	v_cvt_pk_bf16_f32 v34, v39, s0
	global_store_short v[32:33], v34, off offset:64
	v_or_b32_e32 v32, v66, v189
	v_ashrrev_i32_e32 v33, 31, v32
	v_lshlrev_b64 v[32:33], 11, v[32:33]
	v_lshl_add_u64 v[32:33], v[130:131], 0, v[32:33]
	v_cvt_pk_bf16_f32 v34, v56, s0
	global_store_short v[32:33], v34, off
	v_cvt_pk_bf16_f32 v34, v40, s0
	global_store_short v[32:33], v34, off offset:64
	v_or_b32_e32 v32, v66, v190
	v_ashrrev_i32_e32 v33, 31, v32
	v_lshlrev_b64 v[32:33], 11, v[32:33]
	v_lshl_add_u64 v[32:33], v[130:131], 0, v[32:33]
	v_cvt_pk_bf16_f32 v34, v57, s0
	global_store_short v[32:33], v34, off
	v_cvt_pk_bf16_f32 v34, v41, s0
	global_store_short v[32:33], v34, off offset:64
	v_or_b32_e32 v32, v66, v191
	v_ashrrev_i32_e32 v33, 31, v32
	v_lshlrev_b64 v[32:33], 11, v[32:33]
	v_lshl_add_u64 v[32:33], v[130:131], 0, v[32:33]
	v_cvt_pk_bf16_f32 v34, v58, s0
	global_store_short v[32:33], v34, off
	v_cvt_pk_bf16_f32 v34, v42, s0
	global_store_short v[32:33], v34, off offset:64
	v_or_b32_e32 v32, v66, v192
	v_ashrrev_i32_e32 v33, 31, v32
	v_lshlrev_b64 v[32:33], 11, v[32:33]
	v_lshl_add_u64 v[32:33], v[130:131], 0, v[32:33]
	v_cvt_pk_bf16_f32 v34, v59, s0
	global_store_short v[32:33], v34, off
	v_cvt_pk_bf16_f32 v34, v43, s0
	global_store_short v[32:33], v34, off offset:64
	v_or_b32_e32 v32, v66, v193
	v_ashrrev_i32_e32 v33, 31, v32
	v_lshlrev_b64 v[32:33], 11, v[32:33]
	v_lshl_add_u64 v[32:33], v[130:131], 0, v[32:33]
	v_cvt_pk_bf16_f32 v34, v60, s0
	global_store_short v[32:33], v34, off
	v_cvt_pk_bf16_f32 v34, v44, s0
	global_store_short v[32:33], v34, off offset:64
	v_or_b32_e32 v32, v66, v194
	v_ashrrev_i32_e32 v33, 31, v32
	v_lshlrev_b64 v[32:33], 11, v[32:33]
	v_lshl_add_u64 v[32:33], v[130:131], 0, v[32:33]
	v_cvt_pk_bf16_f32 v34, v61, s0
	global_store_short v[32:33], v34, off
	v_cvt_pk_bf16_f32 v34, v45, s0
	global_store_short v[32:33], v34, off offset:64
	v_or_b32_e32 v32, v66, v195
	v_ashrrev_i32_e32 v33, 31, v32
	v_lshlrev_b64 v[32:33], 11, v[32:33]
	v_lshl_add_u64 v[32:33], v[130:131], 0, v[32:33]
	v_cvt_pk_bf16_f32 v34, v62, s0
	global_store_short v[32:33], v34, off
	v_cvt_pk_bf16_f32 v34, v46, s0
	global_store_short v[32:33], v34, off offset:64
	v_or_b32_e32 v32, v66, v196
	v_ashrrev_i32_e32 v33, 31, v32
	v_lshlrev_b64 v[32:33], 11, v[32:33]
	v_lshl_add_u64 v[32:33], v[130:131], 0, v[32:33]
	v_cvt_pk_bf16_f32 v34, v63, s0
	global_store_short v[32:33], v34, off
	v_cvt_pk_bf16_f32 v34, v47, s0
	global_store_short v[32:33], v34, off offset:64
	v_or_b32_e32 v34, 0x60, v132
	v_or_b32_e32 v32, v34, v181
	v_ashrrev_i32_e32 v33, 31, v32
	v_lshlrev_b64 v[32:33], 11, v[32:33]
	v_lshl_add_u64 v[32:33], v[130:131], 0, v[32:33]
	v_cvt_pk_bf16_f32 v0, v0, s0
	global_store_short v[32:33], v16, off
	global_store_short v[32:33], v0, off offset:64
	v_or_b32_e32 v32, v34, v182
	v_ashrrev_i32_e32 v33, 31, v32
	v_lshlrev_b64 v[32:33], 11, v[32:33]
	v_lshl_add_u64 v[32:33], v[130:131], 0, v[32:33]
	v_cvt_pk_bf16_f32 v0, v17, s0
	global_store_short v[32:33], v0, off
	v_cvt_pk_bf16_f32 v0, v1, s0
	global_store_short v[32:33], v0, off offset:64
	v_or_b32_e32 v0, v34, v183
	v_ashrrev_i32_e32 v1, 31, v0
	v_lshlrev_b64 v[0:1], 11, v[0:1]
	v_lshl_add_u64 v[0:1], v[130:131], 0, v[0:1]
	v_cvt_pk_bf16_f32 v16, v18, s0
	v_cvt_pk_bf16_f32 v2, v2, s0
	global_store_short v[0:1], v16, off
	global_store_short v[0:1], v2, off offset:64
	v_or_b32_e32 v0, v34, v184
	v_ashrrev_i32_e32 v1, 31, v0
	v_lshlrev_b64 v[0:1], 11, v[0:1]
	v_lshl_add_u64 v[0:1], v[130:131], 0, v[0:1]
	v_cvt_pk_bf16_f32 v2, v19, s0
	global_store_short v[0:1], v2, off
	v_cvt_pk_bf16_f32 v2, v3, s0
	global_store_short v[0:1], v2, off offset:64
	v_or_b32_e32 v0, v34, v185
	v_ashrrev_i32_e32 v1, 31, v0
	v_lshlrev_b64 v[0:1], 11, v[0:1]
	v_lshl_add_u64 v[0:1], v[130:131], 0, v[0:1]
	v_cvt_pk_bf16_f32 v2, v20, s0
	global_store_short v[0:1], v2, off
	v_cvt_pk_bf16_f32 v2, v4, s0
	global_store_short v[0:1], v2, off offset:64
	v_or_b32_e32 v0, v34, v186
	v_ashrrev_i32_e32 v1, 31, v0
	v_lshlrev_b64 v[0:1], 11, v[0:1]
	v_lshl_add_u64 v[0:1], v[130:131], 0, v[0:1]
	v_cvt_pk_bf16_f32 v2, v21, s0
	global_store_short v[0:1], v2, off
	v_cvt_pk_bf16_f32 v2, v5, s0
	global_store_short v[0:1], v2, off offset:64
	v_or_b32_e32 v0, v34, v187
	v_ashrrev_i32_e32 v1, 31, v0
	v_lshlrev_b64 v[0:1], 11, v[0:1]
	v_lshl_add_u64 v[0:1], v[130:131], 0, v[0:1]
	v_cvt_pk_bf16_f32 v2, v22, s0
	global_store_short v[0:1], v2, off
	v_cvt_pk_bf16_f32 v2, v6, s0
	global_store_short v[0:1], v2, off offset:64
	v_or_b32_e32 v0, v34, v188
	v_ashrrev_i32_e32 v1, 31, v0
	v_lshlrev_b64 v[0:1], 11, v[0:1]
	v_lshl_add_u64 v[0:1], v[130:131], 0, v[0:1]
	v_cvt_pk_bf16_f32 v2, v23, s0
	global_store_short v[0:1], v2, off
	v_cvt_pk_bf16_f32 v2, v7, s0
	global_store_short v[0:1], v2, off offset:64
	v_or_b32_e32 v0, v34, v189
	v_ashrrev_i32_e32 v1, 31, v0
	v_lshlrev_b64 v[0:1], 11, v[0:1]
	v_lshl_add_u64 v[0:1], v[130:131], 0, v[0:1]
	v_cvt_pk_bf16_f32 v2, v24, s0
	global_store_short v[0:1], v2, off
	v_cvt_pk_bf16_f32 v2, v8, s0
	global_store_short v[0:1], v2, off offset:64
	v_or_b32_e32 v0, v34, v190
	v_ashrrev_i32_e32 v1, 31, v0
	v_lshlrev_b64 v[0:1], 11, v[0:1]
	v_lshl_add_u64 v[0:1], v[130:131], 0, v[0:1]
	v_cvt_pk_bf16_f32 v2, v25, s0
	global_store_short v[0:1], v2, off
	v_cvt_pk_bf16_f32 v2, v9, s0
	global_store_short v[0:1], v2, off offset:64
	v_or_b32_e32 v0, v34, v191
	v_ashrrev_i32_e32 v1, 31, v0
	v_lshlrev_b64 v[0:1], 11, v[0:1]
	v_lshl_add_u64 v[0:1], v[130:131], 0, v[0:1]
	v_cvt_pk_bf16_f32 v2, v26, s0
	global_store_short v[0:1], v2, off
	v_cvt_pk_bf16_f32 v2, v10, s0
	global_store_short v[0:1], v2, off offset:64
	v_or_b32_e32 v0, v34, v192
	v_ashrrev_i32_e32 v1, 31, v0
	v_lshlrev_b64 v[0:1], 11, v[0:1]
	v_lshl_add_u64 v[0:1], v[130:131], 0, v[0:1]
	v_cvt_pk_bf16_f32 v2, v27, s0
	global_store_short v[0:1], v2, off
	v_cvt_pk_bf16_f32 v2, v11, s0
	global_store_short v[0:1], v2, off offset:64
	v_or_b32_e32 v0, v34, v193
	v_ashrrev_i32_e32 v1, 31, v0
	v_lshlrev_b64 v[0:1], 11, v[0:1]
	v_lshl_add_u64 v[0:1], v[130:131], 0, v[0:1]
	v_cvt_pk_bf16_f32 v2, v28, s0
	global_store_short v[0:1], v2, off
	v_cvt_pk_bf16_f32 v2, v12, s0
	global_store_short v[0:1], v2, off offset:64
	v_or_b32_e32 v0, v34, v194
	v_ashrrev_i32_e32 v1, 31, v0
	v_lshlrev_b64 v[0:1], 11, v[0:1]
	v_lshl_add_u64 v[0:1], v[130:131], 0, v[0:1]
	v_cvt_pk_bf16_f32 v2, v29, s0
	global_store_short v[0:1], v2, off
	v_cvt_pk_bf16_f32 v2, v13, s0
	global_store_short v[0:1], v2, off offset:64
	v_or_b32_e32 v0, v34, v195
	v_ashrrev_i32_e32 v1, 31, v0
	v_lshlrev_b64 v[0:1], 11, v[0:1]
	v_lshl_add_u64 v[0:1], v[130:131], 0, v[0:1]
	v_cvt_pk_bf16_f32 v2, v30, s0
	global_store_short v[0:1], v2, off
	v_cvt_pk_bf16_f32 v2, v14, s0
	global_store_short v[0:1], v2, off offset:64
	v_or_b32_e32 v0, v34, v196
	v_ashrrev_i32_e32 v1, 31, v0
	v_lshlrev_b64 v[0:1], 11, v[0:1]
	v_lshl_add_u64 v[0:1], v[130:131], 0, v[0:1]
	v_cvt_pk_bf16_f32 v2, v31, s0
	global_store_short v[0:1], v2, off
	v_cvt_pk_bf16_f32 v2, v15, s0
	s_add_i32 s0, s0, s3
	v_readlane_b32 s3, v252, 8
	s_add_i32 s2, s2, s3
	s_cmp_gt_i32 s4, 31
	global_store_short v[0:1], v2, off offset:64
	s_cbranch_scc0 .LBB0_1101

.LBB0_1161:
	s_and_b32 s21, s20, 0x18000
	v_add_u32_e32 v128, s21, v203
	s_add_i32 s21, s20, 0xfffe8000
	s_and_b32 s21, s21, 0x18000
	v_or_b32_e32 v222, s21, v202
	v_add_u32_e32 v223, s21, v199
	s_waitcnt lgkmcnt(0)
	v_mfma_f32_32x32x16_bf16 v[112:127], v[150:153], v[142:145], v[112:127]
	v_mfma_f32_32x32x16_bf16 v[96:111], v[150:153], v[130:133], v[96:111]
	s_waitcnt vmcnt(8)
	s_barrier
	v_add_u32_e32 v180, v222, v200
	v_add_u32_e32 v224, v223, v200
	ds_read_b128 v[176:179], v180 offset:16384
	ds_read_b128 v[180:183], v180 offset:18432
	ds_read_b128 v[184:187], v224
	v_mfma_f32_32x32x16_bf16 v[80:95], v[146:149], v[142:145], v[80:95]
	v_mfma_f32_32x32x16_bf16 v[64:79], v[146:149], v[130:133], v[64:79]
	ds_read_b128 v[188:191], v224 offset:2048
	v_readfirstlane_b32 s21, v128
	s_mov_b32 m0, s21
	s_nop 0
	global_load_lds_dwordx4 v[172:173], off
	v_mfma_f32_32x32x16_bf16 v[48:63], v[138:141], v[142:145], v[48:63]
	v_mfma_f32_32x32x16_bf16 v[32:47], v[138:141], v[130:133], v[32:47]
	ds_read_b128 v[192:195], v224 offset:4096
	s_add_i32 s22, s21, 0x2000
	v_lshl_add_u64 v[150:151], v[172:173], 0, s[26:27]
	s_mov_b32 m0, s22
	s_nop 0
	global_load_lds_dwordx4 v[150:151], off
	v_mfma_f32_32x32x16_bf16 v[16:31], v[134:137], v[142:145], v[16:31]
	v_mfma_f32_32x32x16_bf16 v[0:15], v[134:137], v[130:133], v[0:15]
	ds_read_b128 v[240:243], v224 offset:6144
	s_waitcnt lgkmcnt(3)
	v_mfma_f32_32x32x16_bf16 v[112:127], v[184:187], v[176:179], v[112:127]
	v_add_u32_e32 v128, v222, v201
	ds_read_b128 v[142:145], v128 offset:16384
	v_mfma_f32_32x32x16_bf16 v[96:111], v[184:187], v[180:183], v[96:111]
	ds_read_b128 v[130:133], v128 offset:18432
	s_add_i32 s22, s21, 0x6000
	s_addk_i32 s21, 0x4000
	s_mov_b32 m0, s21
	s_nop 0
	global_load_lds_dwordx4 v[174:175], off
	s_waitcnt lgkmcnt(4)
	v_mfma_f32_32x32x16_bf16 v[80:95], v[188:191], v[176:179], v[80:95]
	v_add_u32_e32 v128, v223, v201
	ds_read_b128 v[150:153], v128
	v_mfma_f32_32x32x16_bf16 v[64:79], v[188:191], v[180:183], v[64:79]
	ds_read_b128 v[146:149], v128 offset:2048
	s_waitcnt lgkmcnt(5)
	v_mfma_f32_32x32x16_bf16 v[48:63], v[192:195], v[176:179], v[48:63]
	ds_read_b128 v[138:141], v128 offset:4096
	v_mfma_f32_32x32x16_bf16 v[32:47], v[192:195], v[180:183], v[32:47]
	ds_read_b128 v[134:137], v128 offset:6144
	v_lshl_add_u64 v[224:225], v[174:175], 0, s[26:27]
	s_mov_b32 m0, s22
	s_nop 0
	global_load_lds_dwordx4 v[224:225], off
	s_waitcnt lgkmcnt(6)
	v_mfma_f32_32x32x16_bf16 v[16:31], v[240:243], v[176:179], v[16:31]
	s_add_i32 s20, s20, 0x8000
	v_lshl_add_u64 v[172:173], v[172:173], 0, 64
	v_lshl_add_u64 v[174:175], v[174:175], 0, 64
	s_cmp_eq_u32 s20, 0x100000
	v_mfma_f32_32x32x16_bf16 v[0:15], v[240:243], v[180:183], v[0:15]
	s_cbranch_scc0 .LBB0_1161
	s_waitcnt vmcnt(8) lgkmcnt(0)
	s_barrier
	v_add_u32_e32 v128, v202, v200
	ds_read_b128 v[172:175], v128 offset:49152
	ds_read_b128 v[176:179], v128 offset:51200
	v_add_u32_e32 v128, v199, v200
	ds_read_b128 v[180:183], v128 offset:32768
	ds_read_b128 v[184:187], v128 offset:34816
	ds_read_b128 v[188:191], v128 offset:36864
	ds_read_b128 v[192:195], v128 offset:38912
	s_waitcnt lgkmcnt(9)
	v_mfma_f32_32x32x16_bf16 v[112:127], v[150:153], v[142:145], v[112:127]
	v_mfma_f32_32x32x16_bf16 v[96:111], v[150:153], v[130:133], v[96:111]
	s_waitcnt lgkmcnt(8)
	v_mfma_f32_32x32x16_bf16 v[80:95], v[146:149], v[142:145], v[80:95]
	v_mfma_f32_32x32x16_bf16 v[64:79], v[146:149], v[130:133], v[64:79]
	s_waitcnt lgkmcnt(7)
	v_mfma_f32_32x32x16_bf16 v[48:63], v[138:141], v[142:145], v[48:63]
	v_mfma_f32_32x32x16_bf16 v[32:47], v[138:141], v[130:133], v[32:47]
	s_waitcnt lgkmcnt(6)
	v_mfma_f32_32x32x16_bf16 v[16:31], v[134:137], v[142:145], v[16:31]
	v_mfma_f32_32x32x16_bf16 v[0:15], v[134:137], v[130:133], v[0:15]
	v_add_u32_e32 v128, v202, v201
	ds_read_b128 v[130:133], v128 offset:49152
	ds_read_b128 v[134:137], v128 offset:51200
	v_add_u32_e32 v128, v199, v201
	ds_read_b128 v[138:141], v128 offset:32768
	ds_read_b128 v[142:145], v128 offset:34816
	ds_read_b128 v[146:149], v128 offset:36864
	ds_read_b128 v[150:153], v128 offset:38912
	s_waitcnt lgkmcnt(9)
	v_mfma_f32_32x32x16_bf16 v[112:127], v[180:183], v[172:175], v[112:127]
	v_mfma_f32_32x32x16_bf16 v[96:111], v[180:183], v[176:179], v[96:111]
	s_waitcnt lgkmcnt(8)
	v_mfma_f32_32x32x16_bf16 v[80:95], v[184:187], v[172:175], v[80:95]
	v_mfma_f32_32x32x16_bf16 v[64:79], v[184:187], v[176:179], v[64:79]
	s_waitcnt lgkmcnt(7)
	v_mfma_f32_32x32x16_bf16 v[48:63], v[188:191], v[172:175], v[48:63]
	v_mfma_f32_32x32x16_bf16 v[32:47], v[188:191], v[176:179], v[32:47]
	s_waitcnt vmcnt(4) lgkmcnt(0)
	s_barrier
	v_add_u32_e32 v128, v236, v200
	s_waitcnt lgkmcnt(6)
	v_mfma_f32_32x32x16_bf16 v[16:31], v[192:195], v[172:175], v[16:31]
	v_mfma_f32_32x32x16_bf16 v[0:15], v[192:195], v[176:179], v[0:15]
	ds_read_b128 v[172:175], v128 offset:16384
	ds_read_b128 v[176:179], v128 offset:18432
	v_add_u32_e32 v128, v237, v200
	ds_read_b128 v[180:183], v128
	ds_read_b128 v[184:187], v128 offset:2048
	ds_read_b128 v[188:191], v128 offset:4096
	ds_read_b128 v[192:195], v128 offset:6144
	s_waitcnt lgkmcnt(9)
	v_mfma_f32_32x32x16_bf16 v[112:127], v[138:141], v[130:133], v[112:127]
	v_mfma_f32_32x32x16_bf16 v[96:111], v[138:141], v[134:137], v[96:111]
	s_waitcnt lgkmcnt(8)
	v_mfma_f32_32x32x16_bf16 v[80:95], v[142:145], v[130:133], v[80:95]
	v_mfma_f32_32x32x16_bf16 v[64:79], v[142:145], v[134:137], v[64:79]
	s_waitcnt lgkmcnt(7)
	v_mfma_f32_32x32x16_bf16 v[48:63], v[146:149], v[130:133], v[48:63]
	v_mfma_f32_32x32x16_bf16 v[32:47], v[146:149], v[134:137], v[32:47]
	s_waitcnt lgkmcnt(6)
	v_mfma_f32_32x32x16_bf16 v[16:31], v[150:153], v[130:133], v[16:31]
	v_mfma_f32_32x32x16_bf16 v[0:15], v[150:153], v[134:137], v[0:15]
	v_add_u32_e32 v128, v236, v201
	ds_read_b128 v[130:133], v128 offset:16384
	ds_read_b128 v[134:137], v128 offset:18432
	v_add_u32_e32 v128, v237, v201
	ds_read_b128 v[138:141], v128
	ds_read_b128 v[142:145], v128 offset:2048
	ds_read_b128 v[146:149], v128 offset:4096
	ds_read_b128 v[150:153], v128 offset:6144
	s_waitcnt lgkmcnt(9)
	v_mfma_f32_32x32x16_bf16 v[112:127], v[180:183], v[172:175], v[112:127]
	v_mfma_f32_32x32x16_bf16 v[96:111], v[180:183], v[176:179], v[96:111]
	s_waitcnt lgkmcnt(8)
	v_mfma_f32_32x32x16_bf16 v[80:95], v[184:187], v[172:175], v[80:95]
	v_mfma_f32_32x32x16_bf16 v[64:79], v[184:187], v[176:179], v[64:79]
	s_waitcnt lgkmcnt(7)
	v_mfma_f32_32x32x16_bf16 v[48:63], v[188:191], v[172:175], v[48:63]
	v_mfma_f32_32x32x16_bf16 v[32:47], v[188:191], v[176:179], v[32:47]
	s_waitcnt vmcnt(0) lgkmcnt(0)
	s_barrier
	v_add_u32_e32 v128, v234, v200
	s_waitcnt lgkmcnt(6)
	v_mfma_f32_32x32x16_bf16 v[16:31], v[192:195], v[172:175], v[16:31]
	v_mfma_f32_32x32x16_bf16 v[0:15], v[192:195], v[176:179], v[0:15]
	ds_read_b128 v[172:175], v128 offset:16384
	ds_read_b128 v[176:179], v128 offset:18432
	v_add_u32_e32 v128, v235, v200
	ds_read_b128 v[180:183], v128
	ds_read_b128 v[184:187], v128 offset:2048
	ds_read_b128 v[188:191], v128 offset:4096
	ds_read_b128 v[192:195], v128 offset:6144
	s_waitcnt lgkmcnt(9)
	v_mfma_f32_32x32x16_bf16 v[112:127], v[138:141], v[130:133], v[112:127]
	v_mfma_f32_32x32x16_bf16 v[96:111], v[138:141], v[134:137], v[96:111]
	s_waitcnt lgkmcnt(8)
	v_mfma_f32_32x32x16_bf16 v[80:95], v[142:145], v[130:133], v[80:95]
	v_mfma_f32_32x32x16_bf16 v[64:79], v[142:145], v[134:137], v[64:79]
	s_waitcnt lgkmcnt(7)
	v_mfma_f32_32x32x16_bf16 v[48:63], v[146:149], v[130:133], v[48:63]
	v_mfma_f32_32x32x16_bf16 v[32:47], v[146:149], v[134:137], v[32:47]
	s_waitcnt lgkmcnt(6)
	v_mfma_f32_32x32x16_bf16 v[16:31], v[150:153], v[130:133], v[16:31]
	v_mfma_f32_32x32x16_bf16 v[0:15], v[150:153], v[134:137], v[0:15]
	v_add_u32_e32 v128, v234, v201
	ds_read_b128 v[130:133], v128 offset:16384
	ds_read_b128 v[136:139], v128 offset:18432
	v_add_u32_e32 v128, v235, v201
	ds_read_b128 v[140:143], v128
	ds_read_b128 v[144:147], v128 offset:2048
	ds_read_b128 v[148:151], v128 offset:4096
	ds_read_b128 v[240:243], v128 offset:6144
	s_waitcnt lgkmcnt(9)
	v_mfma_f32_32x32x16_bf16 v[112:127], v[180:183], v[172:175], v[112:127]
	v_mfma_f32_32x32x16_bf16 v[96:111], v[180:183], v[176:179], v[96:111]
	s_waitcnt lgkmcnt(8)
	v_mfma_f32_32x32x16_bf16 v[80:95], v[184:187], v[172:175], v[80:95]
	v_mfma_f32_32x32x16_bf16 v[64:79], v[184:187], v[176:179], v[64:79]
	s_waitcnt lgkmcnt(7)
	v_mfma_f32_32x32x16_bf16 v[48:63], v[188:191], v[172:175], v[48:63]
	v_mfma_f32_32x32x16_bf16 v[32:47], v[188:191], v[176:179], v[32:47]
	s_waitcnt lgkmcnt(6)
	v_mfma_f32_32x32x16_bf16 v[16:31], v[192:195], v[172:175], v[16:31]
	v_or_b32_e32 v134, s1, v196
	s_movk_i32 s1, 0x1840
	v_cmp_gt_i32_e32 vcc, s1, v134
	v_mfma_f32_32x32x16_bf16 v[0:15], v[192:195], v[176:179], v[0:15]
	s_waitcnt lgkmcnt(3)
	v_mfma_f32_32x32x16_bf16 v[112:127], v[140:143], v[130:133], v[112:127]
	v_mfma_f32_32x32x16_bf16 v[96:111], v[140:143], v[136:139], v[96:111]
	s_waitcnt lgkmcnt(2)
	v_mfma_f32_32x32x16_bf16 v[80:95], v[144:147], v[130:133], v[80:95]
	v_mfma_f32_32x32x16_bf16 v[64:79], v[144:147], v[136:139], v[64:79]
	s_waitcnt lgkmcnt(1)
	v_mfma_f32_32x32x16_bf16 v[48:63], v[148:151], v[130:133], v[48:63]
	v_mfma_f32_32x32x16_bf16 v[32:47], v[148:151], v[136:139], v[32:47]
	s_waitcnt lgkmcnt(0)
	v_mfma_f32_32x32x16_bf16 v[16:31], v[240:243], v[130:133], v[16:31]
	v_mfma_f32_32x32x16_bf16 v[0:15], v[240:243], v[136:139], v[0:15]
	s_and_saveexec_b64 s[20:21], vcc
	s_cbranch_execz .LBB0_1159
	v_add_u32_e32 v239, s0, v159
	s_movk_i32 s0, 0x7ff
	v_cmp_lt_i32_e32 vcc, s0, v134
	s_and_saveexec_b64 s[0:1], vcc
	s_xor_b64 s[22:23], exec, s[0:1]
	s_cbranch_execz .LBB0_1816
	s_cmpk_lt_u32 s24, 0x1800
	v_or_b32_e32 v130, v134, v197
	s_mov_b64 s[0:1], -1
	s_cbranch_scc0 .LBB0_1302
	v_add_u32_e32 v128, 0xfffff800, v130
	v_lshlrev_b64 v[132:133], 2, v[128:129]
	v_lshl_add_u64 v[134:135], s[16:17], 0, v[132:133]
	v_add_co_u32_e32 v136, vcc, 0x4000, v134
	v_lshl_add_u64 v[132:133], s[18:19], 0, v[132:133]
	s_nop 0
	v_addc_co_u32_e32 v137, vcc, 0, v135, vcc
	v_add_co_u32_e32 v138, vcc, 0x8000, v134
	v_mov_b32_e32 v131, v113
	s_nop 0
	v_addc_co_u32_e32 v139, vcc, 0, v135, vcc
	global_load_dword v188, v[134:135], off
	s_nop 0
	global_load_dword v134, v[136:137], off
	global_load_dword v186, v[138:139], off
	global_load_dword v190, v[132:133], off
	v_ashrrev_i32_e32 v132, 7, v239
	v_ashrrev_i32_e32 v133, 31, v132
	v_lshlrev_b64 v[136:137], 15, v[132:133]
	v_lshl_add_u64 v[178:179], s[2:3], 0, v[136:137]
	v_lshl_add_u64 v[136:137], v[128:129], 1, v[178:179]
	s_and_saveexec_b64 s[0:1], s[6:7]
	s_xor_b64 s[0:1], exec, s[0:1]
	s_cbranch_execz .LBB0_1167
	v_add_co_u32_e32 v138, vcc, 0x4000, v136
	v_cvt_pk_bf16_f32 v131, v30, s0
	s_nop 0
	v_addc_co_u32_e32 v139, vcc, 0, v137, vcc
	global_store_short v[138:139], v131, off
	v_mov_b32_e32 v131, v31

.LBB0_2226:
	s_and_b32 s9, s8, 0x18000
	v_add_u32_e32 v222, s9, v180
	s_add_i32 s9, s8, 0xfffe8000
	s_and_b32 s9, s9, 0x18000
	v_or_b32_e32 v223, s9, v179
	v_add_u32_e32 v233, s9, v176
	s_waitcnt lgkmcnt(0)
	v_mfma_f32_32x32x16_bf16 v[112:127], v[150:153], v[142:145], v[112:127]
	v_mfma_f32_32x32x16_bf16 v[96:111], v[150:153], v[130:133], v[96:111]
	s_waitcnt vmcnt(8)
	s_barrier
	v_add_u32_e32 v206, v223, v177
	v_add_u32_e32 v234, v233, v177
	ds_read_b128 v[202:205], v206 offset:16384
	ds_read_b128 v[206:209], v206 offset:18432
	ds_read_b128 v[210:213], v234
	v_mfma_f32_32x32x16_bf16 v[80:95], v[146:149], v[142:145], v[80:95]
	v_mfma_f32_32x32x16_bf16 v[64:79], v[146:149], v[130:133], v[64:79]
	ds_read_b128 v[214:217], v234 offset:2048
	v_readfirstlane_b32 s9, v222
	s_mov_b32 m0, s9
	s_nop 0
	global_load_lds_dwordx4 v[170:171], off
	v_mfma_f32_32x32x16_bf16 v[48:63], v[138:141], v[142:145], v[48:63]
	v_mfma_f32_32x32x16_bf16 v[32:47], v[138:141], v[130:133], v[32:47]
	ds_read_b128 v[224:227], v234 offset:4096
	s_add_i32 s10, s9, 0x2000
	v_lshl_add_u64 v[150:151], v[170:171], 0, s[12:13]
	s_mov_b32 m0, s10
	s_nop 0
	global_load_lds_dwordx4 v[150:151], off
	v_mfma_f32_32x32x16_bf16 v[16:31], v[134:137], v[142:145], v[16:31]
	v_mfma_f32_32x32x16_bf16 v[0:15], v[134:137], v[130:133], v[0:15]
	ds_read_b128 v[234:237], v234 offset:6144
	s_waitcnt lgkmcnt(3)
	v_mfma_f32_32x32x16_bf16 v[112:127], v[210:213], v[202:205], v[112:127]
	v_add_u32_e32 v130, v223, v178
	v_add_u32_e32 v134, v233, v178
	ds_read_b128 v[142:145], v130 offset:16384
	v_mfma_f32_32x32x16_bf16 v[96:111], v[210:213], v[206:209], v[96:111]
	ds_read_b128 v[130:133], v130 offset:18432
	s_add_i32 s10, s9, 0x6000
	s_addk_i32 s9, 0x4000
	s_mov_b32 m0, s9
	s_nop 0
	global_load_lds_dwordx4 v[172:173], off
	s_waitcnt lgkmcnt(4)
	v_mfma_f32_32x32x16_bf16 v[80:95], v[214:217], v[202:205], v[80:95]
	ds_read_b128 v[150:153], v134
	v_mfma_f32_32x32x16_bf16 v[64:79], v[214:217], v[206:209], v[64:79]
	ds_read_b128 v[146:149], v134 offset:2048
	s_waitcnt lgkmcnt(5)
	v_mfma_f32_32x32x16_bf16 v[48:63], v[224:227], v[202:205], v[48:63]
	ds_read_b128 v[138:141], v134 offset:4096
	v_mfma_f32_32x32x16_bf16 v[32:47], v[224:227], v[206:209], v[32:47]
	ds_read_b128 v[134:137], v134 offset:6144
	v_lshl_add_u64 v[222:223], v[172:173], 0, s[12:13]
	s_mov_b32 m0, s10
	s_nop 0
	global_load_lds_dwordx4 v[222:223], off
	s_waitcnt lgkmcnt(6)
	v_mfma_f32_32x32x16_bf16 v[16:31], v[234:237], v[202:205], v[16:31]
	s_add_i32 s8, s8, 0x8000
	v_lshl_add_u64 v[170:171], v[170:171], 0, 64
	v_lshl_add_u64 v[172:173], v[172:173], 0, 64
	s_cmp_eq_u32 s8, 0x200000
	v_mfma_f32_32x32x16_bf16 v[0:15], v[234:237], v[206:209], v[0:15]
	s_cbranch_scc0 .LBB0_2226
	s_waitcnt vmcnt(8) lgkmcnt(0)
	s_barrier
	v_add_u32_e32 v202, v179, v177
	v_add_u32_e32 v222, v176, v177
	ds_read_b128 v[170:173], v202 offset:49152
	ds_read_b128 v[202:205], v202 offset:51200
	ds_read_b128 v[206:209], v222 offset:32768
	ds_read_b128 v[210:213], v222 offset:34816
	ds_read_b128 v[214:217], v222 offset:36864
	ds_read_b128 v[224:227], v222 offset:38912
	s_waitcnt lgkmcnt(9)
	v_mfma_f32_32x32x16_bf16 v[112:127], v[150:153], v[142:145], v[112:127]
	v_mfma_f32_32x32x16_bf16 v[96:111], v[150:153], v[130:133], v[96:111]
	s_waitcnt lgkmcnt(8)
	v_mfma_f32_32x32x16_bf16 v[80:95], v[146:149], v[142:145], v[80:95]
	v_mfma_f32_32x32x16_bf16 v[64:79], v[146:149], v[130:133], v[64:79]
	s_waitcnt lgkmcnt(7)
	v_mfma_f32_32x32x16_bf16 v[48:63], v[138:141], v[142:145], v[48:63]
	v_mfma_f32_32x32x16_bf16 v[32:47], v[138:141], v[130:133], v[32:47]
	s_waitcnt lgkmcnt(6)
	v_mfma_f32_32x32x16_bf16 v[16:31], v[134:137], v[142:145], v[16:31]
	v_mfma_f32_32x32x16_bf16 v[0:15], v[134:137], v[130:133], v[0:15]
	v_add_u32_e32 v134, v179, v178
	v_add_u32_e32 v150, v176, v178
	ds_read_b128 v[130:133], v134 offset:49152
	ds_read_b128 v[134:137], v134 offset:51200
	ds_read_b128 v[138:141], v150 offset:32768
	ds_read_b128 v[142:145], v150 offset:34816
	ds_read_b128 v[146:149], v150 offset:36864
	ds_read_b128 v[150:153], v150 offset:38912
	s_waitcnt lgkmcnt(9)
	v_mfma_f32_32x32x16_bf16 v[112:127], v[206:209], v[170:173], v[112:127]
	v_mfma_f32_32x32x16_bf16 v[96:111], v[206:209], v[202:205], v[96:111]
	s_waitcnt lgkmcnt(8)
	v_mfma_f32_32x32x16_bf16 v[80:95], v[210:213], v[170:173], v[80:95]
	v_mfma_f32_32x32x16_bf16 v[64:79], v[210:213], v[202:205], v[64:79]
	s_waitcnt lgkmcnt(7)
	v_mfma_f32_32x32x16_bf16 v[48:63], v[214:217], v[170:173], v[48:63]
	v_mfma_f32_32x32x16_bf16 v[32:47], v[214:217], v[202:205], v[32:47]
	s_waitcnt lgkmcnt(6)
	v_mfma_f32_32x32x16_bf16 v[0:15], v[224:227], v[202:205], v[0:15]
	s_waitcnt vmcnt(4) lgkmcnt(0)
	s_barrier
	v_add_u32_e32 v202, v199, v177
	v_add_u32_e32 v222, v200, v177
	v_mfma_f32_32x32x16_bf16 v[16:31], v[224:227], v[170:173], v[16:31]
	ds_read_b128 v[170:173], v202 offset:16384
	ds_read_b128 v[202:205], v202 offset:18432
	ds_read_b128 v[206:209], v222
	ds_read_b128 v[210:213], v222 offset:2048
	ds_read_b128 v[214:217], v222 offset:4096
	ds_read_b128 v[224:227], v222 offset:6144
	s_waitcnt lgkmcnt(9)
	v_mfma_f32_32x32x16_bf16 v[112:127], v[138:141], v[130:133], v[112:127]
	v_mfma_f32_32x32x16_bf16 v[96:111], v[138:141], v[134:137], v[96:111]
	s_waitcnt lgkmcnt(8)
	v_mfma_f32_32x32x16_bf16 v[80:95], v[142:145], v[130:133], v[80:95]
	v_mfma_f32_32x32x16_bf16 v[64:79], v[142:145], v[134:137], v[64:79]
	s_waitcnt lgkmcnt(7)
	v_mfma_f32_32x32x16_bf16 v[48:63], v[146:149], v[130:133], v[48:63]
	v_mfma_f32_32x32x16_bf16 v[32:47], v[146:149], v[134:137], v[32:47]
	s_waitcnt lgkmcnt(6)
	v_mfma_f32_32x32x16_bf16 v[16:31], v[150:153], v[130:133], v[16:31]
	v_mfma_f32_32x32x16_bf16 v[0:15], v[150:153], v[134:137], v[0:15]
	v_add_u32_e32 v134, v199, v178
	v_add_u32_e32 v150, v200, v178
	ds_read_b128 v[130:133], v134 offset:16384
	ds_read_b128 v[134:137], v134 offset:18432
	ds_read_b128 v[138:141], v150
	ds_read_b128 v[142:145], v150 offset:2048
	ds_read_b128 v[146:149], v150 offset:4096
	ds_read_b128 v[150:153], v150 offset:6144
	s_waitcnt lgkmcnt(9)
	v_mfma_f32_32x32x16_bf16 v[112:127], v[206:209], v[170:173], v[112:127]
	v_mfma_f32_32x32x16_bf16 v[96:111], v[206:209], v[202:205], v[96:111]
	s_waitcnt lgkmcnt(8)
	v_mfma_f32_32x32x16_bf16 v[80:95], v[210:213], v[170:173], v[80:95]
	v_mfma_f32_32x32x16_bf16 v[64:79], v[210:213], v[202:205], v[64:79]
	s_waitcnt lgkmcnt(7)
	v_mfma_f32_32x32x16_bf16 v[48:63], v[214:217], v[170:173], v[48:63]
	v_mfma_f32_32x32x16_bf16 v[32:47], v[214:217], v[202:205], v[32:47]
	s_waitcnt lgkmcnt(6)
	v_mfma_f32_32x32x16_bf16 v[0:15], v[224:227], v[202:205], v[0:15]
	s_waitcnt vmcnt(0) lgkmcnt(0)
	s_barrier
	v_add_u32_e32 v202, v197, v177
	v_add_u32_e32 v222, v198, v177
	v_mfma_f32_32x32x16_bf16 v[16:31], v[224:227], v[170:173], v[16:31]
	ds_read_b128 v[170:173], v202 offset:16384
	ds_read_b128 v[202:205], v202 offset:18432
	ds_read_b128 v[206:209], v222
	ds_read_b128 v[210:213], v222 offset:2048
	ds_read_b128 v[214:217], v222 offset:4096
	ds_read_b128 v[224:227], v222 offset:6144
	s_waitcnt lgkmcnt(9)
	v_mfma_f32_32x32x16_bf16 v[112:127], v[138:141], v[130:133], v[112:127]
	v_mfma_f32_32x32x16_bf16 v[96:111], v[138:141], v[134:137], v[96:111]
	s_waitcnt lgkmcnt(8)
	v_mfma_f32_32x32x16_bf16 v[80:95], v[142:145], v[130:133], v[80:95]
	v_mfma_f32_32x32x16_bf16 v[64:79], v[142:145], v[134:137], v[64:79]
	s_waitcnt lgkmcnt(7)
	v_mfma_f32_32x32x16_bf16 v[48:63], v[146:149], v[130:133], v[48:63]
	v_mfma_f32_32x32x16_bf16 v[32:47], v[146:149], v[134:137], v[32:47]
	s_waitcnt lgkmcnt(6)
	v_mfma_f32_32x32x16_bf16 v[16:31], v[150:153], v[130:133], v[16:31]
	v_mfma_f32_32x32x16_bf16 v[0:15], v[150:153], v[134:137], v[0:15]
	v_add_u32_e32 v134, v197, v178
	v_add_u32_e32 v150, v198, v178
	ds_read_b128 v[130:133], v134 offset:16384
	ds_read_b128 v[134:137], v134 offset:18432
	ds_read_b128 v[138:141], v150
	ds_read_b128 v[142:145], v150 offset:2048
	ds_read_b128 v[146:149], v150 offset:4096
	ds_read_b128 v[150:153], v150 offset:6144
	s_waitcnt lgkmcnt(9)
	v_mfma_f32_32x32x16_bf16 v[112:127], v[206:209], v[170:173], v[112:127]
	v_mfma_f32_32x32x16_bf16 v[96:111], v[206:209], v[202:205], v[96:111]
	s_waitcnt lgkmcnt(8)
	v_mfma_f32_32x32x16_bf16 v[80:95], v[210:213], v[170:173], v[80:95]
	v_mfma_f32_32x32x16_bf16 v[64:79], v[210:213], v[202:205], v[64:79]
	s_waitcnt lgkmcnt(7)
	v_mfma_f32_32x32x16_bf16 v[48:63], v[214:217], v[170:173], v[48:63]
	v_mfma_f32_32x32x16_bf16 v[32:47], v[214:217], v[202:205], v[32:47]
	s_waitcnt lgkmcnt(6)
	v_mfma_f32_32x32x16_bf16 v[16:31], v[224:227], v[170:173], v[16:31]
	v_mfma_f32_32x32x16_bf16 v[0:15], v[224:227], v[202:205], v[0:15]
	s_waitcnt lgkmcnt(3)
	v_mfma_f32_32x32x16_bf16 v[112:127], v[138:141], v[130:133], v[112:127]
	s_waitcnt lgkmcnt(2)
	v_mfma_f32_32x32x16_bf16 v[80:95], v[142:145], v[130:133], v[80:95]
	s_waitcnt lgkmcnt(1)
	v_mfma_f32_32x32x16_bf16 v[48:63], v[146:149], v[130:133], v[48:63]
	s_waitcnt lgkmcnt(0)
	v_mfma_f32_32x32x16_bf16 v[16:31], v[150:153], v[130:133], v[16:31]
	v_add_u32_e32 v132, s6, v174
	v_or_b32_e32 v130, s7, v128
	v_ashrrev_i32_e32 v131, 31, v130
	v_lshl_add_u64 v[130:131], v[130:131], 1, v[158:159]
	v_readlane_b32 s6, v252, 7
	s_add_i32 s4, s4, s6
	s_add_i32 s2, s2, s6
	v_mfma_f32_32x32x16_bf16 v[96:111], v[138:141], v[134:137], v[96:111]
	v_or_b32_e32 v138, v132, v181
	v_ashrrev_i32_e32 v139, 31, v138
	v_readlane_b32 s6, v252, 8
	s_add_i32 s5, s5, s6
	s_cmp_gt_i32 s4, 31
	v_mfma_f32_32x32x16_bf16 v[64:79], v[142:145], v[134:137], v[64:79]
	v_mfma_f32_32x32x16_bf16 v[32:47], v[146:149], v[134:137], v[32:47]
	v_mfma_f32_32x32x16_bf16 v[0:15], v[150:153], v[134:137], v[0:15]
	v_and_b32_e32 v134, 0xff, v138
	v_lshl_add_u32 v134, v134, 2, v250
	ds_read_b96 v[134:136], v134
	v_lshlrev_b64 v[138:139], 11, v[138:139]
	v_lshl_add_u64 v[138:139], v[130:131], 0, v[138:139]
	s_waitcnt lgkmcnt(0)
	v_mul_f32_e32 v112, v112, v134
	v_mul_f32_e32 v96, v96, v134
	v_cvt_pk_bf16_f32 v112, v112, s0
	v_cvt_pk_bf16_f32 v96, v96, s0
	global_store_short v[138:139], v112, off
	global_store_short v[138:139], v96, off offset:64
	v_or_b32_e32 v138, v132, v182
	v_ashrrev_i32_e32 v139, 31, v138
	v_lshlrev_b64 v[138:139], 11, v[138:139]
	v_mul_f32_e32 v96, v113, v135
	v_lshl_add_u64 v[138:139], v[130:131], 0, v[138:139]
	v_cvt_pk_bf16_f32 v96, v96, s0
	global_store_short v[138:139], v96, off
	v_mul_f32_e32 v96, v97, v135
	v_cvt_pk_bf16_f32 v96, v96, s0
	global_store_short v[138:139], v96, off offset:64
	v_or_b32_e32 v96, v132, v183
	v_ashrrev_i32_e32 v97, 31, v96
	v_lshlrev_b64 v[96:97], 11, v[96:97]
	v_mul_f32_e32 v112, v114, v136
	v_mul_f32_e32 v98, v98, v136
	v_lshl_add_u64 v[96:97], v[130:131], 0, v[96:97]
	v_cvt_pk_bf16_f32 v112, v112, s0
	v_cvt_pk_bf16_f32 v98, v98, s0
	global_store_short v[96:97], v112, off
	global_store_short v[96:97], v98, off offset:64
	v_or_b32_e32 v96, v132, v184
	v_ashrrev_i32_e32 v97, 31, v96
	v_and_b32_e32 v112, 0xff, v96
	v_lshl_add_u32 v112, v112, 2, v250
	ds_read_b32 v98, v112
	v_lshlrev_b64 v[96:97], 11, v[96:97]
	v_lshl_add_u64 v[96:97], v[130:131], 0, v[96:97]
	s_waitcnt lgkmcnt(0)
	v_mul_f32_e32 v112, v115, v98
	v_cvt_pk_bf16_f32 v112, v112, s0
	global_store_short v[96:97], v112, off
	v_mul_f32_e32 v98, v99, v98
	v_or_b32_e32 v112, v132, v185
	v_cvt_pk_bf16_f32 v98, v98, s0
	v_ashrrev_i32_e32 v113, 31, v112
	global_store_short v[96:97], v98, off offset:64
	v_and_b32_e32 v96, 0xff, v112
	v_lshl_add_u32 v96, v96, 2, v250
	ds_read_b96 v[96:98], v96
	v_lshlrev_b64 v[112:113], 11, v[112:113]
	v_lshl_add_u64 v[112:113], v[130:131], 0, v[112:113]
	s_waitcnt lgkmcnt(0)
	v_mul_f32_e32 v99, v116, v96
	v_mul_f32_e32 v96, v100, v96
	v_cvt_pk_bf16_f32 v99, v99, s0
	v_cvt_pk_bf16_f32 v96, v96, s0
	global_store_short v[112:113], v99, off
	global_store_short v[112:113], v96, off offset:64
	v_or_b32_e32 v112, v132, v186
	v_ashrrev_i32_e32 v113, 31, v112
	v_lshlrev_b64 v[112:113], 11, v[112:113]
	v_mul_f32_e32 v96, v117, v97
	v_lshl_add_u64 v[112:113], v[130:131], 0, v[112:113]
	v_cvt_pk_bf16_f32 v96, v96, s0
	global_store_short v[112:113], v96, off
	v_mul_f32_e32 v96, v101, v97
	v_cvt_pk_bf16_f32 v96, v96, s0
	global_store_short v[112:113], v96, off offset:64
	v_or_b32_e32 v96, v132, v187
	v_ashrrev_i32_e32 v97, 31, v96
	v_lshlrev_b64 v[96:97], 11, v[96:97]
	v_mul_f32_e32 v99, v118, v98
	v_mul_f32_e32 v98, v102, v98
	v_lshl_add_u64 v[96:97], v[130:131], 0, v[96:97]
	v_cvt_pk_bf16_f32 v99, v99, s0
	v_cvt_pk_bf16_f32 v98, v98, s0
	global_store_short v[96:97], v99, off
	global_store_short v[96:97], v98, off offset:64
	v_or_b32_e32 v96, v132, v188
	v_ashrrev_i32_e32 v97, 31, v96
	v_and_b32_e32 v98, 0xff, v96
	v_lshl_add_u32 v98, v98, 2, v250
	ds_read_b32 v98, v98
	v_lshlrev_b64 v[96:97], 11, v[96:97]
	v_or_b32_e32 v100, v132, v189
	v_lshl_add_u64 v[96:97], v[130:131], 0, v[96:97]
	v_ashrrev_i32_e32 v101, 31, v100
	s_waitcnt lgkmcnt(0)
	v_mul_f32_e32 v99, v119, v98
	v_mul_f32_e32 v98, v103, v98
	v_cvt_pk_bf16_f32 v99, v99, s0
	v_cvt_pk_bf16_f32 v98, v98, s0
	global_store_short v[96:97], v99, off
	global_store_short v[96:97], v98, off offset:64
	v_and_b32_e32 v96, 0xff, v100
	v_lshl_add_u32 v96, v96, 2, v250
	ds_read_b96 v[96:98], v96
	v_lshlrev_b64 v[100:101], 11, v[100:101]
	v_lshl_add_u64 v[100:101], v[130:131], 0, v[100:101]
	s_waitcnt lgkmcnt(0)
	v_mul_f32_e32 v99, v120, v96
	v_mul_f32_e32 v96, v104, v96
	v_cvt_pk_bf16_f32 v99, v99, s0
	v_cvt_pk_bf16_f32 v96, v96, s0
	global_store_short v[100:101], v99, off
	global_store_short v[100:101], v96, off offset:64
	v_or_b32_e32 v100, v132, v190
	v_ashrrev_i32_e32 v101, 31, v100
	v_lshlrev_b64 v[100:101], 11, v[100:101]
	v_mul_f32_e32 v96, v121, v97
	v_lshl_add_u64 v[100:101], v[130:131], 0, v[100:101]
	v_cvt_pk_bf16_f32 v96, v96, s0
	global_store_short v[100:101], v96, off
	v_mul_f32_e32 v96, v105, v97
	v_cvt_pk_bf16_f32 v96, v96, s0
	global_store_short v[100:101], v96, off offset:64
	v_or_b32_e32 v96, v132, v191
	v_ashrrev_i32_e32 v97, 31, v96
	v_lshlrev_b64 v[96:97], 11, v[96:97]
	v_mul_f32_e32 v99, v122, v98
	v_mul_f32_e32 v98, v106, v98
	v_lshl_add_u64 v[96:97], v[130:131], 0, v[96:97]
	v_cvt_pk_bf16_f32 v99, v99, s0
	v_cvt_pk_bf16_f32 v98, v98, s0
	global_store_short v[96:97], v99, off
	global_store_short v[96:97], v98, off offset:64
	v_or_b32_e32 v96, v132, v192
	v_ashrrev_i32_e32 v97, 31, v96
	v_and_b32_e32 v98, 0xff, v96
	v_lshl_add_u32 v98, v98, 2, v250
	ds_read_b32 v98, v98
	v_lshlrev_b64 v[96:97], 11, v[96:97]
	v_or_b32_e32 v100, v132, v193
	v_lshl_add_u64 v[96:97], v[130:131], 0, v[96:97]
	v_ashrrev_i32_e32 v101, 31, v100
	s_waitcnt lgkmcnt(0)
	v_mul_f32_e32 v99, v123, v98
	v_mul_f32_e32 v98, v107, v98
	v_cvt_pk_bf16_f32 v99, v99, s0
	v_cvt_pk_bf16_f32 v98, v98, s0
	global_store_short v[96:97], v99, off
	global_store_short v[96:97], v98, off offset:64
	v_and_b32_e32 v96, 0xff, v100
	v_lshl_add_u32 v96, v96, 2, v250
	ds_read_b96 v[96:98], v96
	v_lshlrev_b64 v[100:101], 11, v[100:101]
	v_lshl_add_u64 v[100:101], v[130:131], 0, v[100:101]
	s_waitcnt lgkmcnt(0)
	v_mul_f32_e32 v99, v124, v96
	v_mul_f32_e32 v96, v108, v96
	v_cvt_pk_bf16_f32 v99, v99, s0
	v_cvt_pk_bf16_f32 v96, v96, s0
	global_store_short v[100:101], v99, off
	global_store_short v[100:101], v96, off offset:64
	v_or_b32_e32 v100, v132, v194
	v_ashrrev_i32_e32 v101, 31, v100
	v_lshlrev_b64 v[100:101], 11, v[100:101]
	v_mul_f32_e32 v96, v125, v97
	v_lshl_add_u64 v[100:101], v[130:131], 0, v[100:101]
	v_cvt_pk_bf16_f32 v96, v96, s0
	global_store_short v[100:101], v96, off
	v_mul_f32_e32 v96, v109, v97
	v_cvt_pk_bf16_f32 v96, v96, s0
	global_store_short v[100:101], v96, off offset:64
	v_or_b32_e32 v96, v132, v195
	v_ashrrev_i32_e32 v97, 31, v96
	v_lshlrev_b64 v[96:97], 11, v[96:97]
	v_mul_f32_e32 v99, v126, v98
	v_mul_f32_e32 v98, v110, v98
	v_lshl_add_u64 v[96:97], v[130:131], 0, v[96:97]
	v_cvt_pk_bf16_f32 v99, v99, s0
	v_cvt_pk_bf16_f32 v98, v98, s0
	global_store_short v[96:97], v99, off
	global_store_short v[96:97], v98, off offset:64
	v_or_b32_e32 v96, v132, v196
	v_ashrrev_i32_e32 v97, 31, v96
	v_and_b32_e32 v98, 0xff, v96
	v_lshl_add_u32 v98, v98, 2, v250
	ds_read_b32 v98, v98
	v_lshlrev_b64 v[96:97], 11, v[96:97]
	v_lshl_add_u64 v[96:97], v[130:131], 0, v[96:97]
	s_waitcnt lgkmcnt(0)
	v_mul_f32_e32 v99, v127, v98
	v_mul_f32_e32 v98, v111, v98
	v_cvt_pk_bf16_f32 v99, v99, s0
	v_cvt_pk_bf16_f32 v98, v98, s0
	global_store_short v[96:97], v99, off
	global_store_short v[96:97], v98, off offset:64
	v_or_b32_e32 v96, 32, v132
	v_or_b32_e32 v102, v96, v181
	v_ashrrev_i32_e32 v103, 31, v102
	v_and_b32_e32 v98, 0xff, v102
	v_lshl_add_u32 v98, v98, 2, v250
	ds_read_b96 v[98:100], v98
	v_lshlrev_b64 v[102:103], 11, v[102:103]
	v_lshl_add_u64 v[102:103], v[130:131], 0, v[102:103]
	s_waitcnt lgkmcnt(0)
	v_mul_f32_e32 v80, v80, v98
	v_mul_f32_e32 v64, v64, v98
	v_cvt_pk_bf16_f32 v80, v80, s0
	v_cvt_pk_bf16_f32 v64, v64, s0
	global_store_short v[102:103], v80, off
	global_store_short v[102:103], v64, off offset:64
	v_or_b32_e32 v102, v96, v182
	v_ashrrev_i32_e32 v103, 31, v102
	v_lshlrev_b64 v[102:103], 11, v[102:103]
	v_mul_f32_e32 v64, v81, v99
	v_lshl_add_u64 v[102:103], v[130:131], 0, v[102:103]
	v_cvt_pk_bf16_f32 v64, v64, s0
	global_store_short v[102:103], v64, off
	v_mul_f32_e32 v64, v65, v99
	v_cvt_pk_bf16_f32 v64, v64, s0
	global_store_short v[102:103], v64, off offset:64
	v_or_b32_e32 v64, v96, v183
	v_ashrrev_i32_e32 v65, 31, v64
	v_lshlrev_b64 v[64:65], 11, v[64:65]
	v_mul_f32_e32 v80, v82, v100
	v_mul_f32_e32 v66, v66, v100
	v_lshl_add_u64 v[64:65], v[130:131], 0, v[64:65]
	v_cvt_pk_bf16_f32 v80, v80, s0
	v_cvt_pk_bf16_f32 v66, v66, s0
	global_store_short v[64:65], v80, off
	global_store_short v[64:65], v66, off offset:64
	v_or_b32_e32 v64, v96, v184
	v_ashrrev_i32_e32 v65, 31, v64
	v_and_b32_e32 v80, 0xff, v64
	v_lshl_add_u32 v80, v80, 2, v250
	ds_read_b32 v66, v80
	v_lshlrev_b64 v[64:65], 11, v[64:65]
	v_lshl_add_u64 v[64:65], v[130:131], 0, v[64:65]
	s_waitcnt lgkmcnt(0)
	v_mul_f32_e32 v80, v83, v66
	v_cvt_pk_bf16_f32 v80, v80, s0
	global_store_short v[64:65], v80, off
	v_mul_f32_e32 v66, v67, v66
	v_or_b32_e32 v80, v96, v185
	v_cvt_pk_bf16_f32 v66, v66, s0
	v_ashrrev_i32_e32 v81, 31, v80
	global_store_short v[64:65], v66, off offset:64
	v_and_b32_e32 v64, 0xff, v80
	v_lshl_add_u32 v64, v64, 2, v250
	ds_read_b96 v[64:66], v64
	v_lshlrev_b64 v[80:81], 11, v[80:81]
	v_lshl_add_u64 v[80:81], v[130:131], 0, v[80:81]
	s_waitcnt lgkmcnt(0)
	v_mul_f32_e32 v67, v84, v64
	v_mul_f32_e32 v64, v68, v64
	v_cvt_pk_bf16_f32 v67, v67, s0
	v_cvt_pk_bf16_f32 v64, v64, s0
	global_store_short v[80:81], v67, off
	global_store_short v[80:81], v64, off offset:64
	v_or_b32_e32 v80, v96, v186
	v_ashrrev_i32_e32 v81, 31, v80
	v_lshlrev_b64 v[80:81], 11, v[80:81]
	v_mul_f32_e32 v64, v85, v65
	v_lshl_add_u64 v[80:81], v[130:131], 0, v[80:81]
	v_cvt_pk_bf16_f32 v64, v64, s0
	global_store_short v[80:81], v64, off
	v_mul_f32_e32 v64, v69, v65
	v_cvt_pk_bf16_f32 v64, v64, s0
	global_store_short v[80:81], v64, off offset:64
	v_or_b32_e32 v64, v96, v187
	v_ashrrev_i32_e32 v65, 31, v64
	v_lshlrev_b64 v[64:65], 11, v[64:65]
	v_mul_f32_e32 v67, v86, v66
	v_mul_f32_e32 v66, v70, v66
	v_lshl_add_u64 v[64:65], v[130:131], 0, v[64:65]
	v_cvt_pk_bf16_f32 v67, v67, s0
	v_cvt_pk_bf16_f32 v66, v66, s0
	global_store_short v[64:65], v67, off
	global_store_short v[64:65], v66, off offset:64
	v_or_b32_e32 v64, v96, v188
	v_ashrrev_i32_e32 v65, 31, v64
	v_and_b32_e32 v66, 0xff, v64
	v_lshl_add_u32 v66, v66, 2, v250
	ds_read_b32 v66, v66
	v_lshlrev_b64 v[64:65], 11, v[64:65]
	v_or_b32_e32 v68, v96, v189
	v_lshl_add_u64 v[64:65], v[130:131], 0, v[64:65]
	v_ashrrev_i32_e32 v69, 31, v68
	s_waitcnt lgkmcnt(0)
	v_mul_f32_e32 v67, v87, v66
	v_mul_f32_e32 v66, v71, v66
	v_cvt_pk_bf16_f32 v67, v67, s0
	v_cvt_pk_bf16_f32 v66, v66, s0
	global_store_short v[64:65], v67, off
	global_store_short v[64:65], v66, off offset:64
	v_and_b32_e32 v64, 0xff, v68
	v_lshl_add_u32 v64, v64, 2, v250
	ds_read_b96 v[64:66], v64
	v_lshlrev_b64 v[68:69], 11, v[68:69]
	v_lshl_add_u64 v[68:69], v[130:131], 0, v[68:69]
	s_waitcnt lgkmcnt(0)
	v_mul_f32_e32 v67, v88, v64
	v_mul_f32_e32 v64, v72, v64
	v_cvt_pk_bf16_f32 v67, v67, s0
	v_cvt_pk_bf16_f32 v64, v64, s0
	global_store_short v[68:69], v67, off
	global_store_short v[68:69], v64, off offset:64
	v_or_b32_e32 v68, v96, v190
	v_ashrrev_i32_e32 v69, 31, v68
	v_lshlrev_b64 v[68:69], 11, v[68:69]
	v_mul_f32_e32 v64, v89, v65
	v_lshl_add_u64 v[68:69], v[130:131], 0, v[68:69]
	v_cvt_pk_bf16_f32 v64, v64, s0
	global_store_short v[68:69], v64, off
	v_mul_f32_e32 v64, v73, v65
	v_cvt_pk_bf16_f32 v64, v64, s0
	global_store_short v[68:69], v64, off offset:64
	v_or_b32_e32 v64, v96, v191
	v_ashrrev_i32_e32 v65, 31, v64
	v_lshlrev_b64 v[64:65], 11, v[64:65]
	v_mul_f32_e32 v67, v90, v66
	v_mul_f32_e32 v66, v74, v66
	v_lshl_add_u64 v[64:65], v[130:131], 0, v[64:65]
	v_cvt_pk_bf16_f32 v67, v67, s0
	v_cvt_pk_bf16_f32 v66, v66, s0
	global_store_short v[64:65], v67, off
	global_store_short v[64:65], v66, off offset:64
	v_or_b32_e32 v64, v96, v192
	v_ashrrev_i32_e32 v65, 31, v64
	v_and_b32_e32 v66, 0xff, v64
	v_lshl_add_u32 v66, v66, 2, v250
	ds_read_b32 v66, v66
	v_lshlrev_b64 v[64:65], 11, v[64:65]
	v_or_b32_e32 v68, v96, v193
	v_lshl_add_u64 v[64:65], v[130:131], 0, v[64:65]
	v_ashrrev_i32_e32 v69, 31, v68
	s_waitcnt lgkmcnt(0)
	v_mul_f32_e32 v67, v91, v66
	v_mul_f32_e32 v66, v75, v66
	v_cvt_pk_bf16_f32 v67, v67, s0
	v_cvt_pk_bf16_f32 v66, v66, s0
	global_store_short v[64:65], v67, off
	global_store_short v[64:65], v66, off offset:64
	v_and_b32_e32 v64, 0xff, v68
	v_lshl_add_u32 v64, v64, 2, v250
	ds_read_b96 v[64:66], v64
	v_lshlrev_b64 v[68:69], 11, v[68:69]
	v_lshl_add_u64 v[68:69], v[130:131], 0, v[68:69]
	s_waitcnt lgkmcnt(0)
	v_mul_f32_e32 v67, v92, v64
	v_mul_f32_e32 v64, v76, v64
	v_cvt_pk_bf16_f32 v67, v67, s0
	v_cvt_pk_bf16_f32 v64, v64, s0
	global_store_short v[68:69], v67, off
	global_store_short v[68:69], v64, off offset:64
	v_or_b32_e32 v68, v96, v194
	v_ashrrev_i32_e32 v69, 31, v68
	v_lshlrev_b64 v[68:69], 11, v[68:69]
	v_mul_f32_e32 v64, v93, v65
	v_lshl_add_u64 v[68:69], v[130:131], 0, v[68:69]
	v_cvt_pk_bf16_f32 v64, v64, s0
	global_store_short v[68:69], v64, off
	v_mul_f32_e32 v64, v77, v65
	v_cvt_pk_bf16_f32 v64, v64, s0
	global_store_short v[68:69], v64, off offset:64
	v_or_b32_e32 v64, v96, v195
	v_ashrrev_i32_e32 v65, 31, v64
	v_lshlrev_b64 v[64:65], 11, v[64:65]
	v_mul_f32_e32 v67, v94, v66
	v_mul_f32_e32 v66, v78, v66
	v_lshl_add_u64 v[64:65], v[130:131], 0, v[64:65]
	v_cvt_pk_bf16_f32 v67, v67, s0
	v_cvt_pk_bf16_f32 v66, v66, s0
	global_store_short v[64:65], v67, off
	global_store_short v[64:65], v66, off offset:64
	v_or_b32_e32 v64, v96, v196
	v_ashrrev_i32_e32 v65, 31, v64
	v_and_b32_e32 v66, 0xff, v64
	v_lshl_add_u32 v66, v66, 2, v250
	ds_read_b32 v66, v66
	v_lshlrev_b64 v[64:65], 11, v[64:65]
	v_lshl_add_u64 v[64:65], v[130:131], 0, v[64:65]
	s_waitcnt lgkmcnt(0)
	v_mul_f32_e32 v67, v95, v66
	v_mul_f32_e32 v66, v79, v66
	v_cvt_pk_bf16_f32 v67, v67, s0
	v_cvt_pk_bf16_f32 v66, v66, s0
	global_store_short v[64:65], v67, off
	global_store_short v[64:65], v66, off offset:64
	v_or_b32_e32 v64, 64, v132
	v_or_b32_e32 v70, v64, v181
	v_ashrrev_i32_e32 v71, 31, v70
	v_and_b32_e32 v66, 0xff, v70
	v_lshl_add_u32 v66, v66, 2, v250
	ds_read_b96 v[66:68], v66
	v_lshlrev_b64 v[70:71], 11, v[70:71]
	v_lshl_add_u64 v[70:71], v[130:131], 0, v[70:71]
	s_waitcnt lgkmcnt(0)
	v_mul_f32_e32 v48, v48, v66
	v_mul_f32_e32 v32, v32, v66
	v_cvt_pk_bf16_f32 v48, v48, s0
	v_cvt_pk_bf16_f32 v32, v32, s0
	global_store_short v[70:71], v48, off
	global_store_short v[70:71], v32, off offset:64
	v_or_b32_e32 v70, v64, v182
	v_ashrrev_i32_e32 v71, 31, v70
	v_lshlrev_b64 v[70:71], 11, v[70:71]
	v_mul_f32_e32 v32, v49, v67
	v_lshl_add_u64 v[70:71], v[130:131], 0, v[70:71]
	v_cvt_pk_bf16_f32 v32, v32, s0
	global_store_short v[70:71], v32, off
	v_mul_f32_e32 v32, v33, v67
	v_cvt_pk_bf16_f32 v32, v32, s0
	global_store_short v[70:71], v32, off offset:64
	v_or_b32_e32 v32, v64, v183
	v_ashrrev_i32_e32 v33, 31, v32
	v_lshlrev_b64 v[32:33], 11, v[32:33]
	v_mul_f32_e32 v48, v50, v68
	v_mul_f32_e32 v34, v34, v68
	v_lshl_add_u64 v[32:33], v[130:131], 0, v[32:33]
	v_cvt_pk_bf16_f32 v48, v48, s0
	v_cvt_pk_bf16_f32 v34, v34, s0
	global_store_short v[32:33], v48, off
	global_store_short v[32:33], v34, off offset:64
	v_or_b32_e32 v32, v64, v184
	v_ashrrev_i32_e32 v33, 31, v32
	v_and_b32_e32 v48, 0xff, v32
	v_lshl_add_u32 v48, v48, 2, v250
	ds_read_b32 v34, v48
	v_lshlrev_b64 v[32:33], 11, v[32:33]
	v_lshl_add_u64 v[32:33], v[130:131], 0, v[32:33]
	s_waitcnt lgkmcnt(0)
	v_mul_f32_e32 v48, v51, v34
	v_cvt_pk_bf16_f32 v48, v48, s0
	global_store_short v[32:33], v48, off
	v_mul_f32_e32 v34, v35, v34
	v_or_b32_e32 v48, v64, v185
	v_cvt_pk_bf16_f32 v34, v34, s0
	v_ashrrev_i32_e32 v49, 31, v48
	global_store_short v[32:33], v34, off offset:64
	v_and_b32_e32 v32, 0xff, v48
	v_lshl_add_u32 v32, v32, 2, v250
	ds_read_b96 v[32:34], v32
	v_lshlrev_b64 v[48:49], 11, v[48:49]
	v_lshl_add_u64 v[48:49], v[130:131], 0, v[48:49]
	s_waitcnt lgkmcnt(0)
	v_mul_f32_e32 v35, v52, v32
	v_mul_f32_e32 v32, v36, v32
	v_cvt_pk_bf16_f32 v35, v35, s0
	v_cvt_pk_bf16_f32 v32, v32, s0
	global_store_short v[48:49], v35, off
	global_store_short v[48:49], v32, off offset:64
	v_or_b32_e32 v48, v64, v186
	v_ashrrev_i32_e32 v49, 31, v48
	v_lshlrev_b64 v[48:49], 11, v[48:49]
	v_mul_f32_e32 v32, v53, v33
	v_lshl_add_u64 v[48:49], v[130:131], 0, v[48:49]
	v_cvt_pk_bf16_f32 v32, v32, s0
	global_store_short v[48:49], v32, off
	v_mul_f32_e32 v32, v37, v33
	v_cvt_pk_bf16_f32 v32, v32, s0
	global_store_short v[48:49], v32, off offset:64
	v_or_b32_e32 v32, v64, v187
	v_ashrrev_i32_e32 v33, 31, v32
	v_lshlrev_b64 v[32:33], 11, v[32:33]
	v_mul_f32_e32 v35, v54, v34
	v_mul_f32_e32 v34, v38, v34
	v_lshl_add_u64 v[32:33], v[130:131], 0, v[32:33]
	v_cvt_pk_bf16_f32 v35, v35, s0
	v_cvt_pk_bf16_f32 v34, v34, s0
	global_store_short v[32:33], v35, off
	global_store_short v[32:33], v34, off offset:64
	v_or_b32_e32 v32, v64, v188
	v_ashrrev_i32_e32 v33, 31, v32
	v_and_b32_e32 v34, 0xff, v32
	v_lshl_add_u32 v34, v34, 2, v250
	ds_read_b32 v34, v34
	v_lshlrev_b64 v[32:33], 11, v[32:33]
	v_or_b32_e32 v36, v64, v189
	v_lshl_add_u64 v[32:33], v[130:131], 0, v[32:33]
	v_ashrrev_i32_e32 v37, 31, v36
	s_waitcnt lgkmcnt(0)
	v_mul_f32_e32 v35, v55, v34
	v_mul_f32_e32 v34, v39, v34
	v_cvt_pk_bf16_f32 v35, v35, s0
	v_cvt_pk_bf16_f32 v34, v34, s0
	global_store_short v[32:33], v35, off
	global_store_short v[32:33], v34, off offset:64
	v_and_b32_e32 v32, 0xff, v36
	v_lshl_add_u32 v32, v32, 2, v250
	ds_read_b96 v[32:34], v32
	v_lshlrev_b64 v[36:37], 11, v[36:37]
	v_lshl_add_u64 v[36:37], v[130:131], 0, v[36:37]
	s_waitcnt lgkmcnt(0)
	v_mul_f32_e32 v35, v56, v32
	v_mul_f32_e32 v32, v40, v32
	v_cvt_pk_bf16_f32 v35, v35, s0
	v_cvt_pk_bf16_f32 v32, v32, s0
	global_store_short v[36:37], v35, off
	global_store_short v[36:37], v32, off offset:64
	v_or_b32_e32 v36, v64, v190
	v_ashrrev_i32_e32 v37, 31, v36
	v_lshlrev_b64 v[36:37], 11, v[36:37]
	v_mul_f32_e32 v32, v57, v33
	v_lshl_add_u64 v[36:37], v[130:131], 0, v[36:37]
	v_cvt_pk_bf16_f32 v32, v32, s0
	global_store_short v[36:37], v32, off
	v_mul_f32_e32 v32, v41, v33
	v_cvt_pk_bf16_f32 v32, v32, s0
	global_store_short v[36:37], v32, off offset:64
	v_or_b32_e32 v32, v64, v191
	v_ashrrev_i32_e32 v33, 31, v32
	v_lshlrev_b64 v[32:33], 11, v[32:33]
	v_mul_f32_e32 v35, v58, v34
	v_mul_f32_e32 v34, v42, v34
	v_lshl_add_u64 v[32:33], v[130:131], 0, v[32:33]
	v_cvt_pk_bf16_f32 v35, v35, s0
	v_cvt_pk_bf16_f32 v34, v34, s0
	global_store_short v[32:33], v35, off
	global_store_short v[32:33], v34, off offset:64
	v_or_b32_e32 v32, v64, v192
	v_ashrrev_i32_e32 v33, 31, v32
	v_and_b32_e32 v34, 0xff, v32
	v_lshl_add_u32 v34, v34, 2, v250
	ds_read_b32 v34, v34
	v_lshlrev_b64 v[32:33], 11, v[32:33]
	v_or_b32_e32 v36, v64, v193
	v_lshl_add_u64 v[32:33], v[130:131], 0, v[32:33]
	v_ashrrev_i32_e32 v37, 31, v36
	s_waitcnt lgkmcnt(0)
	v_mul_f32_e32 v35, v59, v34
	v_mul_f32_e32 v34, v43, v34
	v_cvt_pk_bf16_f32 v35, v35, s0
	v_cvt_pk_bf16_f32 v34, v34, s0
	global_store_short v[32:33], v35, off
	global_store_short v[32:33], v34, off offset:64
	v_and_b32_e32 v32, 0xff, v36
	v_lshl_add_u32 v32, v32, 2, v250
	ds_read_b96 v[32:34], v32
	v_lshlrev_b64 v[36:37], 11, v[36:37]
	v_lshl_add_u64 v[36:37], v[130:131], 0, v[36:37]
	s_waitcnt lgkmcnt(0)
	v_mul_f32_e32 v35, v60, v32
	v_mul_f32_e32 v32, v44, v32
	v_cvt_pk_bf16_f32 v35, v35, s0
	v_cvt_pk_bf16_f32 v32, v32, s0
	global_store_short v[36:37], v35, off
	global_store_short v[36:37], v32, off offset:64
	v_or_b32_e32 v36, v64, v194
	v_ashrrev_i32_e32 v37, 31, v36
	v_lshlrev_b64 v[36:37], 11, v[36:37]
	v_mul_f32_e32 v32, v61, v33
	v_lshl_add_u64 v[36:37], v[130:131], 0, v[36:37]
	v_cvt_pk_bf16_f32 v32, v32, s0
	global_store_short v[36:37], v32, off
	v_mul_f32_e32 v32, v45, v33
	v_cvt_pk_bf16_f32 v32, v32, s0
	global_store_short v[36:37], v32, off offset:64
	v_or_b32_e32 v32, v64, v195
	v_ashrrev_i32_e32 v33, 31, v32
	v_lshlrev_b64 v[32:33], 11, v[32:33]
	v_mul_f32_e32 v35, v62, v34
	v_mul_f32_e32 v34, v46, v34
	v_lshl_add_u64 v[32:33], v[130:131], 0, v[32:33]
	v_cvt_pk_bf16_f32 v35, v35, s0
	v_cvt_pk_bf16_f32 v34, v34, s0
	global_store_short v[32:33], v35, off
	global_store_short v[32:33], v34, off offset:64
	v_or_b32_e32 v32, v64, v196
	v_ashrrev_i32_e32 v33, 31, v32
	v_and_b32_e32 v34, 0xff, v32
	v_lshl_add_u32 v34, v34, 2, v250
	ds_read_b32 v34, v34
	v_lshlrev_b64 v[32:33], 11, v[32:33]
	v_lshl_add_u64 v[32:33], v[130:131], 0, v[32:33]
	s_waitcnt lgkmcnt(0)
	v_mul_f32_e32 v35, v63, v34
	v_mul_f32_e32 v34, v47, v34
	v_cvt_pk_bf16_f32 v35, v35, s0
	v_cvt_pk_bf16_f32 v34, v34, s0
	global_store_short v[32:33], v35, off
	global_store_short v[32:33], v34, off offset:64
	v_or_b32_e32 v32, 0x60, v132
	v_or_b32_e32 v38, v32, v181
	v_ashrrev_i32_e32 v39, 31, v38
	v_and_b32_e32 v34, 0xff, v38
	v_lshl_add_u32 v34, v34, 2, v250
	ds_read_b96 v[34:36], v34
	v_lshlrev_b64 v[38:39], 11, v[38:39]
	v_lshl_add_u64 v[38:39], v[130:131], 0, v[38:39]
	s_waitcnt lgkmcnt(0)
	v_mul_f32_e32 v16, v16, v34
	v_mul_f32_e32 v0, v0, v34
	v_cvt_pk_bf16_f32 v16, v16, s0
	v_cvt_pk_bf16_f32 v0, v0, s0
	global_store_short v[38:39], v16, off
	global_store_short v[38:39], v0, off offset:64
	v_or_b32_e32 v38, v32, v182
	v_ashrrev_i32_e32 v39, 31, v38
	v_lshlrev_b64 v[38:39], 11, v[38:39]
	v_mul_f32_e32 v0, v17, v35
	v_lshl_add_u64 v[38:39], v[130:131], 0, v[38:39]
	v_cvt_pk_bf16_f32 v0, v0, s0
	global_store_short v[38:39], v0, off
	v_mul_f32_e32 v0, v1, v35
	v_cvt_pk_bf16_f32 v0, v0, s0
	global_store_short v[38:39], v0, off offset:64
	v_or_b32_e32 v0, v32, v183
	v_ashrrev_i32_e32 v1, 31, v0
	v_lshlrev_b64 v[0:1], 11, v[0:1]
	v_mul_f32_e32 v16, v18, v36
	v_mul_f32_e32 v2, v2, v36
	v_lshl_add_u64 v[0:1], v[130:131], 0, v[0:1]
	v_cvt_pk_bf16_f32 v16, v16, s0
	v_cvt_pk_bf16_f32 v2, v2, s0
	global_store_short v[0:1], v16, off
	global_store_short v[0:1], v2, off offset:64
	v_or_b32_e32 v0, v32, v184
	v_ashrrev_i32_e32 v1, 31, v0
	v_and_b32_e32 v16, 0xff, v0
	v_lshl_add_u32 v16, v16, 2, v250
	ds_read_b32 v2, v16
	v_lshlrev_b64 v[0:1], 11, v[0:1]
	v_lshl_add_u64 v[0:1], v[130:131], 0, v[0:1]
	s_waitcnt lgkmcnt(0)
	v_mul_f32_e32 v16, v19, v2
	v_cvt_pk_bf16_f32 v16, v16, s0
	global_store_short v[0:1], v16, off
	v_mul_f32_e32 v2, v3, v2
	v_or_b32_e32 v16, v32, v185
	v_cvt_pk_bf16_f32 v2, v2, s0
	v_ashrrev_i32_e32 v17, 31, v16
	global_store_short v[0:1], v2, off offset:64
	v_and_b32_e32 v0, 0xff, v16
	v_lshl_add_u32 v0, v0, 2, v250
	ds_read_b96 v[0:2], v0
	v_lshlrev_b64 v[16:17], 11, v[16:17]
	v_lshl_add_u64 v[16:17], v[130:131], 0, v[16:17]
	s_waitcnt lgkmcnt(0)
	v_mul_f32_e32 v3, v20, v0
	v_mul_f32_e32 v0, v4, v0
	v_cvt_pk_bf16_f32 v3, v3, s0
	v_cvt_pk_bf16_f32 v0, v0, s0
	global_store_short v[16:17], v3, off
	global_store_short v[16:17], v0, off offset:64
	v_or_b32_e32 v16, v32, v186
	v_ashrrev_i32_e32 v17, 31, v16
	v_lshlrev_b64 v[16:17], 11, v[16:17]
	v_mul_f32_e32 v0, v21, v1
	v_lshl_add_u64 v[16:17], v[130:131], 0, v[16:17]
	v_cvt_pk_bf16_f32 v0, v0, s0
	global_store_short v[16:17], v0, off
	v_mul_f32_e32 v0, v5, v1
	v_cvt_pk_bf16_f32 v0, v0, s0
	global_store_short v[16:17], v0, off offset:64
	v_or_b32_e32 v0, v32, v187
	v_ashrrev_i32_e32 v1, 31, v0
	v_lshlrev_b64 v[0:1], 11, v[0:1]
	v_mul_f32_e32 v3, v22, v2
	v_mul_f32_e32 v2, v6, v2
	v_lshl_add_u64 v[0:1], v[130:131], 0, v[0:1]
	v_cvt_pk_bf16_f32 v3, v3, s0
	v_cvt_pk_bf16_f32 v2, v2, s0
	global_store_short v[0:1], v3, off
	global_store_short v[0:1], v2, off offset:64
	v_or_b32_e32 v0, v32, v188
	v_ashrrev_i32_e32 v1, 31, v0
	v_and_b32_e32 v2, 0xff, v0
	v_lshl_add_u32 v2, v2, 2, v250
	ds_read_b32 v2, v2
	v_lshlrev_b64 v[0:1], 11, v[0:1]
	v_or_b32_e32 v4, v32, v189
	v_lshl_add_u64 v[0:1], v[130:131], 0, v[0:1]
	v_ashrrev_i32_e32 v5, 31, v4
	s_waitcnt lgkmcnt(0)
	v_mul_f32_e32 v3, v23, v2
	v_mul_f32_e32 v2, v7, v2
	v_cvt_pk_bf16_f32 v3, v3, s0
	v_cvt_pk_bf16_f32 v2, v2, s0
	global_store_short v[0:1], v3, off
	global_store_short v[0:1], v2, off offset:64
	v_and_b32_e32 v0, 0xff, v4
	v_lshl_add_u32 v0, v0, 2, v250
	ds_read_b96 v[0:2], v0
	v_lshlrev_b64 v[4:5], 11, v[4:5]
	v_lshl_add_u64 v[4:5], v[130:131], 0, v[4:5]
	s_waitcnt lgkmcnt(0)
	v_mul_f32_e32 v3, v24, v0
	v_mul_f32_e32 v0, v8, v0
	v_cvt_pk_bf16_f32 v3, v3, s0
	v_cvt_pk_bf16_f32 v0, v0, s0
	global_store_short v[4:5], v3, off
	global_store_short v[4:5], v0, off offset:64
	v_or_b32_e32 v4, v32, v190
	v_ashrrev_i32_e32 v5, 31, v4
	v_lshlrev_b64 v[4:5], 11, v[4:5]
	v_mul_f32_e32 v0, v25, v1
	v_lshl_add_u64 v[4:5], v[130:131], 0, v[4:5]
	v_cvt_pk_bf16_f32 v0, v0, s0
	global_store_short v[4:5], v0, off
	v_mul_f32_e32 v0, v9, v1
	v_cvt_pk_bf16_f32 v0, v0, s0
	global_store_short v[4:5], v0, off offset:64
	v_or_b32_e32 v0, v32, v191
	v_ashrrev_i32_e32 v1, 31, v0
	v_lshlrev_b64 v[0:1], 11, v[0:1]
	v_mul_f32_e32 v3, v26, v2
	v_mul_f32_e32 v2, v10, v2
	v_lshl_add_u64 v[0:1], v[130:131], 0, v[0:1]
	v_cvt_pk_bf16_f32 v3, v3, s0
	v_cvt_pk_bf16_f32 v2, v2, s0
	global_store_short v[0:1], v3, off
	global_store_short v[0:1], v2, off offset:64
	v_or_b32_e32 v0, v32, v192
	v_ashrrev_i32_e32 v1, 31, v0
	v_and_b32_e32 v2, 0xff, v0
	v_lshl_add_u32 v2, v2, 2, v250
	ds_read_b32 v2, v2
	v_lshlrev_b64 v[0:1], 11, v[0:1]
	v_or_b32_e32 v4, v32, v193
	v_lshl_add_u64 v[0:1], v[130:131], 0, v[0:1]
	v_ashrrev_i32_e32 v5, 31, v4
	s_waitcnt lgkmcnt(0)
	v_mul_f32_e32 v3, v27, v2
	v_mul_f32_e32 v2, v11, v2
	v_cvt_pk_bf16_f32 v3, v3, s0
	v_cvt_pk_bf16_f32 v2, v2, s0
	global_store_short v[0:1], v3, off
	global_store_short v[0:1], v2, off offset:64
	v_and_b32_e32 v0, 0xff, v4
	v_lshl_add_u32 v0, v0, 2, v250
	ds_read_b96 v[0:2], v0
	v_lshlrev_b64 v[4:5], 11, v[4:5]
	v_lshl_add_u64 v[4:5], v[130:131], 0, v[4:5]
	s_waitcnt lgkmcnt(0)
	v_mul_f32_e32 v3, v28, v0
	v_mul_f32_e32 v0, v12, v0
	v_cvt_pk_bf16_f32 v3, v3, s0
	v_cvt_pk_bf16_f32 v0, v0, s0
	global_store_short v[4:5], v3, off
	global_store_short v[4:5], v0, off offset:64
	v_or_b32_e32 v4, v32, v194
	v_ashrrev_i32_e32 v5, 31, v4
	v_lshlrev_b64 v[4:5], 11, v[4:5]
	v_mul_f32_e32 v0, v29, v1
	v_lshl_add_u64 v[4:5], v[130:131], 0, v[4:5]
	v_cvt_pk_bf16_f32 v0, v0, s0
	global_store_short v[4:5], v0, off
	v_mul_f32_e32 v0, v13, v1
	v_cvt_pk_bf16_f32 v0, v0, s0
	global_store_short v[4:5], v0, off offset:64
	v_or_b32_e32 v0, v32, v195
	v_ashrrev_i32_e32 v1, 31, v0
	v_lshlrev_b64 v[0:1], 11, v[0:1]
	v_mul_f32_e32 v3, v30, v2
	v_mul_f32_e32 v2, v14, v2
	v_lshl_add_u64 v[0:1], v[130:131], 0, v[0:1]
	v_cvt_pk_bf16_f32 v3, v3, s0
	v_cvt_pk_bf16_f32 v2, v2, s0
	global_store_short v[0:1], v3, off
	global_store_short v[0:1], v2, off offset:64
	v_or_b32_e32 v0, v32, v196
	v_ashrrev_i32_e32 v1, 31, v0
	v_and_b32_e32 v2, 0xff, v0
	v_lshl_add_u32 v2, v2, 2, v250
	ds_read_b32 v2, v2
	v_lshlrev_b64 v[0:1], 11, v[0:1]
	v_lshl_add_u64 v[0:1], v[130:131], 0, v[0:1]
	s_waitcnt lgkmcnt(0)
	v_mul_f32_e32 v3, v31, v2
	v_mul_f32_e32 v2, v15, v2
	v_cvt_pk_bf16_f32 v3, v3, s0
	v_cvt_pk_bf16_f32 v2, v2, s0
	global_store_short v[0:1], v3, off
	global_store_short v[0:1], v2, off offset:64
	s_cbranch_scc0 .LBB0_2225

.LBB0_2340:
	s_and_b32 s19, s18, 0x18000
	v_add_u32_e32 v187, s19, v180
	s_add_i32 s19, s18, 0xfffe8000
	s_and_b32 s19, s19, 0x18000
	v_or_b32_e32 v212, s19, v179
	v_add_u32_e32 v213, s19, v176
	s_waitcnt lgkmcnt(0)
	v_mfma_f32_32x32x16_bf16 v[112:127], v[150:153], v[142:145], v[112:127]
	v_mfma_f32_32x32x16_bf16 v[96:111], v[150:153], v[130:133], v[96:111]
	s_waitcnt vmcnt(8)
	s_barrier
	v_add_u32_e32 v192, v212, v177
	v_add_u32_e32 v208, v213, v177
	ds_read_b128 v[188:191], v192 offset:16384
	ds_read_b128 v[192:195], v192 offset:18432
	ds_read_b128 v[196:199], v208
	v_mfma_f32_32x32x16_bf16 v[80:95], v[146:149], v[142:145], v[80:95]
	v_mfma_f32_32x32x16_bf16 v[64:79], v[146:149], v[130:133], v[64:79]
	ds_read_b128 v[200:203], v208 offset:2048
	v_readfirstlane_b32 s19, v187
	s_mov_b32 m0, s19
	s_nop 0
	global_load_lds_dwordx4 v[170:171], off
	v_mfma_f32_32x32x16_bf16 v[48:63], v[138:141], v[142:145], v[48:63]
	v_mfma_f32_32x32x16_bf16 v[32:47], v[138:141], v[130:133], v[32:47]
	ds_read_b128 v[204:207], v208 offset:4096
	s_add_i32 s20, s19, 0x2000
	v_lshl_add_u64 v[150:151], v[170:171], 0, s[34:35]
	s_mov_b32 m0, s20
	s_nop 0
	global_load_lds_dwordx4 v[150:151], off
	v_mfma_f32_32x32x16_bf16 v[16:31], v[134:137], v[142:145], v[16:31]
	v_mfma_f32_32x32x16_bf16 v[0:15], v[134:137], v[130:133], v[0:15]
	ds_read_b128 v[208:211], v208 offset:6144
	s_waitcnt lgkmcnt(3)
	v_mfma_f32_32x32x16_bf16 v[112:127], v[196:199], v[188:191], v[112:127]
	v_add_u32_e32 v130, v212, v178
	v_add_u32_e32 v134, v213, v178
	ds_read_b128 v[142:145], v130 offset:16384
	v_mfma_f32_32x32x16_bf16 v[96:111], v[196:199], v[192:195], v[96:111]
	ds_read_b128 v[130:133], v130 offset:18432
	s_add_i32 s20, s19, 0x6000
	s_addk_i32 s19, 0x4000
	s_mov_b32 m0, s19
	s_nop 0
	global_load_lds_dwordx4 v[172:173], off
	s_waitcnt lgkmcnt(4)
	v_mfma_f32_32x32x16_bf16 v[80:95], v[200:203], v[188:191], v[80:95]
	ds_read_b128 v[150:153], v134
	v_mfma_f32_32x32x16_bf16 v[64:79], v[200:203], v[192:195], v[64:79]
	ds_read_b128 v[146:149], v134 offset:2048
	s_waitcnt lgkmcnt(5)
	v_mfma_f32_32x32x16_bf16 v[48:63], v[204:207], v[188:191], v[48:63]
	ds_read_b128 v[138:141], v134 offset:4096
	v_mfma_f32_32x32x16_bf16 v[32:47], v[204:207], v[192:195], v[32:47]
	ds_read_b128 v[134:137], v134 offset:6144
	v_lshl_add_u64 v[212:213], v[172:173], 0, s[34:35]
	s_mov_b32 m0, s20
	s_nop 0
	global_load_lds_dwordx4 v[212:213], off
	s_waitcnt lgkmcnt(6)
	v_mfma_f32_32x32x16_bf16 v[16:31], v[208:211], v[188:191], v[16:31]
	s_add_i32 s18, s18, 0x8000
	v_lshl_add_u64 v[170:171], v[170:171], 0, 64
	v_lshl_add_u64 v[172:173], v[172:173], 0, 64
	s_cmp_eq_u32 s18, 0x100000
	v_mfma_f32_32x32x16_bf16 v[0:15], v[208:211], v[192:195], v[0:15]
	s_cbranch_scc0 .LBB0_2340
	s_waitcnt vmcnt(8) lgkmcnt(0)
	s_barrier
	v_add_u32_e32 v187, v179, v177
	ds_read_b128 v[170:173], v187 offset:49152
	ds_read_b128 v[188:191], v187 offset:51200
	v_add_u32_e32 v187, v176, v177
	ds_read_b128 v[192:195], v187 offset:32768
	ds_read_b128 v[196:199], v187 offset:34816
	ds_read_b128 v[200:203], v187 offset:36864
	ds_read_b128 v[204:207], v187 offset:38912
	s_waitcnt lgkmcnt(9)
	v_mfma_f32_32x32x16_bf16 v[112:127], v[150:153], v[142:145], v[112:127]
	v_mfma_f32_32x32x16_bf16 v[96:111], v[150:153], v[130:133], v[96:111]
	s_waitcnt lgkmcnt(8)
	v_mfma_f32_32x32x16_bf16 v[80:95], v[146:149], v[142:145], v[80:95]
	v_mfma_f32_32x32x16_bf16 v[64:79], v[146:149], v[130:133], v[64:79]
	s_waitcnt lgkmcnt(7)
	v_mfma_f32_32x32x16_bf16 v[48:63], v[138:141], v[142:145], v[48:63]
	v_mfma_f32_32x32x16_bf16 v[32:47], v[138:141], v[130:133], v[32:47]
	s_waitcnt lgkmcnt(6)
	v_mfma_f32_32x32x16_bf16 v[16:31], v[134:137], v[142:145], v[16:31]
	v_mfma_f32_32x32x16_bf16 v[0:15], v[134:137], v[130:133], v[0:15]
	v_add_u32_e32 v134, v179, v178
	v_add_u32_e32 v150, v176, v178
	ds_read_b128 v[130:133], v134 offset:49152
	ds_read_b128 v[134:137], v134 offset:51200
	ds_read_b128 v[138:141], v150 offset:32768
	ds_read_b128 v[142:145], v150 offset:34816
	ds_read_b128 v[146:149], v150 offset:36864
	ds_read_b128 v[150:153], v150 offset:38912
	s_waitcnt lgkmcnt(9)
	v_mfma_f32_32x32x16_bf16 v[112:127], v[192:195], v[170:173], v[112:127]
	v_mfma_f32_32x32x16_bf16 v[96:111], v[192:195], v[188:191], v[96:111]
	s_waitcnt lgkmcnt(8)
	v_mfma_f32_32x32x16_bf16 v[80:95], v[196:199], v[170:173], v[80:95]
	v_mfma_f32_32x32x16_bf16 v[64:79], v[196:199], v[188:191], v[64:79]
	s_waitcnt lgkmcnt(7)
	v_mfma_f32_32x32x16_bf16 v[48:63], v[200:203], v[170:173], v[48:63]
	v_mfma_f32_32x32x16_bf16 v[32:47], v[200:203], v[188:191], v[32:47]
	s_waitcnt vmcnt(4) lgkmcnt(0)
	s_barrier
	v_add_u32_e32 v187, v184, v177
	s_waitcnt lgkmcnt(6)
	v_mfma_f32_32x32x16_bf16 v[16:31], v[204:207], v[170:173], v[16:31]
	v_mfma_f32_32x32x16_bf16 v[0:15], v[204:207], v[188:191], v[0:15]
	ds_read_b128 v[170:173], v187 offset:16384
	ds_read_b128 v[188:191], v187 offset:18432
	v_add_u32_e32 v187, v185, v177
	ds_read_b128 v[192:195], v187
	ds_read_b128 v[196:199], v187 offset:2048
	ds_read_b128 v[200:203], v187 offset:4096
	ds_read_b128 v[204:207], v187 offset:6144
	s_waitcnt lgkmcnt(9)
	v_mfma_f32_32x32x16_bf16 v[112:127], v[138:141], v[130:133], v[112:127]
	v_mfma_f32_32x32x16_bf16 v[96:111], v[138:141], v[134:137], v[96:111]
	s_waitcnt lgkmcnt(8)
	v_mfma_f32_32x32x16_bf16 v[80:95], v[142:145], v[130:133], v[80:95]
	v_mfma_f32_32x32x16_bf16 v[64:79], v[142:145], v[134:137], v[64:79]
	s_waitcnt lgkmcnt(7)
	v_mfma_f32_32x32x16_bf16 v[48:63], v[146:149], v[130:133], v[48:63]
	v_mfma_f32_32x32x16_bf16 v[32:47], v[146:149], v[134:137], v[32:47]
	s_waitcnt lgkmcnt(6)
	v_mfma_f32_32x32x16_bf16 v[16:31], v[150:153], v[130:133], v[16:31]
	v_mfma_f32_32x32x16_bf16 v[0:15], v[150:153], v[134:137], v[0:15]
	v_add_u32_e32 v134, v184, v178
	v_add_u32_e32 v150, v185, v178
	ds_read_b128 v[130:133], v134 offset:16384
	ds_read_b128 v[134:137], v134 offset:18432
	ds_read_b128 v[138:141], v150
	ds_read_b128 v[142:145], v150 offset:2048
	ds_read_b128 v[146:149], v150 offset:4096
	ds_read_b128 v[150:153], v150 offset:6144
	s_waitcnt lgkmcnt(9)
	v_mfma_f32_32x32x16_bf16 v[112:127], v[192:195], v[170:173], v[112:127]
	v_mfma_f32_32x32x16_bf16 v[96:111], v[192:195], v[188:191], v[96:111]
	s_waitcnt lgkmcnt(8)
	v_mfma_f32_32x32x16_bf16 v[80:95], v[196:199], v[170:173], v[80:95]
	v_mfma_f32_32x32x16_bf16 v[64:79], v[196:199], v[188:191], v[64:79]
	s_waitcnt lgkmcnt(7)
	v_mfma_f32_32x32x16_bf16 v[48:63], v[200:203], v[170:173], v[48:63]
	v_mfma_f32_32x32x16_bf16 v[32:47], v[200:203], v[188:191], v[32:47]
	s_waitcnt vmcnt(0) lgkmcnt(0)
	s_barrier
	v_add_u32_e32 v187, v182, v177
	s_waitcnt lgkmcnt(6)
	v_mfma_f32_32x32x16_bf16 v[16:31], v[204:207], v[170:173], v[16:31]
	v_mfma_f32_32x32x16_bf16 v[0:15], v[204:207], v[188:191], v[0:15]
	ds_read_b128 v[170:173], v187 offset:16384
	ds_read_b128 v[188:191], v187 offset:18432
	v_add_u32_e32 v187, v183, v177
	ds_read_b128 v[192:195], v187
	ds_read_b128 v[196:199], v187 offset:2048
	ds_read_b128 v[200:203], v187 offset:4096
	ds_read_b128 v[204:207], v187 offset:6144
	s_waitcnt lgkmcnt(9)
	v_mfma_f32_32x32x16_bf16 v[112:127], v[138:141], v[130:133], v[112:127]
	v_mfma_f32_32x32x16_bf16 v[96:111], v[138:141], v[134:137], v[96:111]
	s_waitcnt lgkmcnt(8)
	v_mfma_f32_32x32x16_bf16 v[80:95], v[142:145], v[130:133], v[80:95]
	v_mfma_f32_32x32x16_bf16 v[64:79], v[142:145], v[134:137], v[64:79]
	s_waitcnt lgkmcnt(7)
	v_mfma_f32_32x32x16_bf16 v[48:63], v[146:149], v[130:133], v[48:63]
	v_mfma_f32_32x32x16_bf16 v[32:47], v[146:149], v[134:137], v[32:47]
	s_waitcnt lgkmcnt(6)
	v_mfma_f32_32x32x16_bf16 v[16:31], v[150:153], v[130:133], v[16:31]
	v_mfma_f32_32x32x16_bf16 v[0:15], v[150:153], v[134:137], v[0:15]
	v_add_u32_e32 v134, v182, v178
	v_add_u32_e32 v150, v183, v178
	ds_read_b128 v[130:133], v134 offset:16384
	ds_read_b128 v[134:137], v134 offset:18432
	ds_read_b128 v[138:141], v150
	ds_read_b128 v[142:145], v150 offset:2048
	ds_read_b128 v[146:149], v150 offset:4096
	ds_read_b128 v[150:153], v150 offset:6144
	s_waitcnt lgkmcnt(9)
	v_mfma_f32_32x32x16_bf16 v[112:127], v[192:195], v[170:173], v[112:127]
	v_mfma_f32_32x32x16_bf16 v[96:111], v[192:195], v[188:191], v[96:111]
	s_waitcnt lgkmcnt(8)
	v_mfma_f32_32x32x16_bf16 v[80:95], v[196:199], v[170:173], v[80:95]
	v_mfma_f32_32x32x16_bf16 v[64:79], v[196:199], v[188:191], v[64:79]
	s_waitcnt lgkmcnt(7)
	v_mfma_f32_32x32x16_bf16 v[48:63], v[200:203], v[170:173], v[48:63]
	v_mfma_f32_32x32x16_bf16 v[32:47], v[200:203], v[188:191], v[32:47]
	s_waitcnt lgkmcnt(6)
	v_mfma_f32_32x32x16_bf16 v[16:31], v[204:207], v[170:173], v[16:31]
	v_mfma_f32_32x32x16_bf16 v[0:15], v[204:207], v[188:191], v[0:15]
	s_waitcnt lgkmcnt(3)
	v_mfma_f32_32x32x16_bf16 v[112:127], v[138:141], v[130:133], v[112:127]
	s_waitcnt lgkmcnt(2)
	v_mfma_f32_32x32x16_bf16 v[80:95], v[142:145], v[130:133], v[80:95]
	s_waitcnt lgkmcnt(1)
	v_mfma_f32_32x32x16_bf16 v[48:63], v[146:149], v[130:133], v[48:63]
	s_waitcnt lgkmcnt(0)
	v_mfma_f32_32x32x16_bf16 v[16:31], v[150:153], v[130:133], v[16:31]
	v_or_b32_e32 v132, s12, v174
	v_ashrrev_i32_e32 v130, 1, v132
	v_or_b32_e32 v130, v130, v154
	v_ashrrev_i32_e32 v131, 31, v130
	s_movk_i32 s12, 0x5000
	v_mfma_f32_32x32x16_bf16 v[96:111], v[138:141], v[134:137], v[96:111]
	v_mfma_f32_32x32x16_bf16 v[64:79], v[142:145], v[134:137], v[64:79]
	v_add_u32_e32 v142, s13, v155
	s_mov_b32 s13, 0xb000
	v_ashrrev_i32_e32 v133, 7, v142
	v_mfma_f32_32x32x16_bf16 v[32:47], v[146:149], v[134:137], v[32:47]
	v_mfma_f32_32x32x16_bf16 v[0:15], v[150:153], v[134:137], v[0:15]
	v_lshl_add_u64 v[134:135], v[130:131], 2, s[10:11]
	v_add_co_u32_e32 v138, vcc, s12, v134
	s_mov_b32 s12, 0x8000
	s_nop 0
	v_addc_co_u32_e32 v139, vcc, 0, v135, vcc
	global_load_dword v137, v[138:139], off offset:2048
	v_add_co_u32_e32 v138, vcc, s13, v134
	global_load_dword v136, v[134:135], off
	s_nop 0
	v_addc_co_u32_e32 v139, vcc, 0, v135, vcc
	v_add_co_u32_e32 v140, vcc, s47, v134
	global_load_dword v139, v[138:139], off
	s_nop 0
	v_addc_co_u32_e32 v141, vcc, 0, v135, vcc
	global_load_dword v138, v[140:141], off offset:3072
	v_add_co_u32_e32 v140, vcc, s12, v134
	s_mov_b32 s12, 0xd000
	s_nop 0
	v_addc_co_u32_e32 v141, vcc, 0, v135, vcc
	v_add_co_u32_e32 v134, vcc, s12, v134
	global_load_dword v140, v[140:141], off offset:1024
	s_nop 0
	v_addc_co_u32_e32 v135, vcc, 0, v135, vcc
	global_load_dword v141, v[134:135], off offset:3072
	v_readlane_b32 s100, v252, 7
	s_add_i32 s100, s14, s100
	s_cmpk_lt_i32 s100, 0xb0
	s_cbranch_scc0 .Lpf_none_up
	s_and_b32 vcc_lo, s100, 7
	s_or_b32 vcc_lo, vcc_lo, s16
	s_lshl_b32 vcc_lo, vcc_lo, 8
	v_add_u32_e32 v238, vcc_lo, v175
	v_ashrrev_i32_e32 v239, 31, v238
	v_lshlrev_b64 v[238:239], 11, v[238:239]
	v_lshl_add_u64 v[238:239], v[156:157], 0, v[238:239]
	s_lshl_b32 vcc_lo, s100, 5
	s_and_b32 vcc_lo, vcc_lo, 0xffffff00
	v_add_u32_e32 v240, vcc_lo, v175
	v_ashrrev_i32_e32 v241, 31, v240
	v_lshlrev_b64 v[240:241], 11, v[240:241]
	v_lshl_add_u64 v[240:241], v[158:159], 0, v[240:241]
	v_readfirstlane_b32 s100, v180
	s_mov_b32 m0, s100
	s_nop 0
	global_load_lds_dwordx4 v[238:239], off
	v_lshl_add_u64 v[242:243], v[238:239], 0, s[34:35]
	s_add_i32 m0, s100, 0x2000
	s_nop 0
	global_load_lds_dwordx4 v[242:243], off
	s_add_i32 m0, s100, 0x4000
	s_nop 0
	global_load_lds_dwordx4 v[240:241], off
	v_lshl_add_u64 v[242:243], v[240:241], 0, s[34:35]
	s_add_i32 m0, s100, 0x6000
	s_nop 0
	global_load_lds_dwordx4 v[242:243], off
	v_lshl_add_u64 v[242:243], v[238:239], 0, 64
	s_add_i32 m0, s100, 0x8000
	s_nop 0
	global_load_lds_dwordx4 v[242:243], off
	s_mov_b64 vcc, 0x40040
	v_lshl_add_u64 v[242:243], v[238:239], 0, vcc
	s_add_i32 m0, s100, 0xa000
	s_nop 0
	global_load_lds_dwordx4 v[242:243], off
	v_lshl_add_u64 v[242:243], v[240:241], 0, 64
	s_add_i32 m0, s100, 0xc000
	s_nop 0
	global_load_lds_dwordx4 v[242:243], off
	s_mov_b64 vcc, 0x40040
	v_lshl_add_u64 v[242:243], v[240:241], 0, vcc
	s_add_i32 m0, s100, 0xe000
	s_nop 0
	global_load_lds_dwordx4 v[242:243], off
	s_mov_b64 vcc, 0x80
	v_lshl_add_u64 v[242:243], v[238:239], 0, vcc
	s_add_i32 m0, s100, 0x10000
	s_nop 0
	global_load_lds_dwordx4 v[242:243], off
	s_mov_b64 vcc, 0x40080
	v_lshl_add_u64 v[242:243], v[238:239], 0, vcc
	s_add_i32 m0, s100, 0x12000
	s_nop 0
	global_load_lds_dwordx4 v[242:243], off
	s_mov_b64 vcc, 0x80
	v_lshl_add_u64 v[242:243], v[240:241], 0, vcc
	s_add_i32 m0, s100, 0x14000
	s_nop 0
	global_load_lds_dwordx4 v[242:243], off
	s_mov_b64 vcc, 0x40080
	v_lshl_add_u64 v[242:243], v[240:241], 0, vcc
	s_add_i32 m0, s100, 0x16000
	s_nop 0
	global_load_lds_dwordx4 v[242:243], off
	s_mov_b32 s101, 1
	s_branch .Lpf_done_up

.LBB0_2551:
	s_and_b32 s7, s5, 0x18000
	v_add_u32_e32 v222, s7, v180
	s_add_i32 s7, s5, 0xfffe8000
	s_and_b32 s7, s7, 0x18000
	v_or_b32_e32 v223, s7, v179
	v_add_u32_e32 v233, s7, v176
	s_waitcnt lgkmcnt(0)
	v_mfma_f32_32x32x16_bf16 v[112:127], v[150:153], v[142:145], v[112:127]
	v_mfma_f32_32x32x16_bf16 v[96:111], v[150:153], v[130:133], v[96:111]
	s_waitcnt vmcnt(8)
	s_barrier
	v_add_u32_e32 v206, v223, v177
	v_add_u32_e32 v234, v233, v177
	ds_read_b128 v[202:205], v206 offset:16384
	ds_read_b128 v[206:209], v206 offset:18432
	ds_read_b128 v[210:213], v234
	v_mfma_f32_32x32x16_bf16 v[80:95], v[146:149], v[142:145], v[80:95]
	v_mfma_f32_32x32x16_bf16 v[64:79], v[146:149], v[130:133], v[64:79]
	ds_read_b128 v[214:217], v234 offset:2048
	v_readfirstlane_b32 s7, v222
	s_mov_b32 m0, s7
	s_nop 0
	global_load_lds_dwordx4 v[170:171], off
	v_mfma_f32_32x32x16_bf16 v[48:63], v[138:141], v[142:145], v[48:63]
	v_mfma_f32_32x32x16_bf16 v[32:47], v[138:141], v[130:133], v[32:47]
	ds_read_b128 v[224:227], v234 offset:4096
	s_add_i32 s8, s7, 0x2000
	v_lshl_add_u64 v[150:151], v[170:171], 0, s[10:11]
	s_mov_b32 m0, s8
	s_nop 0
	global_load_lds_dwordx4 v[150:151], off
	v_mfma_f32_32x32x16_bf16 v[16:31], v[134:137], v[142:145], v[16:31]
	v_mfma_f32_32x32x16_bf16 v[0:15], v[134:137], v[130:133], v[0:15]
	ds_read_b128 v[234:237], v234 offset:6144
	s_waitcnt lgkmcnt(3)
	v_mfma_f32_32x32x16_bf16 v[112:127], v[210:213], v[202:205], v[112:127]
	v_add_u32_e32 v130, v223, v178
	v_add_u32_e32 v134, v233, v178
	ds_read_b128 v[142:145], v130 offset:16384
	v_mfma_f32_32x32x16_bf16 v[96:111], v[210:213], v[206:209], v[96:111]
	ds_read_b128 v[130:133], v130 offset:18432
	s_add_i32 s8, s7, 0x6000
	s_addk_i32 s7, 0x4000
	s_mov_b32 m0, s7
	s_nop 0
	global_load_lds_dwordx4 v[172:173], off
	s_waitcnt lgkmcnt(4)
	v_mfma_f32_32x32x16_bf16 v[80:95], v[214:217], v[202:205], v[80:95]
	ds_read_b128 v[150:153], v134
	v_mfma_f32_32x32x16_bf16 v[64:79], v[214:217], v[206:209], v[64:79]
	ds_read_b128 v[146:149], v134 offset:2048
	s_waitcnt lgkmcnt(5)
	v_mfma_f32_32x32x16_bf16 v[48:63], v[224:227], v[202:205], v[48:63]
	ds_read_b128 v[138:141], v134 offset:4096
	v_mfma_f32_32x32x16_bf16 v[32:47], v[224:227], v[206:209], v[32:47]
	ds_read_b128 v[134:137], v134 offset:6144
	v_lshl_add_u64 v[222:223], v[172:173], 0, s[10:11]
	s_mov_b32 m0, s8
	s_nop 0
	global_load_lds_dwordx4 v[222:223], off
	s_waitcnt lgkmcnt(6)
	v_mfma_f32_32x32x16_bf16 v[16:31], v[234:237], v[202:205], v[16:31]
	s_add_i32 s5, s5, 0x8000
	v_lshl_add_u64 v[170:171], v[170:171], 0, 64
	v_lshl_add_u64 v[172:173], v[172:173], 0, 64
	s_cmp_eq_u32 s5, 0x2c0000
	v_mfma_f32_32x32x16_bf16 v[0:15], v[234:237], v[206:209], v[0:15]
	s_cbranch_scc0 .LBB0_2551
	s_waitcnt vmcnt(8) lgkmcnt(0)
	s_barrier
	v_add_u32_e32 v202, v179, v177
	v_add_u32_e32 v222, v176, v177
	ds_read_b128 v[170:173], v202 offset:49152
	ds_read_b128 v[202:205], v202 offset:51200
	ds_read_b128 v[206:209], v222 offset:32768
	ds_read_b128 v[210:213], v222 offset:34816
	ds_read_b128 v[214:217], v222 offset:36864
	ds_read_b128 v[224:227], v222 offset:38912
	s_waitcnt lgkmcnt(9)
	v_mfma_f32_32x32x16_bf16 v[112:127], v[150:153], v[142:145], v[112:127]
	v_mfma_f32_32x32x16_bf16 v[96:111], v[150:153], v[130:133], v[96:111]
	s_waitcnt lgkmcnt(8)
	v_mfma_f32_32x32x16_bf16 v[80:95], v[146:149], v[142:145], v[80:95]
	v_mfma_f32_32x32x16_bf16 v[64:79], v[146:149], v[130:133], v[64:79]
	s_waitcnt lgkmcnt(7)
	v_mfma_f32_32x32x16_bf16 v[48:63], v[138:141], v[142:145], v[48:63]
	v_mfma_f32_32x32x16_bf16 v[32:47], v[138:141], v[130:133], v[32:47]
	s_waitcnt lgkmcnt(6)
	v_mfma_f32_32x32x16_bf16 v[16:31], v[134:137], v[142:145], v[16:31]
	v_mfma_f32_32x32x16_bf16 v[0:15], v[134:137], v[130:133], v[0:15]
	v_add_u32_e32 v134, v179, v178
	v_add_u32_e32 v150, v176, v178
	ds_read_b128 v[130:133], v134 offset:49152
	ds_read_b128 v[134:137], v134 offset:51200
	ds_read_b128 v[138:141], v150 offset:32768
	ds_read_b128 v[142:145], v150 offset:34816
	ds_read_b128 v[146:149], v150 offset:36864
	ds_read_b128 v[150:153], v150 offset:38912
	s_waitcnt lgkmcnt(9)
	v_mfma_f32_32x32x16_bf16 v[112:127], v[206:209], v[170:173], v[112:127]
	v_mfma_f32_32x32x16_bf16 v[96:111], v[206:209], v[202:205], v[96:111]
	s_waitcnt lgkmcnt(8)
	v_mfma_f32_32x32x16_bf16 v[80:95], v[210:213], v[170:173], v[80:95]
	v_mfma_f32_32x32x16_bf16 v[64:79], v[210:213], v[202:205], v[64:79]
	s_waitcnt lgkmcnt(7)
	v_mfma_f32_32x32x16_bf16 v[48:63], v[214:217], v[170:173], v[48:63]
	v_mfma_f32_32x32x16_bf16 v[32:47], v[214:217], v[202:205], v[32:47]
	s_waitcnt lgkmcnt(6)
	v_mfma_f32_32x32x16_bf16 v[0:15], v[224:227], v[202:205], v[0:15]
	s_waitcnt vmcnt(4) lgkmcnt(0)
	s_barrier
	v_add_u32_e32 v202, v199, v177
	v_add_u32_e32 v222, v200, v177
	v_mfma_f32_32x32x16_bf16 v[16:31], v[224:227], v[170:173], v[16:31]
	ds_read_b128 v[170:173], v202 offset:16384
	ds_read_b128 v[202:205], v202 offset:18432
	ds_read_b128 v[206:209], v222
	ds_read_b128 v[210:213], v222 offset:2048
	ds_read_b128 v[214:217], v222 offset:4096
	ds_read_b128 v[224:227], v222 offset:6144
	s_waitcnt lgkmcnt(9)
	v_mfma_f32_32x32x16_bf16 v[112:127], v[138:141], v[130:133], v[112:127]
	v_mfma_f32_32x32x16_bf16 v[96:111], v[138:141], v[134:137], v[96:111]
	s_waitcnt lgkmcnt(8)
	v_mfma_f32_32x32x16_bf16 v[80:95], v[142:145], v[130:133], v[80:95]
	v_mfma_f32_32x32x16_bf16 v[64:79], v[142:145], v[134:137], v[64:79]
	s_waitcnt lgkmcnt(7)
	v_mfma_f32_32x32x16_bf16 v[48:63], v[146:149], v[130:133], v[48:63]
	v_mfma_f32_32x32x16_bf16 v[32:47], v[146:149], v[134:137], v[32:47]
	s_waitcnt lgkmcnt(6)
	v_mfma_f32_32x32x16_bf16 v[16:31], v[150:153], v[130:133], v[16:31]
	v_mfma_f32_32x32x16_bf16 v[0:15], v[150:153], v[134:137], v[0:15]
	v_add_u32_e32 v134, v199, v178
	v_add_u32_e32 v150, v200, v178
	ds_read_b128 v[130:133], v134 offset:16384
	ds_read_b128 v[134:137], v134 offset:18432
	ds_read_b128 v[138:141], v150
	ds_read_b128 v[142:145], v150 offset:2048
	ds_read_b128 v[146:149], v150 offset:4096
	ds_read_b128 v[150:153], v150 offset:6144
	s_waitcnt lgkmcnt(9)
	v_mfma_f32_32x32x16_bf16 v[112:127], v[206:209], v[170:173], v[112:127]
	v_mfma_f32_32x32x16_bf16 v[96:111], v[206:209], v[202:205], v[96:111]
	s_waitcnt lgkmcnt(8)
	v_mfma_f32_32x32x16_bf16 v[80:95], v[210:213], v[170:173], v[80:95]
	v_mfma_f32_32x32x16_bf16 v[64:79], v[210:213], v[202:205], v[64:79]
	s_waitcnt lgkmcnt(7)
	v_mfma_f32_32x32x16_bf16 v[48:63], v[214:217], v[170:173], v[48:63]
	v_mfma_f32_32x32x16_bf16 v[32:47], v[214:217], v[202:205], v[32:47]
	s_waitcnt lgkmcnt(6)
	v_mfma_f32_32x32x16_bf16 v[0:15], v[224:227], v[202:205], v[0:15]
	s_waitcnt vmcnt(0) lgkmcnt(0)
	s_barrier
	v_add_u32_e32 v202, v197, v177
	v_add_u32_e32 v222, v198, v177
	v_mfma_f32_32x32x16_bf16 v[16:31], v[224:227], v[170:173], v[16:31]
	ds_read_b128 v[170:173], v202 offset:16384
	ds_read_b128 v[202:205], v202 offset:18432
	ds_read_b128 v[206:209], v222
	ds_read_b128 v[210:213], v222 offset:2048
	ds_read_b128 v[214:217], v222 offset:4096
	ds_read_b128 v[224:227], v222 offset:6144
	s_waitcnt lgkmcnt(9)
	v_mfma_f32_32x32x16_bf16 v[112:127], v[138:141], v[130:133], v[112:127]
	v_mfma_f32_32x32x16_bf16 v[96:111], v[138:141], v[134:137], v[96:111]
	s_waitcnt lgkmcnt(8)
	v_mfma_f32_32x32x16_bf16 v[80:95], v[142:145], v[130:133], v[80:95]
	v_mfma_f32_32x32x16_bf16 v[64:79], v[142:145], v[134:137], v[64:79]
	s_waitcnt lgkmcnt(7)
	v_mfma_f32_32x32x16_bf16 v[48:63], v[146:149], v[130:133], v[48:63]
	v_mfma_f32_32x32x16_bf16 v[32:47], v[146:149], v[134:137], v[32:47]
	s_waitcnt lgkmcnt(6)
	v_mfma_f32_32x32x16_bf16 v[16:31], v[150:153], v[130:133], v[16:31]
	v_mfma_f32_32x32x16_bf16 v[0:15], v[150:153], v[134:137], v[0:15]
	v_add_u32_e32 v134, v197, v178
	v_add_u32_e32 v150, v198, v178
	ds_read_b128 v[130:133], v134 offset:16384
	ds_read_b128 v[134:137], v134 offset:18432
	ds_read_b128 v[138:141], v150
	ds_read_b128 v[142:145], v150 offset:2048
	ds_read_b128 v[146:149], v150 offset:4096
	ds_read_b128 v[150:153], v150 offset:6144
	s_waitcnt lgkmcnt(9)
	v_mfma_f32_32x32x16_bf16 v[112:127], v[206:209], v[170:173], v[112:127]
	v_mfma_f32_32x32x16_bf16 v[96:111], v[206:209], v[202:205], v[96:111]
	s_waitcnt lgkmcnt(8)
	v_mfma_f32_32x32x16_bf16 v[80:95], v[210:213], v[170:173], v[80:95]
	v_mfma_f32_32x32x16_bf16 v[64:79], v[210:213], v[202:205], v[64:79]
	s_waitcnt lgkmcnt(7)
	v_mfma_f32_32x32x16_bf16 v[48:63], v[214:217], v[170:173], v[48:63]
	v_mfma_f32_32x32x16_bf16 v[32:47], v[214:217], v[202:205], v[32:47]
	s_waitcnt lgkmcnt(6)
	v_mfma_f32_32x32x16_bf16 v[16:31], v[224:227], v[170:173], v[16:31]
	s_movk_i32 s7, 0x1600
	v_mfma_f32_32x32x16_bf16 v[0:15], v[224:227], v[202:205], v[0:15]
	s_waitcnt lgkmcnt(3)
	v_mfma_f32_32x32x16_bf16 v[112:127], v[138:141], v[130:133], v[112:127]
	v_mfma_f32_32x32x16_bf16 v[96:111], v[138:141], v[134:137], v[96:111]
	s_nop 10
	v_cvt_pk_bf16_f32 v112, v112, s0
	s_waitcnt lgkmcnt(2)
	v_mfma_f32_32x32x16_bf16 v[80:95], v[142:145], v[130:133], v[80:95]
	v_cvt_pk_bf16_f32 v96, v96, s0
	v_cvt_pk_bf16_f32 v98, v98, s0
	s_waitcnt lgkmcnt(1)
	v_mfma_f32_32x32x16_bf16 v[48:63], v[146:149], v[130:133], v[48:63]
	s_nop 7
	v_cvt_pk_bf16_f32 v80, v80, s0
	s_waitcnt lgkmcnt(0)
	v_mfma_f32_32x32x16_bf16 v[16:31], v[150:153], v[130:133], v[16:31]
	v_add_u32_e32 v132, s3, v128
	v_or_b32_e32 v130, s4, v174
	v_ashrrev_i32_e32 v131, 31, v130
	v_lshl_add_u64 v[130:131], v[130:131], 1, v[158:159]
	v_cvt_pk_bf16_f32 v48, v48, s0
	v_readlane_b32 s3, v252, 7
	s_add_i32 s6, s6, s3
	v_mfma_f32_32x32x16_bf16 v[64:79], v[142:145], v[134:137], v[64:79]
	s_nop 3
	v_cvt_pk_bf16_f32 v16, v16, s0
	v_mfma_f32_32x32x16_bf16 v[32:47], v[146:149], v[134:137], v[32:47]
	s_nop 5
	v_cvt_pk_bf16_f32 v64, v64, s0
	v_cvt_pk_bf16_f32 v66, v66, s0
	v_mfma_f32_32x32x16_bf16 v[0:15], v[150:153], v[134:137], v[0:15]
	v_or_b32_e32 v134, v132, v181
	v_ashrrev_i32_e32 v135, 31, v134
	v_lshlrev_b64 v[134:135], 11, v[134:135]
	v_lshl_add_u64 v[134:135], v[130:131], 0, v[134:135]
	global_store_short v[134:135], v112, off
	global_store_short v[134:135], v96, off offset:64
	v_or_b32_e32 v134, v132, v182
	v_ashrrev_i32_e32 v135, 31, v134
	v_lshlrev_b64 v[134:135], 11, v[134:135]
	v_lshl_add_u64 v[134:135], v[130:131], 0, v[134:135]
	v_cvt_pk_bf16_f32 v96, v113, s0
	global_store_short v[134:135], v96, off
	v_cvt_pk_bf16_f32 v96, v97, s0
	global_store_short v[134:135], v96, off offset:64
	v_or_b32_e32 v96, v132, v183
	v_ashrrev_i32_e32 v97, 31, v96
	v_lshlrev_b64 v[96:97], 11, v[96:97]
	v_lshl_add_u64 v[96:97], v[130:131], 0, v[96:97]
	v_cvt_pk_bf16_f32 v112, v114, s0
	global_store_short v[96:97], v112, off
	global_store_short v[96:97], v98, off offset:64
	v_or_b32_e32 v96, v132, v184
	v_ashrrev_i32_e32 v97, 31, v96
	v_lshlrev_b64 v[96:97], 11, v[96:97]
	v_lshl_add_u64 v[96:97], v[130:131], 0, v[96:97]
	v_cvt_pk_bf16_f32 v98, v115, s0
	global_store_short v[96:97], v98, off
	v_cvt_pk_bf16_f32 v98, v99, s0
	global_store_short v[96:97], v98, off offset:64
	v_or_b32_e32 v96, v132, v185
	v_ashrrev_i32_e32 v97, 31, v96
	v_lshlrev_b64 v[96:97], 11, v[96:97]
	v_lshl_add_u64 v[96:97], v[130:131], 0, v[96:97]
	v_cvt_pk_bf16_f32 v98, v116, s0
	global_store_short v[96:97], v98, off
	v_cvt_pk_bf16_f32 v98, v100, s0
	global_store_short v[96:97], v98, off offset:64
	v_or_b32_e32 v96, v132, v186
	v_ashrrev_i32_e32 v97, 31, v96
	v_lshlrev_b64 v[96:97], 11, v[96:97]
	v_lshl_add_u64 v[96:97], v[130:131], 0, v[96:97]
	v_cvt_pk_bf16_f32 v98, v117, s0
	global_store_short v[96:97], v98, off
	v_cvt_pk_bf16_f32 v98, v101, s0
	global_store_short v[96:97], v98, off offset:64
	v_or_b32_e32 v96, v132, v187
	v_ashrrev_i32_e32 v97, 31, v96
	v_lshlrev_b64 v[96:97], 11, v[96:97]
	v_lshl_add_u64 v[96:97], v[130:131], 0, v[96:97]
	v_cvt_pk_bf16_f32 v98, v118, s0
	global_store_short v[96:97], v98, off
	v_cvt_pk_bf16_f32 v98, v102, s0
	global_store_short v[96:97], v98, off offset:64
	v_or_b32_e32 v96, v132, v188
	v_ashrrev_i32_e32 v97, 31, v96
	v_lshlrev_b64 v[96:97], 11, v[96:97]
	v_lshl_add_u64 v[96:97], v[130:131], 0, v[96:97]
	v_cvt_pk_bf16_f32 v98, v119, s0
	global_store_short v[96:97], v98, off
	v_cvt_pk_bf16_f32 v98, v103, s0
	global_store_short v[96:97], v98, off offset:64
	v_or_b32_e32 v96, v132, v189
	v_ashrrev_i32_e32 v97, 31, v96
	v_lshlrev_b64 v[96:97], 11, v[96:97]
	v_lshl_add_u64 v[96:97], v[130:131], 0, v[96:97]
	v_cvt_pk_bf16_f32 v98, v120, s0
	global_store_short v[96:97], v98, off
	v_cvt_pk_bf16_f32 v98, v104, s0
	global_store_short v[96:97], v98, off offset:64
	v_or_b32_e32 v96, v132, v190
	v_ashrrev_i32_e32 v97, 31, v96
	v_lshlrev_b64 v[96:97], 11, v[96:97]
	v_lshl_add_u64 v[96:97], v[130:131], 0, v[96:97]
	v_cvt_pk_bf16_f32 v98, v121, s0
	global_store_short v[96:97], v98, off
	v_cvt_pk_bf16_f32 v98, v105, s0
	global_store_short v[96:97], v98, off offset:64
	v_or_b32_e32 v96, v132, v191
	v_ashrrev_i32_e32 v97, 31, v96
	v_lshlrev_b64 v[96:97], 11, v[96:97]
	v_lshl_add_u64 v[96:97], v[130:131], 0, v[96:97]
	v_cvt_pk_bf16_f32 v98, v122, s0
	global_store_short v[96:97], v98, off
	v_cvt_pk_bf16_f32 v98, v106, s0
	global_store_short v[96:97], v98, off offset:64
	v_or_b32_e32 v96, v132, v192
	v_ashrrev_i32_e32 v97, 31, v96
	v_lshlrev_b64 v[96:97], 11, v[96:97]
	v_lshl_add_u64 v[96:97], v[130:131], 0, v[96:97]
	v_cvt_pk_bf16_f32 v98, v123, s0
	global_store_short v[96:97], v98, off
	v_cvt_pk_bf16_f32 v98, v107, s0
	global_store_short v[96:97], v98, off offset:64
	v_or_b32_e32 v96, v132, v193
	v_ashrrev_i32_e32 v97, 31, v96
	v_lshlrev_b64 v[96:97], 11, v[96:97]
	v_lshl_add_u64 v[96:97], v[130:131], 0, v[96:97]
	v_cvt_pk_bf16_f32 v98, v124, s0
	global_store_short v[96:97], v98, off
	v_cvt_pk_bf16_f32 v98, v108, s0
	global_store_short v[96:97], v98, off offset:64
	v_or_b32_e32 v96, v132, v194
	v_ashrrev_i32_e32 v97, 31, v96
	v_lshlrev_b64 v[96:97], 11, v[96:97]
	v_lshl_add_u64 v[96:97], v[130:131], 0, v[96:97]
	v_cvt_pk_bf16_f32 v98, v125, s0
	global_store_short v[96:97], v98, off
	v_cvt_pk_bf16_f32 v98, v109, s0
	global_store_short v[96:97], v98, off offset:64
	v_or_b32_e32 v96, v132, v195
	v_ashrrev_i32_e32 v97, 31, v96
	v_lshlrev_b64 v[96:97], 11, v[96:97]
	v_lshl_add_u64 v[96:97], v[130:131], 0, v[96:97]
	v_cvt_pk_bf16_f32 v98, v126, s0
	global_store_short v[96:97], v98, off
	v_cvt_pk_bf16_f32 v98, v110, s0
	global_store_short v[96:97], v98, off offset:64
	v_or_b32_e32 v96, v132, v196
	v_ashrrev_i32_e32 v97, 31, v96
	v_lshlrev_b64 v[96:97], 11, v[96:97]
	v_lshl_add_u64 v[96:97], v[130:131], 0, v[96:97]
	v_cvt_pk_bf16_f32 v98, v127, s0
	global_store_short v[96:97], v98, off
	v_cvt_pk_bf16_f32 v98, v111, s0
	global_store_short v[96:97], v98, off offset:64
	v_or_b32_e32 v98, 32, v132
	v_or_b32_e32 v96, v98, v181
	v_ashrrev_i32_e32 v97, 31, v96
	v_lshlrev_b64 v[96:97], 11, v[96:97]
	v_lshl_add_u64 v[96:97], v[130:131], 0, v[96:97]
	global_store_short v[96:97], v80, off
	global_store_short v[96:97], v64, off offset:64
	v_or_b32_e32 v96, v98, v182
	v_ashrrev_i32_e32 v97, 31, v96
	v_lshlrev_b64 v[96:97], 11, v[96:97]
	v_lshl_add_u64 v[96:97], v[130:131], 0, v[96:97]
	v_cvt_pk_bf16_f32 v64, v81, s0
	global_store_short v[96:97], v64, off
	v_cvt_pk_bf16_f32 v64, v65, s0
	global_store_short v[96:97], v64, off offset:64
	v_or_b32_e32 v64, v98, v183
	v_ashrrev_i32_e32 v65, 31, v64
	v_lshlrev_b64 v[64:65], 11, v[64:65]
	v_lshl_add_u64 v[64:65], v[130:131], 0, v[64:65]
	v_cvt_pk_bf16_f32 v80, v82, s0
	global_store_short v[64:65], v80, off
	global_store_short v[64:65], v66, off offset:64
	v_or_b32_e32 v64, v98, v184
	v_ashrrev_i32_e32 v65, 31, v64
	v_lshlrev_b64 v[64:65], 11, v[64:65]
	v_lshl_add_u64 v[64:65], v[130:131], 0, v[64:65]
	v_cvt_pk_bf16_f32 v66, v83, s0
	global_store_short v[64:65], v66, off
	v_cvt_pk_bf16_f32 v66, v67, s0
	global_store_short v[64:65], v66, off offset:64
	v_or_b32_e32 v64, v98, v185
	v_ashrrev_i32_e32 v65, 31, v64
	v_lshlrev_b64 v[64:65], 11, v[64:65]
	v_lshl_add_u64 v[64:65], v[130:131], 0, v[64:65]
	v_cvt_pk_bf16_f32 v66, v84, s0
	global_store_short v[64:65], v66, off
	v_cvt_pk_bf16_f32 v66, v68, s0
	global_store_short v[64:65], v66, off offset:64
	v_or_b32_e32 v64, v98, v186
	v_ashrrev_i32_e32 v65, 31, v64
	v_lshlrev_b64 v[64:65], 11, v[64:65]
	v_lshl_add_u64 v[64:65], v[130:131], 0, v[64:65]
	v_cvt_pk_bf16_f32 v66, v85, s0
	global_store_short v[64:65], v66, off
	v_cvt_pk_bf16_f32 v66, v69, s0
	global_store_short v[64:65], v66, off offset:64
	v_or_b32_e32 v64, v98, v187
	v_ashrrev_i32_e32 v65, 31, v64
	v_lshlrev_b64 v[64:65], 11, v[64:65]
	v_lshl_add_u64 v[64:65], v[130:131], 0, v[64:65]
	v_cvt_pk_bf16_f32 v66, v86, s0
	global_store_short v[64:65], v66, off
	v_cvt_pk_bf16_f32 v66, v70, s0
	global_store_short v[64:65], v66, off offset:64
	v_or_b32_e32 v64, v98, v188
	v_ashrrev_i32_e32 v65, 31, v64
	v_lshlrev_b64 v[64:65], 11, v[64:65]
	v_lshl_add_u64 v[64:65], v[130:131], 0, v[64:65]
	v_cvt_pk_bf16_f32 v66, v87, s0
	global_store_short v[64:65], v66, off
	v_cvt_pk_bf16_f32 v66, v71, s0
	global_store_short v[64:65], v66, off offset:64
	v_or_b32_e32 v64, v98, v189
	v_ashrrev_i32_e32 v65, 31, v64
	v_lshlrev_b64 v[64:65], 11, v[64:65]
	v_lshl_add_u64 v[64:65], v[130:131], 0, v[64:65]
	v_cvt_pk_bf16_f32 v66, v88, s0
	global_store_short v[64:65], v66, off
	v_cvt_pk_bf16_f32 v66, v72, s0
	global_store_short v[64:65], v66, off offset:64
	v_or_b32_e32 v64, v98, v190
	v_ashrrev_i32_e32 v65, 31, v64
	v_lshlrev_b64 v[64:65], 11, v[64:65]
	v_lshl_add_u64 v[64:65], v[130:131], 0, v[64:65]
	v_cvt_pk_bf16_f32 v66, v89, s0
	global_store_short v[64:65], v66, off
	v_cvt_pk_bf16_f32 v66, v73, s0
	global_store_short v[64:65], v66, off offset:64
	v_or_b32_e32 v64, v98, v191
	v_ashrrev_i32_e32 v65, 31, v64
	v_lshlrev_b64 v[64:65], 11, v[64:65]
	v_lshl_add_u64 v[64:65], v[130:131], 0, v[64:65]
	v_cvt_pk_bf16_f32 v66, v90, s0
	global_store_short v[64:65], v66, off
	v_cvt_pk_bf16_f32 v66, v74, s0
	global_store_short v[64:65], v66, off offset:64
	v_or_b32_e32 v64, v98, v192
	v_ashrrev_i32_e32 v65, 31, v64
	v_lshlrev_b64 v[64:65], 11, v[64:65]
	v_lshl_add_u64 v[64:65], v[130:131], 0, v[64:65]
	v_cvt_pk_bf16_f32 v66, v91, s0
	global_store_short v[64:65], v66, off
	v_cvt_pk_bf16_f32 v66, v75, s0
	global_store_short v[64:65], v66, off offset:64
	v_or_b32_e32 v64, v98, v193
	v_ashrrev_i32_e32 v65, 31, v64
	v_lshlrev_b64 v[64:65], 11, v[64:65]
	v_lshl_add_u64 v[64:65], v[130:131], 0, v[64:65]
	v_cvt_pk_bf16_f32 v66, v92, s0
	global_store_short v[64:65], v66, off
	v_cvt_pk_bf16_f32 v66, v76, s0
	global_store_short v[64:65], v66, off offset:64
	v_or_b32_e32 v64, v98, v194
	v_ashrrev_i32_e32 v65, 31, v64
	v_lshlrev_b64 v[64:65], 11, v[64:65]
	v_lshl_add_u64 v[64:65], v[130:131], 0, v[64:65]
	v_cvt_pk_bf16_f32 v66, v93, s0
	global_store_short v[64:65], v66, off
	v_cvt_pk_bf16_f32 v66, v77, s0
	global_store_short v[64:65], v66, off offset:64
	v_or_b32_e32 v64, v98, v195
	v_ashrrev_i32_e32 v65, 31, v64
	v_lshlrev_b64 v[64:65], 11, v[64:65]
	v_lshl_add_u64 v[64:65], v[130:131], 0, v[64:65]
	v_cvt_pk_bf16_f32 v66, v94, s0
	global_store_short v[64:65], v66, off
	v_cvt_pk_bf16_f32 v66, v78, s0
	global_store_short v[64:65], v66, off offset:64
	v_or_b32_e32 v64, v98, v196
	v_ashrrev_i32_e32 v65, 31, v64
	v_lshlrev_b64 v[64:65], 11, v[64:65]
	v_lshl_add_u64 v[64:65], v[130:131], 0, v[64:65]
	v_cvt_pk_bf16_f32 v66, v95, s0
	global_store_short v[64:65], v66, off
	v_cvt_pk_bf16_f32 v66, v79, s0
	global_store_short v[64:65], v66, off offset:64
	v_or_b32_e32 v66, 64, v132
	v_or_b32_e32 v64, v66, v181
	v_ashrrev_i32_e32 v65, 31, v64
	v_lshlrev_b64 v[64:65], 11, v[64:65]
	v_lshl_add_u64 v[64:65], v[130:131], 0, v[64:65]
	v_cvt_pk_bf16_f32 v32, v32, s0
	global_store_short v[64:65], v48, off
	global_store_short v[64:65], v32, off offset:64
	v_or_b32_e32 v64, v66, v182
	v_ashrrev_i32_e32 v65, 31, v64
	v_lshlrev_b64 v[64:65], 11, v[64:65]
	v_lshl_add_u64 v[64:65], v[130:131], 0, v[64:65]
	v_cvt_pk_bf16_f32 v32, v49, s0
	global_store_short v[64:65], v32, off
	v_cvt_pk_bf16_f32 v32, v33, s0
	global_store_short v[64:65], v32, off offset:64
	v_or_b32_e32 v32, v66, v183
	v_ashrrev_i32_e32 v33, 31, v32
	v_lshlrev_b64 v[32:33], 11, v[32:33]
	v_lshl_add_u64 v[32:33], v[130:131], 0, v[32:33]
	v_cvt_pk_bf16_f32 v48, v50, s0
	v_cvt_pk_bf16_f32 v34, v34, s0
	global_store_short v[32:33], v48, off
	global_store_short v[32:33], v34, off offset:64
	v_or_b32_e32 v32, v66, v184
	v_ashrrev_i32_e32 v33, 31, v32
	v_lshlrev_b64 v[32:33], 11, v[32:33]
	v_lshl_add_u64 v[32:33], v[130:131], 0, v[32:33]
	v_cvt_pk_bf16_f32 v34, v51, s0
	global_store_short v[32:33], v34, off
	v_cvt_pk_bf16_f32 v34, v35, s0
	global_store_short v[32:33], v34, off offset:64
	v_or_b32_e32 v32, v66, v185
	v_ashrrev_i32_e32 v33, 31, v32
	v_lshlrev_b64 v[32:33], 11, v[32:33]
	v_lshl_add_u64 v[32:33], v[130:131], 0, v[32:33]
	v_cvt_pk_bf16_f32 v34, v52, s0
	global_store_short v[32:33], v34, off
	v_cvt_pk_bf16_f32 v34, v36, s0
	global_store_short v[32:33], v34, off offset:64
	v_or_b32_e32 v32, v66, v186
	v_ashrrev_i32_e32 v33, 31, v32
	v_lshlrev_b64 v[32:33], 11, v[32:33]
	v_lshl_add_u64 v[32:33], v[130:131], 0, v[32:33]
	v_cvt_pk_bf16_f32 v34, v53, s0
	global_store_short v[32:33], v34, off
	v_cvt_pk_bf16_f32 v34, v37, s0
	global_store_short v[32:33], v34, off offset:64
	v_or_b32_e32 v32, v66, v187
	v_ashrrev_i32_e32 v33, 31, v32
	v_lshlrev_b64 v[32:33], 11, v[32:33]
	v_lshl_add_u64 v[32:33], v[130:131], 0, v[32:33]
	v_cvt_pk_bf16_f32 v34, v54, s0
	global_store_short v[32:33], v34, off
	v_cvt_pk_bf16_f32 v34, v38, s0
	global_store_short v[32:33], v34, off offset:64
	v_or_b32_e32 v32, v66, v188
	v_ashrrev_i32_e32 v33, 31, v32
	v_lshlrev_b64 v[32:33], 11, v[32:33]
	v_lshl_add_u64 v[32:33], v[130:131], 0, v[32:33]
	v_cvt_pk_bf16_f32 v34, v55, s0
	global_store_short v[32:33], v34, off
	v_cvt_pk_bf16_f32 v34, v39, s0
	global_store_short v[32:33], v34, off offset:64
	v_or_b32_e32 v32, v66, v189
	v_ashrrev_i32_e32 v33, 31, v32
	v_lshlrev_b64 v[32:33], 11, v[32:33]
	v_lshl_add_u64 v[32:33], v[130:131], 0, v[32:33]
	v_cvt_pk_bf16_f32 v34, v56, s0
	global_store_short v[32:33], v34, off
	v_cvt_pk_bf16_f32 v34, v40, s0
	global_store_short v[32:33], v34, off offset:64
	v_or_b32_e32 v32, v66, v190
	v_ashrrev_i32_e32 v33, 31, v32
	v_lshlrev_b64 v[32:33], 11, v[32:33]
	v_lshl_add_u64 v[32:33], v[130:131], 0, v[32:33]
	v_cvt_pk_bf16_f32 v34, v57, s0
	global_store_short v[32:33], v34, off
	v_cvt_pk_bf16_f32 v34, v41, s0
	global_store_short v[32:33], v34, off offset:64
	v_or_b32_e32 v32, v66, v191
	v_ashrrev_i32_e32 v33, 31, v32
	v_lshlrev_b64 v[32:33], 11, v[32:33]
	v_lshl_add_u64 v[32:33], v[130:131], 0, v[32:33]
	v_cvt_pk_bf16_f32 v34, v58, s0
	global_store_short v[32:33], v34, off
	v_cvt_pk_bf16_f32 v34, v42, s0
	global_store_short v[32:33], v34, off offset:64
	v_or_b32_e32 v32, v66, v192
	v_ashrrev_i32_e32 v33, 31, v32
	v_lshlrev_b64 v[32:33], 11, v[32:33]
	v_lshl_add_u64 v[32:33], v[130:131], 0, v[32:33]
	v_cvt_pk_bf16_f32 v34, v59, s0
	global_store_short v[32:33], v34, off
	v_cvt_pk_bf16_f32 v34, v43, s0
	global_store_short v[32:33], v34, off offset:64
	v_or_b32_e32 v32, v66, v193
	v_ashrrev_i32_e32 v33, 31, v32
	v_lshlrev_b64 v[32:33], 11, v[32:33]
	v_lshl_add_u64 v[32:33], v[130:131], 0, v[32:33]
	v_cvt_pk_bf16_f32 v34, v60, s0
	global_store_short v[32:33], v34, off
	v_cvt_pk_bf16_f32 v34, v44, s0
	global_store_short v[32:33], v34, off offset:64
	v_or_b32_e32 v32, v66, v194
	v_ashrrev_i32_e32 v33, 31, v32
	v_lshlrev_b64 v[32:33], 11, v[32:33]
	v_lshl_add_u64 v[32:33], v[130:131], 0, v[32:33]
	v_cvt_pk_bf16_f32 v34, v61, s0
	global_store_short v[32:33], v34, off
	v_cvt_pk_bf16_f32 v34, v45, s0
	global_store_short v[32:33], v34, off offset:64
	v_or_b32_e32 v32, v66, v195
	v_ashrrev_i32_e32 v33, 31, v32
	v_lshlrev_b64 v[32:33], 11, v[32:33]
	v_lshl_add_u64 v[32:33], v[130:131], 0, v[32:33]
	v_cvt_pk_bf16_f32 v34, v62, s0
	global_store_short v[32:33], v34, off
	v_cvt_pk_bf16_f32 v34, v46, s0
	global_store_short v[32:33], v34, off offset:64
	v_or_b32_e32 v32, v66, v196
	v_ashrrev_i32_e32 v33, 31, v32
	v_lshlrev_b64 v[32:33], 11, v[32:33]
	v_lshl_add_u64 v[32:33], v[130:131], 0, v[32:33]
	v_cvt_pk_bf16_f32 v34, v63, s0
	global_store_short v[32:33], v34, off
	v_cvt_pk_bf16_f32 v34, v47, s0
	global_store_short v[32:33], v34, off offset:64
	v_or_b32_e32 v34, 0x60, v132
	v_or_b32_e32 v32, v34, v181
	v_ashrrev_i32_e32 v33, 31, v32
	v_lshlrev_b64 v[32:33], 11, v[32:33]
	v_lshl_add_u64 v[32:33], v[130:131], 0, v[32:33]
	v_cvt_pk_bf16_f32 v0, v0, s0
	global_store_short v[32:33], v16, off
	global_store_short v[32:33], v0, off offset:64
	v_or_b32_e32 v32, v34, v182
	v_ashrrev_i32_e32 v33, 31, v32
	v_lshlrev_b64 v[32:33], 11, v[32:33]
	v_lshl_add_u64 v[32:33], v[130:131], 0, v[32:33]
	v_cvt_pk_bf16_f32 v0, v17, s0
	global_store_short v[32:33], v0, off
	v_cvt_pk_bf16_f32 v0, v1, s0
	global_store_short v[32:33], v0, off offset:64
	v_or_b32_e32 v0, v34, v183
	v_ashrrev_i32_e32 v1, 31, v0
	v_lshlrev_b64 v[0:1], 11, v[0:1]
	v_lshl_add_u64 v[0:1], v[130:131], 0, v[0:1]
	v_cvt_pk_bf16_f32 v16, v18, s0
	v_cvt_pk_bf16_f32 v2, v2, s0
	global_store_short v[0:1], v16, off
	global_store_short v[0:1], v2, off offset:64
	v_or_b32_e32 v0, v34, v184
	v_ashrrev_i32_e32 v1, 31, v0
	v_lshlrev_b64 v[0:1], 11, v[0:1]
	v_lshl_add_u64 v[0:1], v[130:131], 0, v[0:1]
	v_cvt_pk_bf16_f32 v2, v19, s0
	global_store_short v[0:1], v2, off
	v_cvt_pk_bf16_f32 v2, v3, s0
	global_store_short v[0:1], v2, off offset:64
	v_or_b32_e32 v0, v34, v185
	v_ashrrev_i32_e32 v1, 31, v0
	v_lshlrev_b64 v[0:1], 11, v[0:1]
	v_lshl_add_u64 v[0:1], v[130:131], 0, v[0:1]
	v_cvt_pk_bf16_f32 v2, v20, s0
	global_store_short v[0:1], v2, off
	v_cvt_pk_bf16_f32 v2, v4, s0
	global_store_short v[0:1], v2, off offset:64
	v_or_b32_e32 v0, v34, v186
	v_ashrrev_i32_e32 v1, 31, v0
	v_lshlrev_b64 v[0:1], 11, v[0:1]
	v_lshl_add_u64 v[0:1], v[130:131], 0, v[0:1]
	v_cvt_pk_bf16_f32 v2, v21, s0
	global_store_short v[0:1], v2, off
	v_cvt_pk_bf16_f32 v2, v5, s0
	global_store_short v[0:1], v2, off offset:64
	v_or_b32_e32 v0, v34, v187
	v_ashrrev_i32_e32 v1, 31, v0
	v_lshlrev_b64 v[0:1], 11, v[0:1]
	v_lshl_add_u64 v[0:1], v[130:131], 0, v[0:1]
	v_cvt_pk_bf16_f32 v2, v22, s0
	global_store_short v[0:1], v2, off
	v_cvt_pk_bf16_f32 v2, v6, s0
	global_store_short v[0:1], v2, off offset:64
	v_or_b32_e32 v0, v34, v188
	v_ashrrev_i32_e32 v1, 31, v0
	v_lshlrev_b64 v[0:1], 11, v[0:1]
	v_lshl_add_u64 v[0:1], v[130:131], 0, v[0:1]
	v_cvt_pk_bf16_f32 v2, v23, s0
	global_store_short v[0:1], v2, off
	v_cvt_pk_bf16_f32 v2, v7, s0
	global_store_short v[0:1], v2, off offset:64
	v_or_b32_e32 v0, v34, v189
	v_ashrrev_i32_e32 v1, 31, v0
	v_lshlrev_b64 v[0:1], 11, v[0:1]
	v_lshl_add_u64 v[0:1], v[130:131], 0, v[0:1]
	v_cvt_pk_bf16_f32 v2, v24, s0
	global_store_short v[0:1], v2, off
	v_cvt_pk_bf16_f32 v2, v8, s0
	global_store_short v[0:1], v2, off offset:64
	v_or_b32_e32 v0, v34, v190
	v_ashrrev_i32_e32 v1, 31, v0
	v_lshlrev_b64 v[0:1], 11, v[0:1]
	v_lshl_add_u64 v[0:1], v[130:131], 0, v[0:1]
	v_cvt_pk_bf16_f32 v2, v25, s0
	global_store_short v[0:1], v2, off
	v_cvt_pk_bf16_f32 v2, v9, s0
	global_store_short v[0:1], v2, off offset:64
	v_or_b32_e32 v0, v34, v191
	v_ashrrev_i32_e32 v1, 31, v0
	v_lshlrev_b64 v[0:1], 11, v[0:1]
	v_lshl_add_u64 v[0:1], v[130:131], 0, v[0:1]
	v_cvt_pk_bf16_f32 v2, v26, s0
	global_store_short v[0:1], v2, off
	v_cvt_pk_bf16_f32 v2, v10, s0
	global_store_short v[0:1], v2, off offset:64
	v_or_b32_e32 v0, v34, v192
	v_ashrrev_i32_e32 v1, 31, v0
	v_lshlrev_b64 v[0:1], 11, v[0:1]
	v_lshl_add_u64 v[0:1], v[130:131], 0, v[0:1]
	v_cvt_pk_bf16_f32 v2, v27, s0
	global_store_short v[0:1], v2, off
	v_cvt_pk_bf16_f32 v2, v11, s0
	global_store_short v[0:1], v2, off offset:64
	v_or_b32_e32 v0, v34, v193
	v_ashrrev_i32_e32 v1, 31, v0
	v_lshlrev_b64 v[0:1], 11, v[0:1]
	v_lshl_add_u64 v[0:1], v[130:131], 0, v[0:1]
	v_cvt_pk_bf16_f32 v2, v28, s0
	global_store_short v[0:1], v2, off
	v_cvt_pk_bf16_f32 v2, v12, s0
	global_store_short v[0:1], v2, off offset:64
	v_or_b32_e32 v0, v34, v194
	v_ashrrev_i32_e32 v1, 31, v0
	v_lshlrev_b64 v[0:1], 11, v[0:1]
	v_lshl_add_u64 v[0:1], v[130:131], 0, v[0:1]
	v_cvt_pk_bf16_f32 v2, v29, s0
	global_store_short v[0:1], v2, off
	v_cvt_pk_bf16_f32 v2, v13, s0
	global_store_short v[0:1], v2, off offset:64
	v_or_b32_e32 v0, v34, v195
	v_ashrrev_i32_e32 v1, 31, v0
	v_lshlrev_b64 v[0:1], 11, v[0:1]
	v_lshl_add_u64 v[0:1], v[130:131], 0, v[0:1]
	v_cvt_pk_bf16_f32 v2, v30, s0
	global_store_short v[0:1], v2, off
	v_cvt_pk_bf16_f32 v2, v14, s0
	global_store_short v[0:1], v2, off offset:64
	v_or_b32_e32 v0, v34, v196
	v_ashrrev_i32_e32 v1, 31, v0
	v_lshlrev_b64 v[0:1], 11, v[0:1]
	v_lshl_add_u64 v[0:1], v[130:131], 0, v[0:1]
	v_cvt_pk_bf16_f32 v2, v31, s0
	global_store_short v[0:1], v2, off
	v_cvt_pk_bf16_f32 v2, v15, s0
	s_add_i32 s0, s0, s3
	v_readlane_b32 s3, v252, 8
	s_add_i32 s2, s2, s3
	s_cmp_gt_i32 s6, 31
	global_store_short v[0:1], v2, off offset:64
	s_cbranch_scc0 .LBB0_2550
